# v3 plus s_nop pads so every dense MFMA run in the GEMM K-loops starts 8-byte aligned
# baseline (speedup 1.0000x reference)
.LBB0_186:
	v_add_u32_e32 v140, s82, v198
	v_add_u32_e32 v160, s83, v198
	ds_read_b128 v[128:131], v140
	ds_read_b128 v[132:135], v140 offset:1024
	ds_read_b128 v[136:139], v140 offset:2048
	ds_read_b128 v[140:143], v140 offset:3072
	ds_read_b128 v[144:147], v160
	ds_read_b128 v[148:151], v160 offset:1024
	ds_read_b128 v[184:187], v160 offset:2048
	ds_read_b128 v[188:191], v160 offset:3072
	s_add_u32 s46, s60, 0xfffc0080
	s_addc_u32 s47, s61, -1
	s_cmp_eq_u32 s49, 12
	s_cselect_b32 s65, s4, s47
	s_cselect_b32 s64, s5, s46
	s_cselect_b32 s63, s11, s48
	s_cselect_b32 s62, s35, s43
	v_lshl_add_u64 v[252:253], s[60:61], 0, v[174:175]
	s_add_i32 m0, s69, 0xc000
	ds_read_b128 v[220:223], v209
	ds_read_b128 v[224:227], v209 offset:1024
	ds_read_b128 v[228:231], v209 offset:2048
	ds_read_b128 v[232:235], v209 offset:3072
	ds_read_b128 v[236:239], v209 offset:4096
	ds_read_b128 v[240:243], v209 offset:5120
	ds_read_b128 v[244:247], v209 offset:6144
	ds_read_b128 v[248:251], v209 offset:7168
	global_load_lds_dwordx4 v[252:253], off
	v_lshl_add_u64 v[252:253], s[60:61], 0, v[176:177]
	s_add_i32 m0, s69, 0xe000
	s_nop 0
	global_load_lds_dwordx4 v[252:253], off
	s_nop 0
	s_waitcnt vmcnt(8)
	s_waitcnt lgkmcnt(0)
	s_barrier
	s_setprio 1
	s_waitcnt lgkmcnt(0)
	v_mfma_f32_16x16x32_bf16 v[124:127], v[128:131], v[220:223], v[124:127]
	v_mfma_f32_16x16x32_bf16 v[120:123], v[136:139], v[220:223], v[120:123]
	v_mfma_f32_16x16x32_bf16 v[116:119], v[128:131], v[228:231], v[116:119]
	v_mfma_f32_16x16x32_bf16 v[112:115], v[136:139], v[228:231], v[112:115]
	v_mfma_f32_16x16x32_bf16 v[108:111], v[128:131], v[236:239], v[108:111]
	v_mfma_f32_16x16x32_bf16 v[104:107], v[136:139], v[236:239], v[104:107]
	v_mfma_f32_16x16x32_bf16 v[100:103], v[128:131], v[244:247], v[100:103]
	v_mfma_f32_16x16x32_bf16 v[96:99], v[136:139], v[244:247], v[96:99]
	v_mfma_f32_16x16x32_bf16 v[124:127], v[132:135], v[224:227], v[124:127]
	v_mfma_f32_16x16x32_bf16 v[120:123], v[140:143], v[224:227], v[120:123]
	v_mfma_f32_16x16x32_bf16 v[116:119], v[132:135], v[232:235], v[116:119]
	v_mfma_f32_16x16x32_bf16 v[112:115], v[140:143], v[232:235], v[112:115]
	v_mfma_f32_16x16x32_bf16 v[108:111], v[132:135], v[240:243], v[108:111]
	v_mfma_f32_16x16x32_bf16 v[104:107], v[140:143], v[240:243], v[104:107]
	v_mfma_f32_16x16x32_bf16 v[100:103], v[132:135], v[248:251], v[100:103]
	v_mfma_f32_16x16x32_bf16 v[96:99], v[140:143], v[248:251], v[96:99]
	s_setprio 0
	s_setprio 1
	v_mfma_f32_16x16x32_bf16 v[60:63], v[144:147], v[220:223], v[60:63]
	v_mfma_f32_16x16x32_bf16 v[56:59], v[184:187], v[220:223], v[56:59]
	v_mfma_f32_16x16x32_bf16 v[52:55], v[144:147], v[228:231], v[52:55]
	v_mfma_f32_16x16x32_bf16 v[48:51], v[184:187], v[228:231], v[48:51]
	v_mfma_f32_16x16x32_bf16 v[44:47], v[144:147], v[236:239], v[44:47]
	v_mfma_f32_16x16x32_bf16 v[40:43], v[184:187], v[236:239], v[40:43]
	v_mfma_f32_16x16x32_bf16 v[36:39], v[144:147], v[244:247], v[36:39]
	v_mfma_f32_16x16x32_bf16 v[32:35], v[184:187], v[244:247], v[32:35]
	v_mfma_f32_16x16x32_bf16 v[60:63], v[148:151], v[224:227], v[60:63]
	v_mfma_f32_16x16x32_bf16 v[56:59], v[188:191], v[224:227], v[56:59]
	v_mfma_f32_16x16x32_bf16 v[52:55], v[148:151], v[232:235], v[52:55]
	v_mfma_f32_16x16x32_bf16 v[48:51], v[188:191], v[232:235], v[48:51]
	v_mfma_f32_16x16x32_bf16 v[44:47], v[148:151], v[240:243], v[44:47]
	v_mfma_f32_16x16x32_bf16 v[40:43], v[188:191], v[240:243], v[40:43]
	v_mfma_f32_16x16x32_bf16 v[36:39], v[148:151], v[248:251], v[36:39]
	v_mfma_f32_16x16x32_bf16 v[32:35], v[188:191], v[248:251], v[32:35]
	s_setprio 0
	s_barrier
	s_add_i32 s46, s82, s68
	v_lshl_add_u64 v[252:253], s[62:63], 0, v[154:155]
	s_mov_b32 m0, s46
	ds_read_b128 v[220:223], v209 offset:16384
	ds_read_b128 v[224:227], v209 offset:17408
	ds_read_b128 v[228:231], v209 offset:18432
	ds_read_b128 v[232:235], v209 offset:19456
	ds_read_b128 v[236:239], v209 offset:20480
	ds_read_b128 v[240:243], v209 offset:21504
	ds_read_b128 v[244:247], v209 offset:22528
	ds_read_b128 v[248:251], v209 offset:23552
	global_load_lds_dwordx4 v[252:253], off
	s_add_i32 m0, s46, 0x2000
	s_add_u32 s46, s62, 0x40000
	v_lshl_add_u64 v[202:203], s[62:63], 0, v[158:159]
	s_addc_u32 s47, s63, 0
	s_add_i32 s50, s83, s68
	global_load_lds_dwordx4 v[202:203], off
	v_lshl_add_u64 v[204:205], s[46:47], 0, v[154:155]
	s_mov_b32 m0, s50
	v_lshl_add_u64 v[206:207], s[64:65], 0, v[156:157]
	global_load_lds_dwordx4 v[204:205], off
	v_lshl_add_u64 v[204:205], s[46:47], 0, v[158:159]
	s_add_i32 m0, s50, 0x2000
	s_nop 0
	global_load_lds_dwordx4 v[204:205], off
	v_lshl_add_u64 v[204:205], s[64:65], 0, v[152:153]
	s_mov_b32 m0, s69
	s_nop 0
	global_load_lds_dwordx4 v[204:205], off
	s_mov_b32 m0, s70
	s_nop 0
	global_load_lds_dwordx4 v[206:207], off
	s_nop 0
	s_waitcnt vmcnt(8)
	s_waitcnt lgkmcnt(0)
	s_barrier
	s_setprio 1
	s_waitcnt lgkmcnt(0)
	v_mfma_f32_16x16x32_bf16 v[92:95], v[128:131], v[220:223], v[92:95]
	v_mfma_f32_16x16x32_bf16 v[88:91], v[136:139], v[220:223], v[88:91]
	v_mfma_f32_16x16x32_bf16 v[84:87], v[128:131], v[228:231], v[84:87]
	v_mfma_f32_16x16x32_bf16 v[80:83], v[136:139], v[228:231], v[80:83]
	v_mfma_f32_16x16x32_bf16 v[76:79], v[128:131], v[236:239], v[76:79]
	v_mfma_f32_16x16x32_bf16 v[72:75], v[136:139], v[236:239], v[72:75]
	v_mfma_f32_16x16x32_bf16 v[68:71], v[128:131], v[244:247], v[68:71]
	v_mfma_f32_16x16x32_bf16 v[64:67], v[136:139], v[244:247], v[64:67]
	v_mfma_f32_16x16x32_bf16 v[92:95], v[132:135], v[224:227], v[92:95]
	v_mfma_f32_16x16x32_bf16 v[88:91], v[140:143], v[224:227], v[88:91]
	v_mfma_f32_16x16x32_bf16 v[84:87], v[132:135], v[232:235], v[84:87]
	v_mfma_f32_16x16x32_bf16 v[80:83], v[140:143], v[232:235], v[80:83]
	v_mfma_f32_16x16x32_bf16 v[76:79], v[132:135], v[240:243], v[76:79]
	v_mfma_f32_16x16x32_bf16 v[72:75], v[140:143], v[240:243], v[72:75]
	v_mfma_f32_16x16x32_bf16 v[68:71], v[132:135], v[248:251], v[68:71]
	v_mfma_f32_16x16x32_bf16 v[64:67], v[140:143], v[248:251], v[64:67]
	s_setprio 0
	s_setprio 1
	v_mfma_f32_16x16x32_bf16 v[28:31], v[144:147], v[220:223], v[28:31]
	v_mfma_f32_16x16x32_bf16 v[24:27], v[184:187], v[220:223], v[24:27]
	v_mfma_f32_16x16x32_bf16 v[20:23], v[144:147], v[228:231], v[20:23]
	v_mfma_f32_16x16x32_bf16 v[16:19], v[184:187], v[228:231], v[16:19]
	v_mfma_f32_16x16x32_bf16 v[12:15], v[144:147], v[236:239], v[12:15]
	v_mfma_f32_16x16x32_bf16 v[8:11], v[184:187], v[236:239], v[8:11]
	v_mfma_f32_16x16x32_bf16 v[4:7], v[144:147], v[244:247], v[4:7]
	v_mfma_f32_16x16x32_bf16 v[0:3], v[184:187], v[244:247], v[0:3]
	v_mfma_f32_16x16x32_bf16 v[28:31], v[148:151], v[224:227], v[28:31]
	v_mfma_f32_16x16x32_bf16 v[24:27], v[188:191], v[224:227], v[24:27]
	v_mfma_f32_16x16x32_bf16 v[20:23], v[148:151], v[232:235], v[20:23]
	v_mfma_f32_16x16x32_bf16 v[16:19], v[188:191], v[232:235], v[16:19]
	v_mfma_f32_16x16x32_bf16 v[12:15], v[148:151], v[240:243], v[12:15]
	v_mfma_f32_16x16x32_bf16 v[8:11], v[188:191], v[240:243], v[8:11]
	v_mfma_f32_16x16x32_bf16 v[4:7], v[148:151], v[248:251], v[4:7]
	v_mfma_f32_16x16x32_bf16 v[0:3], v[188:191], v[248:251], v[0:3]
	s_setprio 0
	s_barrier
	s_add_i32 s50, 0, 0x18000
	s_add_i32 s51, 0, 0x1c000
	v_add_u32_e32 v140, s50, v198
	v_add_u32_e32 v160, s51, v198
	ds_read_b128 v[128:131], v140
	ds_read_b128 v[132:135], v140 offset:1024
	ds_read_b128 v[136:139], v140 offset:2048
	ds_read_b128 v[140:143], v140 offset:3072
	ds_read_b128 v[144:147], v160
	ds_read_b128 v[148:151], v160 offset:1024
	ds_read_b128 v[184:187], v160 offset:2048
	ds_read_b128 v[188:191], v160 offset:3072
	s_add_u32 s46, s64, 0x40000
	s_addc_u32 s47, s65, 0
	s_mov_b32 m0, s71
	v_lshl_add_u64 v[212:213], s[46:47], 0, v[152:153]
	ds_read_b128 v[220:223], v209 offset:32768
	ds_read_b128 v[224:227], v209 offset:33792
	ds_read_b128 v[228:231], v209 offset:34816
	ds_read_b128 v[232:235], v209 offset:35840
	ds_read_b128 v[236:239], v209 offset:36864
	ds_read_b128 v[240:243], v209 offset:37888
	ds_read_b128 v[244:247], v209 offset:38912
	ds_read_b128 v[248:251], v209 offset:39936
	global_load_lds_dwordx4 v[212:213], off
	v_lshl_add_u64 v[212:213], s[46:47], 0, v[156:157]
	s_mov_b32 m0, s72
	s_nop 0
	global_load_lds_dwordx4 v[212:213], off
	s_nop 0
	s_waitcnt vmcnt(8)
	s_waitcnt lgkmcnt(0)
	s_barrier
	s_setprio 1
	s_waitcnt lgkmcnt(0)
	v_mfma_f32_16x16x32_bf16 v[124:127], v[128:131], v[220:223], v[124:127]
	v_mfma_f32_16x16x32_bf16 v[120:123], v[136:139], v[220:223], v[120:123]
	v_mfma_f32_16x16x32_bf16 v[116:119], v[128:131], v[228:231], v[116:119]
	v_mfma_f32_16x16x32_bf16 v[112:115], v[136:139], v[228:231], v[112:115]
	v_mfma_f32_16x16x32_bf16 v[108:111], v[128:131], v[236:239], v[108:111]
	v_mfma_f32_16x16x32_bf16 v[104:107], v[136:139], v[236:239], v[104:107]
	v_mfma_f32_16x16x32_bf16 v[100:103], v[128:131], v[244:247], v[100:103]
	v_mfma_f32_16x16x32_bf16 v[96:99], v[136:139], v[244:247], v[96:99]
	v_mfma_f32_16x16x32_bf16 v[124:127], v[132:135], v[224:227], v[124:127]
	v_mfma_f32_16x16x32_bf16 v[120:123], v[140:143], v[224:227], v[120:123]
	v_mfma_f32_16x16x32_bf16 v[116:119], v[132:135], v[232:235], v[116:119]
	v_mfma_f32_16x16x32_bf16 v[112:115], v[140:143], v[232:235], v[112:115]
	v_mfma_f32_16x16x32_bf16 v[108:111], v[132:135], v[240:243], v[108:111]
	v_mfma_f32_16x16x32_bf16 v[104:107], v[140:143], v[240:243], v[104:107]
	v_mfma_f32_16x16x32_bf16 v[100:103], v[132:135], v[248:251], v[100:103]
	v_mfma_f32_16x16x32_bf16 v[96:99], v[140:143], v[248:251], v[96:99]
	s_setprio 0
	s_setprio 1
	v_mfma_f32_16x16x32_bf16 v[60:63], v[144:147], v[220:223], v[60:63]
	v_mfma_f32_16x16x32_bf16 v[56:59], v[184:187], v[220:223], v[56:59]
	v_mfma_f32_16x16x32_bf16 v[52:55], v[144:147], v[228:231], v[52:55]
	v_mfma_f32_16x16x32_bf16 v[48:51], v[184:187], v[228:231], v[48:51]
	v_mfma_f32_16x16x32_bf16 v[44:47], v[144:147], v[236:239], v[44:47]
	v_mfma_f32_16x16x32_bf16 v[40:43], v[184:187], v[236:239], v[40:43]
	v_mfma_f32_16x16x32_bf16 v[36:39], v[144:147], v[244:247], v[36:39]
	v_mfma_f32_16x16x32_bf16 v[32:35], v[184:187], v[244:247], v[32:35]
	v_mfma_f32_16x16x32_bf16 v[60:63], v[148:151], v[224:227], v[60:63]
	v_mfma_f32_16x16x32_bf16 v[56:59], v[188:191], v[224:227], v[56:59]
	v_mfma_f32_16x16x32_bf16 v[52:55], v[148:151], v[232:235], v[52:55]
	v_mfma_f32_16x16x32_bf16 v[48:51], v[188:191], v[232:235], v[48:51]
	v_mfma_f32_16x16x32_bf16 v[44:47], v[148:151], v[240:243], v[44:47]
	v_mfma_f32_16x16x32_bf16 v[40:43], v[188:191], v[240:243], v[40:43]
	v_mfma_f32_16x16x32_bf16 v[36:39], v[148:151], v[248:251], v[36:39]
	v_mfma_f32_16x16x32_bf16 v[32:35], v[188:191], v[248:251], v[32:35]
	s_setprio 0
	s_barrier
	s_add_i32 s46, s50, s68
	v_lshl_add_u64 v[212:213], v[252:253], 0, s[16:17]
	s_mov_b32 m0, s46
	ds_read_b128 v[220:223], v209 offset:49152
	ds_read_b128 v[224:227], v209 offset:50176
	ds_read_b128 v[228:231], v209 offset:51200
	ds_read_b128 v[232:235], v209 offset:52224
	ds_read_b128 v[236:239], v209 offset:53248
	ds_read_b128 v[240:243], v209 offset:54272
	ds_read_b128 v[244:247], v209 offset:55296
	ds_read_b128 v[248:251], v209 offset:56320
	global_load_lds_dwordx4 v[212:213], off
	s_add_i32 m0, s46, 0x2000
	s_add_u32 s46, s62, 0x40080
	v_lshl_add_u64 v[202:203], v[202:203], 0, s[16:17]
	s_addc_u32 s47, s63, 0
	s_add_i32 s50, s51, s68
	global_load_lds_dwordx4 v[202:203], off
	v_lshl_add_u64 v[202:203], s[46:47], 0, v[154:155]
	s_mov_b32 m0, s50
	s_nop 0
	global_load_lds_dwordx4 v[202:203], off
	v_lshl_add_u64 v[202:203], s[46:47], 0, v[158:159]
	s_add_i32 m0, s50, 0x2000
	s_nop 0
	global_load_lds_dwordx4 v[202:203], off
	v_lshl_add_u64 v[202:203], v[204:205], 0, s[16:17]
	s_mov_b32 m0, s79
	s_nop 0
	global_load_lds_dwordx4 v[202:203], off
	v_lshl_add_u64 v[202:203], v[206:207], 0, s[16:17]
	s_mov_b32 m0, s80
	s_nop 0
	global_load_lds_dwordx4 v[202:203], off
	s_waitcnt vmcnt(8)
	s_waitcnt lgkmcnt(0)
	s_barrier
	s_setprio 1
	s_waitcnt lgkmcnt(0)
	v_mfma_f32_16x16x32_bf16 v[92:95], v[128:131], v[220:223], v[92:95]
	v_mfma_f32_16x16x32_bf16 v[88:91], v[136:139], v[220:223], v[88:91]
	v_mfma_f32_16x16x32_bf16 v[84:87], v[128:131], v[228:231], v[84:87]
	v_mfma_f32_16x16x32_bf16 v[80:83], v[136:139], v[228:231], v[80:83]
	v_mfma_f32_16x16x32_bf16 v[76:79], v[128:131], v[236:239], v[76:79]
	v_mfma_f32_16x16x32_bf16 v[72:75], v[136:139], v[236:239], v[72:75]
	v_mfma_f32_16x16x32_bf16 v[68:71], v[128:131], v[244:247], v[68:71]
	v_mfma_f32_16x16x32_bf16 v[64:67], v[136:139], v[244:247], v[64:67]
	v_mfma_f32_16x16x32_bf16 v[92:95], v[132:135], v[224:227], v[92:95]
	v_mfma_f32_16x16x32_bf16 v[88:91], v[140:143], v[224:227], v[88:91]
	v_mfma_f32_16x16x32_bf16 v[84:87], v[132:135], v[232:235], v[84:87]
	v_mfma_f32_16x16x32_bf16 v[80:83], v[140:143], v[232:235], v[80:83]
	v_mfma_f32_16x16x32_bf16 v[76:79], v[132:135], v[240:243], v[76:79]
	v_mfma_f32_16x16x32_bf16 v[72:75], v[140:143], v[240:243], v[72:75]
	v_mfma_f32_16x16x32_bf16 v[68:71], v[132:135], v[248:251], v[68:71]
	v_mfma_f32_16x16x32_bf16 v[64:67], v[140:143], v[248:251], v[64:67]
	s_setprio 0
	s_setprio 1
	v_mfma_f32_16x16x32_bf16 v[28:31], v[144:147], v[220:223], v[28:31]
	v_mfma_f32_16x16x32_bf16 v[24:27], v[184:187], v[220:223], v[24:27]
	v_mfma_f32_16x16x32_bf16 v[20:23], v[144:147], v[228:231], v[20:23]
	v_mfma_f32_16x16x32_bf16 v[16:19], v[184:187], v[228:231], v[16:19]
	v_mfma_f32_16x16x32_bf16 v[12:15], v[144:147], v[236:239], v[12:15]
	v_mfma_f32_16x16x32_bf16 v[8:11], v[184:187], v[236:239], v[8:11]
	v_mfma_f32_16x16x32_bf16 v[4:7], v[144:147], v[244:247], v[4:7]
	v_mfma_f32_16x16x32_bf16 v[0:3], v[184:187], v[244:247], v[0:3]
	v_mfma_f32_16x16x32_bf16 v[28:31], v[148:151], v[224:227], v[28:31]
	v_mfma_f32_16x16x32_bf16 v[24:27], v[188:191], v[224:227], v[24:27]
	v_mfma_f32_16x16x32_bf16 v[20:23], v[148:151], v[232:235], v[20:23]
	v_mfma_f32_16x16x32_bf16 v[16:19], v[188:191], v[232:235], v[16:19]
	v_mfma_f32_16x16x32_bf16 v[12:15], v[148:151], v[240:243], v[12:15]
	v_mfma_f32_16x16x32_bf16 v[8:11], v[188:191], v[240:243], v[8:11]
	v_mfma_f32_16x16x32_bf16 v[4:7], v[148:151], v[248:251], v[4:7]
	v_mfma_f32_16x16x32_bf16 v[0:3], v[188:191], v[248:251], v[0:3]
	s_setprio 0
	s_barrier
	s_add_i32 s49, s49, 2
	s_add_u32 s60, s60, 0x100
	s_addc_u32 s61, s61, 0
	s_add_u32 s43, s43, 0x100
	s_addc_u32 s48, s48, 0
	s_cmp_gt_u32 s49, 13
	s_cbranch_scc0 .LBB0_186
	s_and_b64 vcc, exec, s[18:19]
	s_cbranch_vccnz .LBB0_190
	s_lshl_b32 s4, s10, 8
	s_cmp_lt_i32 s58, 8
	s_mov_b64 s[10:11], -1
	s_cbranch_scc0 .LBB0_191

.LBB0_704:
	ds_read_b128 v[154:157], v150
	ds_read_b128 v[158:161], v150 offset:1024
	ds_read_b128 v[162:165], v150 offset:2048
	ds_read_b128 v[166:169], v150 offset:3072
	ds_read_b128 v[170:173], v151
	ds_read_b128 v[174:177], v151 offset:1024
	ds_read_b128 v[178:181], v151 offset:2048
	ds_read_b128 v[182:185], v151 offset:3072
	s_add_u32 s22, s20, 0x100
	s_addc_u32 s23, s21, 0
	s_cmp_eq_u32 s60, 2
	s_cselect_b32 s27, s9, s23
	s_cselect_b32 s26, s8, s22
	s_cselect_b32 s25, s19, s59
	s_cselect_b32 s24, s18, s58
	v_lshl_add_u64 v[144:145], s[20:21], 0, v[136:137]
	s_add_i32 m0, s35, 0xc000
	ds_read_b128 v[186:189], v152
	ds_read_b128 v[190:193], v152 offset:1024
	ds_read_b128 v[198:201], v152 offset:2048
	ds_read_b128 v[202:205], v152 offset:3072
	ds_read_b128 v[206:209], v152 offset:4096
	ds_read_b128 v[210:213], v152 offset:5120
	ds_read_b128 v[214:217], v152 offset:6144
	ds_read_b128 v[218:221], v152 offset:7168
	global_load_lds_dwordx4 v[144:145], off
	v_lshl_add_u64 v[144:145], s[20:21], 0, v[138:139]
	s_add_i32 m0, s35, 0xe000
	s_nop 0
	global_load_lds_dwordx4 v[144:145], off
	s_waitcnt vmcnt(8)
	s_waitcnt lgkmcnt(0)
	s_barrier
	s_setprio 1
	s_waitcnt lgkmcnt(0)
	v_mfma_f32_16x16x32_bf16 v[124:127], v[154:157], v[186:189], v[124:127]
	v_mfma_f32_16x16x32_bf16 v[120:123], v[162:165], v[186:189], v[120:123]
	v_mfma_f32_16x16x32_bf16 v[112:115], v[154:157], v[198:201], v[112:115]
	v_mfma_f32_16x16x32_bf16 v[104:107], v[162:165], v[198:201], v[104:107]
	v_mfma_f32_16x16x32_bf16 v[96:99], v[154:157], v[206:209], v[96:99]
	v_mfma_f32_16x16x32_bf16 v[88:91], v[162:165], v[206:209], v[88:91]
	v_mfma_f32_16x16x32_bf16 v[80:83], v[154:157], v[214:217], v[80:83]
	v_mfma_f32_16x16x32_bf16 v[72:75], v[162:165], v[214:217], v[72:75]
	v_mfma_f32_16x16x32_bf16 v[124:127], v[158:161], v[190:193], v[124:127]
	v_mfma_f32_16x16x32_bf16 v[120:123], v[166:169], v[190:193], v[120:123]
	v_mfma_f32_16x16x32_bf16 v[112:115], v[158:161], v[202:205], v[112:115]
	v_mfma_f32_16x16x32_bf16 v[104:107], v[166:169], v[202:205], v[104:107]
	v_mfma_f32_16x16x32_bf16 v[96:99], v[158:161], v[210:213], v[96:99]
	v_mfma_f32_16x16x32_bf16 v[88:91], v[166:169], v[210:213], v[88:91]
	v_mfma_f32_16x16x32_bf16 v[80:83], v[158:161], v[218:221], v[80:83]
	v_mfma_f32_16x16x32_bf16 v[72:75], v[166:169], v[218:221], v[72:75]
	s_setprio 0
	s_setprio 1
	v_mfma_f32_16x16x32_bf16 v[116:119], v[170:173], v[186:189], v[116:119]
	v_mfma_f32_16x16x32_bf16 v[108:111], v[178:181], v[186:189], v[108:111]
	v_mfma_f32_16x16x32_bf16 v[100:103], v[170:173], v[198:201], v[100:103]
	v_mfma_f32_16x16x32_bf16 v[92:95], v[178:181], v[198:201], v[92:95]
	v_mfma_f32_16x16x32_bf16 v[84:87], v[170:173], v[206:209], v[84:87]
	v_mfma_f32_16x16x32_bf16 v[76:79], v[178:181], v[206:209], v[76:79]
	v_mfma_f32_16x16x32_bf16 v[68:71], v[170:173], v[214:217], v[68:71]
	v_mfma_f32_16x16x32_bf16 v[64:67], v[178:181], v[214:217], v[64:67]
	v_mfma_f32_16x16x32_bf16 v[116:119], v[174:177], v[190:193], v[116:119]
	v_mfma_f32_16x16x32_bf16 v[108:111], v[182:185], v[190:193], v[108:111]
	v_mfma_f32_16x16x32_bf16 v[100:103], v[174:177], v[202:205], v[100:103]
	v_mfma_f32_16x16x32_bf16 v[92:95], v[182:185], v[202:205], v[92:95]
	v_mfma_f32_16x16x32_bf16 v[84:87], v[174:177], v[210:213], v[84:87]
	v_mfma_f32_16x16x32_bf16 v[76:79], v[182:185], v[210:213], v[76:79]
	v_mfma_f32_16x16x32_bf16 v[68:71], v[174:177], v[218:221], v[68:71]
	v_mfma_f32_16x16x32_bf16 v[64:67], v[182:185], v[218:221], v[64:67]
	s_setprio 0
	s_barrier
	s_add_i32 s20, s51, s29
	v_lshl_add_u64 v[144:145], s[24:25], 0, v[132:133]
	s_mov_b32 m0, s20
	ds_read_b128 v[186:189], v152 offset:16384
	ds_read_b128 v[190:193], v152 offset:17408
	ds_read_b128 v[198:201], v152 offset:18432
	ds_read_b128 v[202:205], v152 offset:19456
	ds_read_b128 v[206:209], v152 offset:20480
	ds_read_b128 v[210:213], v152 offset:21504
	ds_read_b128 v[214:217], v152 offset:22528
	ds_read_b128 v[218:221], v152 offset:23552
	global_load_lds_dwordx4 v[144:145], off
	s_add_i32 m0, s20, 0x2000
	s_add_u32 s20, s24, 0x18000
	v_lshl_add_u64 v[194:195], s[24:25], 0, v[128:129]
	s_addc_u32 s21, s25, 0
	s_add_i32 s46, s52, s29
	global_load_lds_dwordx4 v[194:195], off
	v_lshl_add_u64 v[196:197], s[20:21], 0, v[132:133]
	s_mov_b32 m0, s46
	v_lshl_add_u64 v[222:223], s[26:27], 0, v[130:131]
	global_load_lds_dwordx4 v[196:197], off
	v_lshl_add_u64 v[196:197], s[20:21], 0, v[128:129]
	s_add_i32 m0, s46, 0x2000
	s_nop 0
	global_load_lds_dwordx4 v[196:197], off
	v_lshl_add_u64 v[196:197], s[26:27], 0, v[134:135]
	s_mov_b32 m0, s35
	s_nop 0
	global_load_lds_dwordx4 v[196:197], off
	s_mov_b32 m0, s42
	s_nop 0
	global_load_lds_dwordx4 v[222:223], off
	s_nop 0
	s_waitcnt vmcnt(8)
	s_waitcnt lgkmcnt(0)
	s_barrier
	s_setprio 1
	s_waitcnt lgkmcnt(0)
	v_mfma_f32_16x16x32_bf16 v[60:63], v[154:157], v[186:189], v[60:63]
	v_mfma_f32_16x16x32_bf16 v[56:59], v[162:165], v[186:189], v[56:59]
	v_mfma_f32_16x16x32_bf16 v[48:51], v[154:157], v[198:201], v[48:51]
	v_mfma_f32_16x16x32_bf16 v[40:43], v[162:165], v[198:201], v[40:43]
	v_mfma_f32_16x16x32_bf16 v[32:35], v[154:157], v[206:209], v[32:35]
	v_mfma_f32_16x16x32_bf16 v[24:27], v[162:165], v[206:209], v[24:27]
	v_mfma_f32_16x16x32_bf16 v[16:19], v[154:157], v[214:217], v[16:19]
	v_mfma_f32_16x16x32_bf16 v[8:11], v[162:165], v[214:217], v[8:11]
	v_mfma_f32_16x16x32_bf16 v[60:63], v[158:161], v[190:193], v[60:63]
	v_mfma_f32_16x16x32_bf16 v[56:59], v[166:169], v[190:193], v[56:59]
	v_mfma_f32_16x16x32_bf16 v[48:51], v[158:161], v[202:205], v[48:51]
	v_mfma_f32_16x16x32_bf16 v[40:43], v[166:169], v[202:205], v[40:43]
	v_mfma_f32_16x16x32_bf16 v[32:35], v[158:161], v[210:213], v[32:35]
	v_mfma_f32_16x16x32_bf16 v[24:27], v[166:169], v[210:213], v[24:27]
	v_mfma_f32_16x16x32_bf16 v[16:19], v[158:161], v[218:221], v[16:19]
	v_mfma_f32_16x16x32_bf16 v[8:11], v[166:169], v[218:221], v[8:11]
	s_setprio 0
	s_setprio 1
	v_mfma_f32_16x16x32_bf16 v[52:55], v[170:173], v[186:189], v[52:55]
	v_mfma_f32_16x16x32_bf16 v[44:47], v[178:181], v[186:189], v[44:47]
	v_mfma_f32_16x16x32_bf16 v[36:39], v[170:173], v[198:201], v[36:39]
	v_mfma_f32_16x16x32_bf16 v[28:31], v[178:181], v[198:201], v[28:31]
	v_mfma_f32_16x16x32_bf16 v[20:23], v[170:173], v[206:209], v[20:23]
	v_mfma_f32_16x16x32_bf16 v[12:15], v[178:181], v[206:209], v[12:15]
	v_mfma_f32_16x16x32_bf16 v[4:7], v[170:173], v[214:217], v[4:7]
	v_mfma_f32_16x16x32_bf16 v[0:3], v[178:181], v[214:217], v[0:3]
	v_mfma_f32_16x16x32_bf16 v[52:55], v[174:177], v[190:193], v[52:55]
	v_mfma_f32_16x16x32_bf16 v[44:47], v[182:185], v[190:193], v[44:47]
	v_mfma_f32_16x16x32_bf16 v[36:39], v[174:177], v[202:205], v[36:39]
	v_mfma_f32_16x16x32_bf16 v[28:31], v[182:185], v[202:205], v[28:31]
	v_mfma_f32_16x16x32_bf16 v[20:23], v[174:177], v[210:213], v[20:23]
	v_mfma_f32_16x16x32_bf16 v[12:15], v[182:185], v[210:213], v[12:15]
	v_mfma_f32_16x16x32_bf16 v[4:7], v[174:177], v[218:221], v[4:7]
	v_mfma_f32_16x16x32_bf16 v[0:3], v[182:185], v[218:221], v[0:3]
	s_setprio 0
	s_barrier
	s_add_i32 s46, 0, 0x18000
	v_add_u32_e32 v153, s46, v148
	s_add_i32 s47, 0, 0x1c000
	ds_read_b128 v[154:157], v153
	ds_read_b128 v[158:161], v153 offset:1024
	ds_read_b128 v[162:165], v153 offset:2048
	ds_read_b128 v[166:169], v153 offset:3072
	v_add_u32_e32 v153, s47, v148
	ds_read_b128 v[170:173], v153
	ds_read_b128 v[174:177], v153 offset:1024
	ds_read_b128 v[178:181], v153 offset:2048
	ds_read_b128 v[182:185], v153 offset:3072
	s_add_u32 s20, s26, 0x18000
	s_addc_u32 s21, s27, 0
	s_mov_b32 m0, s43
	v_lshl_add_u64 v[224:225], s[20:21], 0, v[134:135]
	ds_read_b128 v[186:189], v152 offset:32768
	ds_read_b128 v[190:193], v152 offset:33792
	ds_read_b128 v[198:201], v152 offset:34816
	ds_read_b128 v[202:205], v152 offset:35840
	ds_read_b128 v[206:209], v152 offset:36864
	ds_read_b128 v[210:213], v152 offset:37888
	ds_read_b128 v[214:217], v152 offset:38912
	ds_read_b128 v[218:221], v152 offset:39936
	global_load_lds_dwordx4 v[224:225], off
	v_lshl_add_u64 v[224:225], s[20:21], 0, v[130:131]
	s_mov_b32 m0, s45
	s_nop 0
	global_load_lds_dwordx4 v[224:225], off
	s_nop 0
	s_waitcnt vmcnt(8)
	s_waitcnt lgkmcnt(0)
	s_barrier
	s_setprio 1
	s_waitcnt lgkmcnt(0)
	v_mfma_f32_16x16x32_bf16 v[124:127], v[154:157], v[186:189], v[124:127]
	v_mfma_f32_16x16x32_bf16 v[120:123], v[162:165], v[186:189], v[120:123]
	v_mfma_f32_16x16x32_bf16 v[112:115], v[154:157], v[198:201], v[112:115]
	v_mfma_f32_16x16x32_bf16 v[104:107], v[162:165], v[198:201], v[104:107]
	v_mfma_f32_16x16x32_bf16 v[96:99], v[154:157], v[206:209], v[96:99]
	v_mfma_f32_16x16x32_bf16 v[88:91], v[162:165], v[206:209], v[88:91]
	v_mfma_f32_16x16x32_bf16 v[80:83], v[154:157], v[214:217], v[80:83]
	v_mfma_f32_16x16x32_bf16 v[72:75], v[162:165], v[214:217], v[72:75]
	v_mfma_f32_16x16x32_bf16 v[124:127], v[158:161], v[190:193], v[124:127]
	v_mfma_f32_16x16x32_bf16 v[120:123], v[166:169], v[190:193], v[120:123]
	v_mfma_f32_16x16x32_bf16 v[112:115], v[158:161], v[202:205], v[112:115]
	v_mfma_f32_16x16x32_bf16 v[104:107], v[166:169], v[202:205], v[104:107]
	v_mfma_f32_16x16x32_bf16 v[96:99], v[158:161], v[210:213], v[96:99]
	v_mfma_f32_16x16x32_bf16 v[88:91], v[166:169], v[210:213], v[88:91]
	v_mfma_f32_16x16x32_bf16 v[80:83], v[158:161], v[218:221], v[80:83]
	v_mfma_f32_16x16x32_bf16 v[72:75], v[166:169], v[218:221], v[72:75]
	s_setprio 0
	s_setprio 1
	v_mfma_f32_16x16x32_bf16 v[116:119], v[170:173], v[186:189], v[116:119]
	v_mfma_f32_16x16x32_bf16 v[108:111], v[178:181], v[186:189], v[108:111]
	v_mfma_f32_16x16x32_bf16 v[100:103], v[170:173], v[198:201], v[100:103]
	v_mfma_f32_16x16x32_bf16 v[92:95], v[178:181], v[198:201], v[92:95]
	v_mfma_f32_16x16x32_bf16 v[84:87], v[170:173], v[206:209], v[84:87]
	v_mfma_f32_16x16x32_bf16 v[76:79], v[178:181], v[206:209], v[76:79]
	v_mfma_f32_16x16x32_bf16 v[68:71], v[170:173], v[214:217], v[68:71]
	v_mfma_f32_16x16x32_bf16 v[64:67], v[178:181], v[214:217], v[64:67]
	v_mfma_f32_16x16x32_bf16 v[116:119], v[174:177], v[190:193], v[116:119]
	v_mfma_f32_16x16x32_bf16 v[108:111], v[182:185], v[190:193], v[108:111]
	v_mfma_f32_16x16x32_bf16 v[100:103], v[174:177], v[202:205], v[100:103]
	v_mfma_f32_16x16x32_bf16 v[92:95], v[182:185], v[202:205], v[92:95]
	v_mfma_f32_16x16x32_bf16 v[84:87], v[174:177], v[210:213], v[84:87]
	v_mfma_f32_16x16x32_bf16 v[76:79], v[182:185], v[210:213], v[76:79]
	v_mfma_f32_16x16x32_bf16 v[68:71], v[174:177], v[218:221], v[68:71]
	v_mfma_f32_16x16x32_bf16 v[64:67], v[182:185], v[218:221], v[64:67]
	s_setprio 0
	s_barrier
	s_add_i32 s20, s46, s29
	v_lshl_add_u64 v[144:145], v[144:145], 0, s[14:15]
	s_mov_b32 m0, s20
	ds_read_b128 v[186:189], v152 offset:49152
	ds_read_b128 v[190:193], v152 offset:50176
	ds_read_b128 v[198:201], v152 offset:51200
	ds_read_b128 v[202:205], v152 offset:52224
	ds_read_b128 v[206:209], v152 offset:53248
	ds_read_b128 v[210:213], v152 offset:54272
	ds_read_b128 v[214:217], v152 offset:55296
	ds_read_b128 v[218:221], v152 offset:56320
	global_load_lds_dwordx4 v[144:145], off
	s_add_i32 m0, s20, 0x2000
	s_add_u32 s20, s24, 0x18080
	v_lshl_add_u64 v[144:145], v[194:195], 0, s[14:15]
	s_addc_u32 s21, s25, 0
	s_add_i32 s24, s47, s29
	global_load_lds_dwordx4 v[144:145], off
	v_lshl_add_u64 v[144:145], s[20:21], 0, v[132:133]
	s_mov_b32 m0, s24
	s_nop 0
	global_load_lds_dwordx4 v[144:145], off
	v_lshl_add_u64 v[144:145], s[20:21], 0, v[128:129]
	s_add_i32 m0, s24, 0x2000
	s_nop 0
	global_load_lds_dwordx4 v[144:145], off
	v_lshl_add_u64 v[144:145], v[196:197], 0, s[14:15]
	s_mov_b32 m0, s49
	s_nop 0
	global_load_lds_dwordx4 v[144:145], off
	v_lshl_add_u64 v[144:145], v[222:223], 0, s[14:15]
	s_mov_b32 m0, s50
	s_nop 0
	global_load_lds_dwordx4 v[144:145], off
	s_waitcnt vmcnt(8)
	s_waitcnt lgkmcnt(0)
	s_barrier
	s_setprio 1
	s_waitcnt lgkmcnt(0)
	v_mfma_f32_16x16x32_bf16 v[60:63], v[154:157], v[186:189], v[60:63]
	v_mfma_f32_16x16x32_bf16 v[56:59], v[162:165], v[186:189], v[56:59]
	v_mfma_f32_16x16x32_bf16 v[48:51], v[154:157], v[198:201], v[48:51]
	v_mfma_f32_16x16x32_bf16 v[40:43], v[162:165], v[198:201], v[40:43]
	v_mfma_f32_16x16x32_bf16 v[32:35], v[154:157], v[206:209], v[32:35]
	v_mfma_f32_16x16x32_bf16 v[24:27], v[162:165], v[206:209], v[24:27]
	v_mfma_f32_16x16x32_bf16 v[16:19], v[154:157], v[214:217], v[16:19]
	v_mfma_f32_16x16x32_bf16 v[8:11], v[162:165], v[214:217], v[8:11]
	v_mfma_f32_16x16x32_bf16 v[60:63], v[158:161], v[190:193], v[60:63]
	v_mfma_f32_16x16x32_bf16 v[56:59], v[166:169], v[190:193], v[56:59]
	v_mfma_f32_16x16x32_bf16 v[48:51], v[158:161], v[202:205], v[48:51]
	v_mfma_f32_16x16x32_bf16 v[40:43], v[166:169], v[202:205], v[40:43]
	v_mfma_f32_16x16x32_bf16 v[32:35], v[158:161], v[210:213], v[32:35]
	v_mfma_f32_16x16x32_bf16 v[24:27], v[166:169], v[210:213], v[24:27]
	v_mfma_f32_16x16x32_bf16 v[16:19], v[158:161], v[218:221], v[16:19]
	v_mfma_f32_16x16x32_bf16 v[8:11], v[166:169], v[218:221], v[8:11]
	s_setprio 0
	s_setprio 1
	v_mfma_f32_16x16x32_bf16 v[52:55], v[170:173], v[186:189], v[52:55]
	v_mfma_f32_16x16x32_bf16 v[44:47], v[178:181], v[186:189], v[44:47]
	v_mfma_f32_16x16x32_bf16 v[36:39], v[170:173], v[198:201], v[36:39]
	v_mfma_f32_16x16x32_bf16 v[28:31], v[178:181], v[198:201], v[28:31]
	v_mfma_f32_16x16x32_bf16 v[20:23], v[170:173], v[206:209], v[20:23]
	v_mfma_f32_16x16x32_bf16 v[12:15], v[178:181], v[206:209], v[12:15]
	v_mfma_f32_16x16x32_bf16 v[4:7], v[170:173], v[214:217], v[4:7]
	v_mfma_f32_16x16x32_bf16 v[0:3], v[178:181], v[214:217], v[0:3]
	v_mfma_f32_16x16x32_bf16 v[52:55], v[174:177], v[190:193], v[52:55]
	v_mfma_f32_16x16x32_bf16 v[44:47], v[182:185], v[190:193], v[44:47]
	v_mfma_f32_16x16x32_bf16 v[36:39], v[174:177], v[202:205], v[36:39]
	v_mfma_f32_16x16x32_bf16 v[28:31], v[182:185], v[202:205], v[28:31]
	v_mfma_f32_16x16x32_bf16 v[20:23], v[174:177], v[210:213], v[20:23]
	v_mfma_f32_16x16x32_bf16 v[12:15], v[182:185], v[210:213], v[12:15]
	v_mfma_f32_16x16x32_bf16 v[4:7], v[174:177], v[218:221], v[4:7]
	v_mfma_f32_16x16x32_bf16 v[0:3], v[182:185], v[218:221], v[0:3]
	s_setprio 0
	s_barrier
	s_add_i32 s60, s60, 2
	s_add_u32 s58, s58, 0x100
	s_addc_u32 s59, s59, 0
	s_cmp_gt_u32 s60, 3
	s_mov_b64 s[20:21], s[22:23]
	s_cbranch_scc0 .LBB0_704
	s_and_b64 vcc, exec, s[16:17]
	s_cbranch_vccz .LBB0_707
	s_barrier

.LBB0_724:
	s_add_u32 s64, s52, s46
	s_addc_u32 s65, s53, 0
	s_add_u32 s47, s64, 0x100
	s_addc_u32 s60, s65, 0
	s_and_b64 s[58:59], s[56:57], exec
	s_cselect_b32 s61, s27, s60
	s_cselect_b32 s60, s79, s47
	s_add_u32 s46, s42, s46
	s_addc_u32 s47, s43, 0
	s_add_u32 s58, s46, 0x100
	s_addc_u32 s59, s47, 0
	s_and_b64 s[46:47], s[56:57], exec
	s_cselect_b32 s63, s25, s59
	s_cselect_b32 s62, s80, s58
	s_add_u32 s66, s64, 0x10080
	ds_read_b128 v[148:151], v145
	ds_read_b128 v[152:155], v145 offset:1024
	ds_read_b128 v[156:159], v145 offset:2048
	ds_read_b128 v[160:163], v145 offset:3072
	ds_read_b128 v[164:167], v146
	ds_read_b128 v[168:171], v146 offset:1024
	ds_read_b128 v[172:175], v146 offset:2048
	ds_read_b128 v[176:179], v146 offset:3072
	s_addc_u32 s67, s65, 0
	s_add_i32 s86, s72, s45
	s_add_i32 m0, s5, 0xc000
	s_add_i32 s89, s5, 0xe000
	s_add_i32 s83, s86, 0x2000
	s_add_u32 s64, s62, 0x10000
	s_addc_u32 s65, s63, 0
	s_add_i32 s85, s73, s45
	s_add_i32 s84, s85, 0x2000
	s_add_i32 s82, 0, 0x18000
	s_add_i32 s81, 0, 0x1c000
	s_add_u32 s58, s60, 0x10000
	s_addc_u32 s59, s61, 0
	s_add_i32 s47, s82, s45
	s_add_i32 s46, s47, 0x2000
	s_add_u32 s56, s62, 0x10080
	s_addc_u32 s57, s63, 0
	s_add_i32 s88, s81, s45
	s_add_i32 s87, s88, 0x2000
	v_lshl_add_u64 v[140:141], s[66:67], 0, v[134:135]
	ds_read_b128 v[180:183], v147
	ds_read_b128 v[184:187], v147 offset:1024
	ds_read_b128 v[188:191], v147 offset:2048
	ds_read_b128 v[192:195], v147 offset:3072
	ds_read_b128 v[198:201], v147 offset:4096
	ds_read_b128 v[202:205], v147 offset:5120
	ds_read_b128 v[206:209], v147 offset:6144
	ds_read_b128 v[210:213], v147 offset:7168
	global_load_lds_dwordx4 v[140:141], off
	v_lshl_add_u64 v[140:141], s[66:67], 0, v[130:131]
	s_mov_b32 m0, s89
	s_nop 0
	global_load_lds_dwordx4 v[140:141], off
	s_nop 0
	s_waitcnt vmcnt(8)
	s_waitcnt lgkmcnt(0)
	s_barrier
	s_setprio 1
	s_waitcnt lgkmcnt(0)
	v_mfma_f32_16x16x32_bf16 v[124:127], v[148:151], v[180:183], v[124:127]
	v_mfma_f32_16x16x32_bf16 v[120:123], v[156:159], v[180:183], v[120:123]
	v_mfma_f32_16x16x32_bf16 v[112:115], v[148:151], v[188:191], v[112:115]
	v_mfma_f32_16x16x32_bf16 v[104:107], v[156:159], v[188:191], v[104:107]
	v_mfma_f32_16x16x32_bf16 v[96:99], v[148:151], v[198:201], v[96:99]
	v_mfma_f32_16x16x32_bf16 v[88:91], v[156:159], v[198:201], v[88:91]
	v_mfma_f32_16x16x32_bf16 v[80:83], v[148:151], v[206:209], v[80:83]
	v_mfma_f32_16x16x32_bf16 v[72:75], v[156:159], v[206:209], v[72:75]
	v_mfma_f32_16x16x32_bf16 v[124:127], v[152:155], v[184:187], v[124:127]
	v_mfma_f32_16x16x32_bf16 v[120:123], v[160:163], v[184:187], v[120:123]
	v_mfma_f32_16x16x32_bf16 v[112:115], v[152:155], v[192:195], v[112:115]
	v_mfma_f32_16x16x32_bf16 v[104:107], v[160:163], v[192:195], v[104:107]
	v_mfma_f32_16x16x32_bf16 v[96:99], v[152:155], v[202:205], v[96:99]
	v_mfma_f32_16x16x32_bf16 v[88:91], v[160:163], v[202:205], v[88:91]
	v_mfma_f32_16x16x32_bf16 v[80:83], v[152:155], v[210:213], v[80:83]
	v_mfma_f32_16x16x32_bf16 v[72:75], v[160:163], v[210:213], v[72:75]
	s_setprio 0
	s_setprio 1
	v_mfma_f32_16x16x32_bf16 v[116:119], v[164:167], v[180:183], v[116:119]
	v_mfma_f32_16x16x32_bf16 v[108:111], v[172:175], v[180:183], v[108:111]
	v_mfma_f32_16x16x32_bf16 v[100:103], v[164:167], v[188:191], v[100:103]
	v_mfma_f32_16x16x32_bf16 v[92:95], v[172:175], v[188:191], v[92:95]
	v_mfma_f32_16x16x32_bf16 v[84:87], v[164:167], v[198:201], v[84:87]
	v_mfma_f32_16x16x32_bf16 v[76:79], v[172:175], v[198:201], v[76:79]
	v_mfma_f32_16x16x32_bf16 v[68:71], v[164:167], v[206:209], v[68:71]
	v_mfma_f32_16x16x32_bf16 v[64:67], v[172:175], v[206:209], v[64:67]
	v_mfma_f32_16x16x32_bf16 v[116:119], v[168:171], v[184:187], v[116:119]
	v_mfma_f32_16x16x32_bf16 v[108:111], v[176:179], v[184:187], v[108:111]
	v_mfma_f32_16x16x32_bf16 v[100:103], v[168:171], v[192:195], v[100:103]
	v_mfma_f32_16x16x32_bf16 v[92:95], v[176:179], v[192:195], v[92:95]
	v_mfma_f32_16x16x32_bf16 v[84:87], v[168:171], v[202:205], v[84:87]
	v_mfma_f32_16x16x32_bf16 v[76:79], v[176:179], v[202:205], v[76:79]
	v_mfma_f32_16x16x32_bf16 v[68:71], v[168:171], v[210:213], v[68:71]
	v_mfma_f32_16x16x32_bf16 v[64:67], v[176:179], v[210:213], v[64:67]
	s_setprio 0
	s_barrier
	s_mov_b32 m0, s86
	v_lshl_add_u64 v[140:141], s[62:63], 0, v[132:133]
	ds_read_b128 v[180:183], v147 offset:16384
	ds_read_b128 v[184:187], v147 offset:17408
	ds_read_b128 v[188:191], v147 offset:18432
	ds_read_b128 v[192:195], v147 offset:19456
	ds_read_b128 v[198:201], v147 offset:20480
	ds_read_b128 v[202:205], v147 offset:21504
	ds_read_b128 v[206:209], v147 offset:22528
	ds_read_b128 v[210:213], v147 offset:23552
	global_load_lds_dwordx4 v[140:141], off
	v_lshl_add_u64 v[196:197], s[62:63], 0, v[128:129]
	s_mov_b32 m0, s83
	v_lshl_add_u64 v[214:215], s[64:65], 0, v[132:133]
	global_load_lds_dwordx4 v[196:197], off
	s_mov_b32 m0, s85
	v_lshl_add_u64 v[216:217], s[60:61], 0, v[130:131]
	global_load_lds_dwordx4 v[214:215], off
	v_lshl_add_u64 v[214:215], s[64:65], 0, v[128:129]
	s_mov_b32 m0, s84
	s_nop 0
	global_load_lds_dwordx4 v[214:215], off
	v_lshl_add_u64 v[214:215], s[60:61], 0, v[134:135]
	s_mov_b32 m0, s5
	s_nop 0
	global_load_lds_dwordx4 v[214:215], off
	s_mov_b32 m0, s35
	s_nop 0
	global_load_lds_dwordx4 v[216:217], off
	s_waitcnt vmcnt(8)
	s_waitcnt lgkmcnt(0)
	s_barrier
	s_setprio 1
	s_waitcnt lgkmcnt(0)
	v_mfma_f32_16x16x32_bf16 v[60:63], v[148:151], v[180:183], v[60:63]
	v_mfma_f32_16x16x32_bf16 v[56:59], v[156:159], v[180:183], v[56:59]
	v_mfma_f32_16x16x32_bf16 v[48:51], v[148:151], v[188:191], v[48:51]
	v_mfma_f32_16x16x32_bf16 v[40:43], v[156:159], v[188:191], v[40:43]
	v_mfma_f32_16x16x32_bf16 v[32:35], v[148:151], v[198:201], v[32:35]
	v_mfma_f32_16x16x32_bf16 v[24:27], v[156:159], v[198:201], v[24:27]
	v_mfma_f32_16x16x32_bf16 v[16:19], v[148:151], v[206:209], v[16:19]
	v_mfma_f32_16x16x32_bf16 v[8:11], v[156:159], v[206:209], v[8:11]
	v_mfma_f32_16x16x32_bf16 v[60:63], v[152:155], v[184:187], v[60:63]
	v_mfma_f32_16x16x32_bf16 v[56:59], v[160:163], v[184:187], v[56:59]
	v_mfma_f32_16x16x32_bf16 v[48:51], v[152:155], v[192:195], v[48:51]
	v_mfma_f32_16x16x32_bf16 v[40:43], v[160:163], v[192:195], v[40:43]
	v_mfma_f32_16x16x32_bf16 v[32:35], v[152:155], v[202:205], v[32:35]
	v_mfma_f32_16x16x32_bf16 v[24:27], v[160:163], v[202:205], v[24:27]
	v_mfma_f32_16x16x32_bf16 v[16:19], v[152:155], v[210:213], v[16:19]
	v_mfma_f32_16x16x32_bf16 v[8:11], v[160:163], v[210:213], v[8:11]
	s_setprio 0
	s_setprio 1
	v_mfma_f32_16x16x32_bf16 v[52:55], v[164:167], v[180:183], v[52:55]
	v_mfma_f32_16x16x32_bf16 v[44:47], v[172:175], v[180:183], v[44:47]
	v_mfma_f32_16x16x32_bf16 v[36:39], v[164:167], v[188:191], v[36:39]
	v_mfma_f32_16x16x32_bf16 v[28:31], v[172:175], v[188:191], v[28:31]
	v_mfma_f32_16x16x32_bf16 v[20:23], v[164:167], v[198:201], v[20:23]
	v_mfma_f32_16x16x32_bf16 v[12:15], v[172:175], v[198:201], v[12:15]
	v_mfma_f32_16x16x32_bf16 v[4:7], v[164:167], v[206:209], v[4:7]
	v_mfma_f32_16x16x32_bf16 v[0:3], v[172:175], v[206:209], v[0:3]
	v_mfma_f32_16x16x32_bf16 v[52:55], v[168:171], v[184:187], v[52:55]
	v_mfma_f32_16x16x32_bf16 v[44:47], v[176:179], v[184:187], v[44:47]
	v_mfma_f32_16x16x32_bf16 v[36:39], v[168:171], v[192:195], v[36:39]
	v_mfma_f32_16x16x32_bf16 v[28:31], v[176:179], v[192:195], v[28:31]
	v_mfma_f32_16x16x32_bf16 v[20:23], v[168:171], v[202:205], v[20:23]
	v_mfma_f32_16x16x32_bf16 v[12:15], v[176:179], v[202:205], v[12:15]
	v_mfma_f32_16x16x32_bf16 v[4:7], v[168:171], v[210:213], v[4:7]
	v_mfma_f32_16x16x32_bf16 v[0:3], v[176:179], v[210:213], v[0:3]
	s_setprio 0
	s_barrier
	v_add_u32_e32 v160, s82, v143
	v_add_u32_e32 v176, s81, v143
	ds_read_b128 v[148:151], v160
	ds_read_b128 v[152:155], v160 offset:1024
	ds_read_b128 v[156:159], v160 offset:2048
	ds_read_b128 v[160:163], v160 offset:3072
	ds_read_b128 v[164:167], v176
	ds_read_b128 v[168:171], v176 offset:1024
	ds_read_b128 v[172:175], v176 offset:2048
	ds_read_b128 v[176:179], v176 offset:3072
	s_mov_b32 m0, s41
	v_lshl_add_u64 v[218:219], s[58:59], 0, v[134:135]
	ds_read_b128 v[180:183], v147 offset:32768
	ds_read_b128 v[184:187], v147 offset:33792
	ds_read_b128 v[188:191], v147 offset:34816
	ds_read_b128 v[192:195], v147 offset:35840
	ds_read_b128 v[198:201], v147 offset:36864
	ds_read_b128 v[202:205], v147 offset:37888
	ds_read_b128 v[206:209], v147 offset:38912
	ds_read_b128 v[210:213], v147 offset:39936
	global_load_lds_dwordx4 v[218:219], off
	v_lshl_add_u64 v[218:219], s[58:59], 0, v[130:131]
	s_mov_b32 m0, s68
	s_nop 0
	global_load_lds_dwordx4 v[218:219], off
	s_waitcnt vmcnt(8)
	s_waitcnt lgkmcnt(0)
	s_barrier
	s_setprio 1
	s_waitcnt lgkmcnt(0)
	v_mfma_f32_16x16x32_bf16 v[124:127], v[148:151], v[180:183], v[124:127]
	v_mfma_f32_16x16x32_bf16 v[120:123], v[156:159], v[180:183], v[120:123]
	v_mfma_f32_16x16x32_bf16 v[112:115], v[148:151], v[188:191], v[112:115]
	v_mfma_f32_16x16x32_bf16 v[104:107], v[156:159], v[188:191], v[104:107]
	v_mfma_f32_16x16x32_bf16 v[96:99], v[148:151], v[198:201], v[96:99]
	v_mfma_f32_16x16x32_bf16 v[88:91], v[156:159], v[198:201], v[88:91]
	v_mfma_f32_16x16x32_bf16 v[80:83], v[148:151], v[206:209], v[80:83]
	v_mfma_f32_16x16x32_bf16 v[72:75], v[156:159], v[206:209], v[72:75]
	v_mfma_f32_16x16x32_bf16 v[124:127], v[152:155], v[184:187], v[124:127]
	v_mfma_f32_16x16x32_bf16 v[120:123], v[160:163], v[184:187], v[120:123]
	v_mfma_f32_16x16x32_bf16 v[112:115], v[152:155], v[192:195], v[112:115]
	v_mfma_f32_16x16x32_bf16 v[104:107], v[160:163], v[192:195], v[104:107]
	v_mfma_f32_16x16x32_bf16 v[96:99], v[152:155], v[202:205], v[96:99]
	v_mfma_f32_16x16x32_bf16 v[88:91], v[160:163], v[202:205], v[88:91]
	v_mfma_f32_16x16x32_bf16 v[80:83], v[152:155], v[210:213], v[80:83]
	v_mfma_f32_16x16x32_bf16 v[72:75], v[160:163], v[210:213], v[72:75]
	s_setprio 0
	s_setprio 1
	v_mfma_f32_16x16x32_bf16 v[116:119], v[164:167], v[180:183], v[116:119]
	v_mfma_f32_16x16x32_bf16 v[108:111], v[172:175], v[180:183], v[108:111]
	v_mfma_f32_16x16x32_bf16 v[100:103], v[164:167], v[188:191], v[100:103]
	v_mfma_f32_16x16x32_bf16 v[92:95], v[172:175], v[188:191], v[92:95]
	v_mfma_f32_16x16x32_bf16 v[84:87], v[164:167], v[198:201], v[84:87]
	v_mfma_f32_16x16x32_bf16 v[76:79], v[172:175], v[198:201], v[76:79]
	v_mfma_f32_16x16x32_bf16 v[68:71], v[164:167], v[206:209], v[68:71]
	v_mfma_f32_16x16x32_bf16 v[64:67], v[172:175], v[206:209], v[64:67]
	v_mfma_f32_16x16x32_bf16 v[116:119], v[168:171], v[184:187], v[116:119]
	v_mfma_f32_16x16x32_bf16 v[108:111], v[176:179], v[184:187], v[108:111]
	v_mfma_f32_16x16x32_bf16 v[100:103], v[168:171], v[192:195], v[100:103]
	v_mfma_f32_16x16x32_bf16 v[92:95], v[176:179], v[192:195], v[92:95]
	v_mfma_f32_16x16x32_bf16 v[84:87], v[168:171], v[202:205], v[84:87]
	v_mfma_f32_16x16x32_bf16 v[76:79], v[176:179], v[202:205], v[76:79]
	v_mfma_f32_16x16x32_bf16 v[68:71], v[168:171], v[210:213], v[68:71]
	v_mfma_f32_16x16x32_bf16 v[64:67], v[176:179], v[210:213], v[64:67]
	s_setprio 0
	s_barrier
	s_mov_b32 m0, s47
	v_lshl_add_u64 v[140:141], v[140:141], 0, s[12:13]
	ds_read_b128 v[180:183], v147 offset:49152
	ds_read_b128 v[184:187], v147 offset:50176
	ds_read_b128 v[188:191], v147 offset:51200
	ds_read_b128 v[192:195], v147 offset:52224
	ds_read_b128 v[198:201], v147 offset:53248
	ds_read_b128 v[202:205], v147 offset:54272
	ds_read_b128 v[206:209], v147 offset:55296
	ds_read_b128 v[210:213], v147 offset:56320
	global_load_lds_dwordx4 v[140:141], off
	v_lshl_add_u64 v[140:141], v[196:197], 0, s[12:13]
	s_mov_b32 m0, s46
	s_nop 0
	global_load_lds_dwordx4 v[140:141], off
	v_lshl_add_u64 v[140:141], s[56:57], 0, v[132:133]
	s_mov_b32 m0, s88
	s_nop 0
	global_load_lds_dwordx4 v[140:141], off
	v_lshl_add_u64 v[140:141], s[56:57], 0, v[128:129]
	s_mov_b32 m0, s87
	s_nop 0
	global_load_lds_dwordx4 v[140:141], off
	v_lshl_add_u64 v[140:141], v[214:215], 0, s[12:13]
	s_mov_b32 m0, s70
	s_nop 0
	global_load_lds_dwordx4 v[140:141], off
	v_lshl_add_u64 v[140:141], v[216:217], 0, s[12:13]
	s_mov_b32 m0, s71
	s_nop 0
	global_load_lds_dwordx4 v[140:141], off
	s_waitcnt vmcnt(8)
	s_waitcnt lgkmcnt(0)
	s_barrier
	s_setprio 1
	s_waitcnt lgkmcnt(0)
	v_mfma_f32_16x16x32_bf16 v[60:63], v[148:151], v[180:183], v[60:63]
	v_mfma_f32_16x16x32_bf16 v[56:59], v[156:159], v[180:183], v[56:59]
	v_mfma_f32_16x16x32_bf16 v[48:51], v[148:151], v[188:191], v[48:51]
	v_mfma_f32_16x16x32_bf16 v[40:43], v[156:159], v[188:191], v[40:43]
	v_mfma_f32_16x16x32_bf16 v[32:35], v[148:151], v[198:201], v[32:35]
	v_mfma_f32_16x16x32_bf16 v[24:27], v[156:159], v[198:201], v[24:27]
	v_mfma_f32_16x16x32_bf16 v[16:19], v[148:151], v[206:209], v[16:19]
	v_mfma_f32_16x16x32_bf16 v[8:11], v[156:159], v[206:209], v[8:11]
	v_mfma_f32_16x16x32_bf16 v[60:63], v[152:155], v[184:187], v[60:63]
	v_mfma_f32_16x16x32_bf16 v[56:59], v[160:163], v[184:187], v[56:59]
	v_mfma_f32_16x16x32_bf16 v[48:51], v[152:155], v[192:195], v[48:51]
	v_mfma_f32_16x16x32_bf16 v[40:43], v[160:163], v[192:195], v[40:43]
	v_mfma_f32_16x16x32_bf16 v[32:35], v[152:155], v[202:205], v[32:35]
	v_mfma_f32_16x16x32_bf16 v[24:27], v[160:163], v[202:205], v[24:27]
	v_mfma_f32_16x16x32_bf16 v[16:19], v[152:155], v[210:213], v[16:19]
	v_mfma_f32_16x16x32_bf16 v[8:11], v[160:163], v[210:213], v[8:11]
	s_setprio 0
	s_setprio 1
	v_mfma_f32_16x16x32_bf16 v[52:55], v[164:167], v[180:183], v[52:55]
	v_mfma_f32_16x16x32_bf16 v[44:47], v[172:175], v[180:183], v[44:47]
	v_mfma_f32_16x16x32_bf16 v[36:39], v[164:167], v[188:191], v[36:39]
	v_mfma_f32_16x16x32_bf16 v[28:31], v[172:175], v[188:191], v[28:31]
	v_mfma_f32_16x16x32_bf16 v[20:23], v[164:167], v[198:201], v[20:23]
	v_mfma_f32_16x16x32_bf16 v[12:15], v[172:175], v[198:201], v[12:15]
	v_mfma_f32_16x16x32_bf16 v[4:7], v[164:167], v[206:209], v[4:7]
	v_mfma_f32_16x16x32_bf16 v[0:3], v[172:175], v[206:209], v[0:3]
	v_mfma_f32_16x16x32_bf16 v[52:55], v[168:171], v[184:187], v[52:55]
	v_mfma_f32_16x16x32_bf16 v[44:47], v[176:179], v[184:187], v[44:47]
	v_mfma_f32_16x16x32_bf16 v[36:39], v[168:171], v[192:195], v[36:39]
	v_mfma_f32_16x16x32_bf16 v[28:31], v[176:179], v[192:195], v[28:31]
	v_mfma_f32_16x16x32_bf16 v[20:23], v[168:171], v[202:205], v[20:23]
	v_mfma_f32_16x16x32_bf16 v[12:15], v[176:179], v[202:205], v[12:15]
	v_mfma_f32_16x16x32_bf16 v[4:7], v[168:171], v[210:213], v[4:7]
	v_mfma_f32_16x16x32_bf16 v[0:3], v[176:179], v[210:213], v[0:3]
	s_setprio 0
	s_barrier
	s_movk_i32 s46, 0x100
	s_andn2_b64 vcc, exec, s[54:55]
	s_mov_b64 s[56:57], -1
	s_mov_b64 s[54:55], 0
	s_cbranch_vccz .LBB0_724
	s_and_b64 vcc, exec, s[14:15]
	s_cbranch_vccz .LBB0_727
	s_barrier

.LBB0_1077:
	ds_read_b128 v[144:147], v154
	ds_read_b128 v[158:161], v154 offset:1024
	ds_read_b128 v[162:165], v154 offset:2048
	ds_read_b128 v[166:169], v154 offset:3072
	ds_read_b128 v[170:173], v155
	ds_read_b128 v[174:177], v155 offset:1024
	ds_read_b128 v[178:181], v155 offset:2048
	ds_read_b128 v[182:185], v155 offset:3072
	s_add_u32 s46, s52, 0xfffc0080
	s_addc_u32 s47, s53, -1
	s_cmp_eq_u32 s69, 12
	s_cselect_b32 s57, s29, s47
	s_cselect_b32 s56, s65, s46
	s_cselect_b32 s55, s27, s68
	s_cselect_b32 s54, s66, s67
	v_lshl_add_u64 v[148:149], s[52:53], 0, v[136:137]
	s_add_i32 m0, s43, 0xc000
	ds_read_b128 v[186:189], v156
	ds_read_b128 v[190:193], v156 offset:1024
	ds_read_b128 v[198:201], v156 offset:2048
	ds_read_b128 v[202:205], v156 offset:3072
	ds_read_b128 v[206:209], v156 offset:4096
	ds_read_b128 v[210:213], v156 offset:5120
	ds_read_b128 v[214:217], v156 offset:6144
	ds_read_b128 v[218:221], v156 offset:7168
	global_load_lds_dwordx4 v[148:149], off
	v_lshl_add_u64 v[148:149], s[52:53], 0, v[138:139]
	s_add_i32 m0, s43, 0xe000
	s_nop 0
	global_load_lds_dwordx4 v[148:149], off
	s_waitcnt vmcnt(8)
	s_waitcnt lgkmcnt(0)
	s_barrier
	s_setprio 1
	s_waitcnt lgkmcnt(0)
	v_mfma_f32_16x16x32_bf16 v[124:127], v[144:147], v[186:189], v[124:127]
	v_mfma_f32_16x16x32_bf16 v[120:123], v[162:165], v[186:189], v[120:123]
	v_mfma_f32_16x16x32_bf16 v[108:111], v[144:147], v[198:201], v[108:111]
	v_mfma_f32_16x16x32_bf16 v[104:107], v[162:165], v[198:201], v[104:107]
	v_mfma_f32_16x16x32_bf16 v[92:95], v[144:147], v[206:209], v[92:95]
	v_mfma_f32_16x16x32_bf16 v[88:91], v[162:165], v[206:209], v[88:91]
	v_mfma_f32_16x16x32_bf16 v[76:79], v[144:147], v[214:217], v[76:79]
	v_mfma_f32_16x16x32_bf16 v[72:75], v[162:165], v[214:217], v[72:75]
	v_mfma_f32_16x16x32_bf16 v[124:127], v[158:161], v[190:193], v[124:127]
	v_mfma_f32_16x16x32_bf16 v[120:123], v[166:169], v[190:193], v[120:123]
	v_mfma_f32_16x16x32_bf16 v[108:111], v[158:161], v[202:205], v[108:111]
	v_mfma_f32_16x16x32_bf16 v[104:107], v[166:169], v[202:205], v[104:107]
	v_mfma_f32_16x16x32_bf16 v[92:95], v[158:161], v[210:213], v[92:95]
	v_mfma_f32_16x16x32_bf16 v[88:91], v[166:169], v[210:213], v[88:91]
	v_mfma_f32_16x16x32_bf16 v[76:79], v[158:161], v[218:221], v[76:79]
	v_mfma_f32_16x16x32_bf16 v[72:75], v[166:169], v[218:221], v[72:75]
	s_setprio 0
	s_setprio 1
	v_mfma_f32_16x16x32_bf16 v[116:119], v[170:173], v[186:189], v[116:119]
	v_mfma_f32_16x16x32_bf16 v[112:115], v[178:181], v[186:189], v[112:115]
	v_mfma_f32_16x16x32_bf16 v[100:103], v[170:173], v[198:201], v[100:103]
	v_mfma_f32_16x16x32_bf16 v[96:99], v[178:181], v[198:201], v[96:99]
	v_mfma_f32_16x16x32_bf16 v[84:87], v[170:173], v[206:209], v[84:87]
	v_mfma_f32_16x16x32_bf16 v[80:83], v[178:181], v[206:209], v[80:83]
	v_mfma_f32_16x16x32_bf16 v[68:71], v[170:173], v[214:217], v[68:71]
	v_mfma_f32_16x16x32_bf16 v[64:67], v[178:181], v[214:217], v[64:67]
	v_mfma_f32_16x16x32_bf16 v[116:119], v[174:177], v[190:193], v[116:119]
	v_mfma_f32_16x16x32_bf16 v[112:115], v[182:185], v[190:193], v[112:115]
	v_mfma_f32_16x16x32_bf16 v[100:103], v[174:177], v[202:205], v[100:103]
	v_mfma_f32_16x16x32_bf16 v[96:99], v[182:185], v[202:205], v[96:99]
	v_mfma_f32_16x16x32_bf16 v[84:87], v[174:177], v[210:213], v[84:87]
	v_mfma_f32_16x16x32_bf16 v[80:83], v[182:185], v[210:213], v[80:83]
	v_mfma_f32_16x16x32_bf16 v[68:71], v[174:177], v[218:221], v[68:71]
	v_mfma_f32_16x16x32_bf16 v[64:67], v[182:185], v[218:221], v[64:67]
	s_setprio 0
	s_barrier
	s_add_i32 s46, s61, s4
	v_lshl_add_u64 v[148:149], s[54:55], 0, v[132:133]
	s_mov_b32 m0, s46
	ds_read_b128 v[186:189], v156 offset:16384
	ds_read_b128 v[190:193], v156 offset:17408
	ds_read_b128 v[198:201], v156 offset:18432
	ds_read_b128 v[202:205], v156 offset:19456
	ds_read_b128 v[206:209], v156 offset:20480
	ds_read_b128 v[210:213], v156 offset:21504
	ds_read_b128 v[214:217], v156 offset:22528
	ds_read_b128 v[218:221], v156 offset:23552
	global_load_lds_dwordx4 v[148:149], off
	s_add_i32 m0, s46, 0x2000
	s_add_u32 s46, s54, 0x40000
	v_lshl_add_u64 v[194:195], s[54:55], 0, v[128:129]
	s_addc_u32 s47, s55, 0
	s_add_i32 s70, s64, s4
	global_load_lds_dwordx4 v[194:195], off
	v_lshl_add_u64 v[196:197], s[46:47], 0, v[132:133]
	s_mov_b32 m0, s70
	v_lshl_add_u64 v[222:223], s[56:57], 0, v[130:131]
	global_load_lds_dwordx4 v[196:197], off
	v_lshl_add_u64 v[196:197], s[46:47], 0, v[128:129]
	s_add_i32 m0, s70, 0x2000
	s_nop 0
	global_load_lds_dwordx4 v[196:197], off
	v_lshl_add_u64 v[196:197], s[56:57], 0, v[134:135]
	s_mov_b32 m0, s43
	s_nop 0
	global_load_lds_dwordx4 v[196:197], off
	s_mov_b32 m0, s48
	s_nop 0
	global_load_lds_dwordx4 v[222:223], off
	s_nop 0
	s_waitcnt vmcnt(8)
	s_waitcnt lgkmcnt(0)
	s_barrier
	s_setprio 1
	s_waitcnt lgkmcnt(0)
	v_mfma_f32_16x16x32_bf16 v[60:63], v[144:147], v[186:189], v[60:63]
	v_mfma_f32_16x16x32_bf16 v[56:59], v[162:165], v[186:189], v[56:59]
	v_mfma_f32_16x16x32_bf16 v[44:47], v[144:147], v[198:201], v[44:47]
	v_mfma_f32_16x16x32_bf16 v[40:43], v[162:165], v[198:201], v[40:43]
	v_mfma_f32_16x16x32_bf16 v[28:31], v[144:147], v[206:209], v[28:31]
	v_mfma_f32_16x16x32_bf16 v[24:27], v[162:165], v[206:209], v[24:27]
	v_mfma_f32_16x16x32_bf16 v[12:15], v[144:147], v[214:217], v[12:15]
	v_mfma_f32_16x16x32_bf16 v[8:11], v[162:165], v[214:217], v[8:11]
	v_mfma_f32_16x16x32_bf16 v[60:63], v[158:161], v[190:193], v[60:63]
	v_mfma_f32_16x16x32_bf16 v[56:59], v[166:169], v[190:193], v[56:59]
	v_mfma_f32_16x16x32_bf16 v[44:47], v[158:161], v[202:205], v[44:47]
	v_mfma_f32_16x16x32_bf16 v[40:43], v[166:169], v[202:205], v[40:43]
	v_mfma_f32_16x16x32_bf16 v[28:31], v[158:161], v[210:213], v[28:31]
	v_mfma_f32_16x16x32_bf16 v[24:27], v[166:169], v[210:213], v[24:27]
	v_mfma_f32_16x16x32_bf16 v[12:15], v[158:161], v[218:221], v[12:15]
	v_mfma_f32_16x16x32_bf16 v[8:11], v[166:169], v[218:221], v[8:11]
	s_setprio 0
	s_setprio 1
	v_mfma_f32_16x16x32_bf16 v[52:55], v[170:173], v[186:189], v[52:55]
	v_mfma_f32_16x16x32_bf16 v[48:51], v[178:181], v[186:189], v[48:51]
	v_mfma_f32_16x16x32_bf16 v[36:39], v[170:173], v[198:201], v[36:39]
	v_mfma_f32_16x16x32_bf16 v[32:35], v[178:181], v[198:201], v[32:35]
	v_mfma_f32_16x16x32_bf16 v[20:23], v[170:173], v[206:209], v[20:23]
	v_mfma_f32_16x16x32_bf16 v[16:19], v[178:181], v[206:209], v[16:19]
	v_mfma_f32_16x16x32_bf16 v[4:7], v[170:173], v[214:217], v[4:7]
	v_mfma_f32_16x16x32_bf16 v[0:3], v[178:181], v[214:217], v[0:3]
	v_mfma_f32_16x16x32_bf16 v[52:55], v[174:177], v[190:193], v[52:55]
	v_mfma_f32_16x16x32_bf16 v[48:51], v[182:185], v[190:193], v[48:51]
	v_mfma_f32_16x16x32_bf16 v[36:39], v[174:177], v[202:205], v[36:39]
	v_mfma_f32_16x16x32_bf16 v[32:35], v[182:185], v[202:205], v[32:35]
	v_mfma_f32_16x16x32_bf16 v[20:23], v[174:177], v[210:213], v[20:23]
	v_mfma_f32_16x16x32_bf16 v[16:19], v[182:185], v[210:213], v[16:19]
	v_mfma_f32_16x16x32_bf16 v[4:7], v[174:177], v[218:221], v[4:7]
	v_mfma_f32_16x16x32_bf16 v[0:3], v[182:185], v[218:221], v[0:3]
	s_setprio 0
	s_barrier
	s_add_i32 s70, 0, 0x18000
	v_add_u32_e32 v157, s70, v152
	s_add_i32 s71, 0, 0x1c000
	ds_read_b128 v[144:147], v157
	ds_read_b128 v[158:161], v157 offset:1024
	ds_read_b128 v[162:165], v157 offset:2048
	ds_read_b128 v[166:169], v157 offset:3072
	v_add_u32_e32 v157, s71, v152
	ds_read_b128 v[170:173], v157
	ds_read_b128 v[174:177], v157 offset:1024
	ds_read_b128 v[178:181], v157 offset:2048
	ds_read_b128 v[182:185], v157 offset:3072
	s_add_u32 s46, s56, 0x40000
	s_addc_u32 s47, s57, 0
	s_mov_b32 m0, s49
	v_lshl_add_u64 v[224:225], s[46:47], 0, v[134:135]
	ds_read_b128 v[186:189], v156 offset:32768
	ds_read_b128 v[190:193], v156 offset:33792
	ds_read_b128 v[198:201], v156 offset:34816
	ds_read_b128 v[202:205], v156 offset:35840
	ds_read_b128 v[206:209], v156 offset:36864
	ds_read_b128 v[210:213], v156 offset:37888
	ds_read_b128 v[214:217], v156 offset:38912
	ds_read_b128 v[218:221], v156 offset:39936
	global_load_lds_dwordx4 v[224:225], off
	v_lshl_add_u64 v[224:225], s[46:47], 0, v[130:131]
	s_mov_b32 m0, s50
	s_nop 0
	global_load_lds_dwordx4 v[224:225], off
	s_nop 0
	s_waitcnt vmcnt(8)
	s_waitcnt lgkmcnt(0)
	s_barrier
	s_setprio 1
	s_waitcnt lgkmcnt(0)
	v_mfma_f32_16x16x32_bf16 v[124:127], v[144:147], v[186:189], v[124:127]
	v_mfma_f32_16x16x32_bf16 v[120:123], v[162:165], v[186:189], v[120:123]
	v_mfma_f32_16x16x32_bf16 v[108:111], v[144:147], v[198:201], v[108:111]
	v_mfma_f32_16x16x32_bf16 v[104:107], v[162:165], v[198:201], v[104:107]
	v_mfma_f32_16x16x32_bf16 v[92:95], v[144:147], v[206:209], v[92:95]
	v_mfma_f32_16x16x32_bf16 v[88:91], v[162:165], v[206:209], v[88:91]
	v_mfma_f32_16x16x32_bf16 v[76:79], v[144:147], v[214:217], v[76:79]
	v_mfma_f32_16x16x32_bf16 v[72:75], v[162:165], v[214:217], v[72:75]
	v_mfma_f32_16x16x32_bf16 v[124:127], v[158:161], v[190:193], v[124:127]
	v_mfma_f32_16x16x32_bf16 v[120:123], v[166:169], v[190:193], v[120:123]
	v_mfma_f32_16x16x32_bf16 v[108:111], v[158:161], v[202:205], v[108:111]
	v_mfma_f32_16x16x32_bf16 v[104:107], v[166:169], v[202:205], v[104:107]
	v_mfma_f32_16x16x32_bf16 v[92:95], v[158:161], v[210:213], v[92:95]
	v_mfma_f32_16x16x32_bf16 v[88:91], v[166:169], v[210:213], v[88:91]
	v_mfma_f32_16x16x32_bf16 v[76:79], v[158:161], v[218:221], v[76:79]
	v_mfma_f32_16x16x32_bf16 v[72:75], v[166:169], v[218:221], v[72:75]
	s_setprio 0
	s_setprio 1
	v_mfma_f32_16x16x32_bf16 v[116:119], v[170:173], v[186:189], v[116:119]
	v_mfma_f32_16x16x32_bf16 v[112:115], v[178:181], v[186:189], v[112:115]
	v_mfma_f32_16x16x32_bf16 v[100:103], v[170:173], v[198:201], v[100:103]
	v_mfma_f32_16x16x32_bf16 v[96:99], v[178:181], v[198:201], v[96:99]
	v_mfma_f32_16x16x32_bf16 v[84:87], v[170:173], v[206:209], v[84:87]
	v_mfma_f32_16x16x32_bf16 v[80:83], v[178:181], v[206:209], v[80:83]
	v_mfma_f32_16x16x32_bf16 v[68:71], v[170:173], v[214:217], v[68:71]
	v_mfma_f32_16x16x32_bf16 v[64:67], v[178:181], v[214:217], v[64:67]
	v_mfma_f32_16x16x32_bf16 v[116:119], v[174:177], v[190:193], v[116:119]
	v_mfma_f32_16x16x32_bf16 v[112:115], v[182:185], v[190:193], v[112:115]
	v_mfma_f32_16x16x32_bf16 v[100:103], v[174:177], v[202:205], v[100:103]
	v_mfma_f32_16x16x32_bf16 v[96:99], v[182:185], v[202:205], v[96:99]
	v_mfma_f32_16x16x32_bf16 v[84:87], v[174:177], v[210:213], v[84:87]
	v_mfma_f32_16x16x32_bf16 v[80:83], v[182:185], v[210:213], v[80:83]
	v_mfma_f32_16x16x32_bf16 v[68:71], v[174:177], v[218:221], v[68:71]
	v_mfma_f32_16x16x32_bf16 v[64:67], v[182:185], v[218:221], v[64:67]
	s_setprio 0
	s_barrier
	s_add_i32 s46, s70, s4
	v_lshl_add_u64 v[148:149], v[148:149], 0, s[16:17]
	s_mov_b32 m0, s46
	ds_read_b128 v[186:189], v156 offset:49152
	ds_read_b128 v[190:193], v156 offset:50176
	ds_read_b128 v[198:201], v156 offset:51200
	ds_read_b128 v[202:205], v156 offset:52224
	ds_read_b128 v[206:209], v156 offset:53248
	ds_read_b128 v[210:213], v156 offset:54272
	ds_read_b128 v[214:217], v156 offset:55296
	ds_read_b128 v[218:221], v156 offset:56320
	global_load_lds_dwordx4 v[148:149], off
	s_add_i32 m0, s46, 0x2000
	s_add_u32 s46, s54, 0x40080
	v_lshl_add_u64 v[148:149], v[194:195], 0, s[16:17]
	s_addc_u32 s47, s55, 0
	s_add_i32 s54, s71, s4
	global_load_lds_dwordx4 v[148:149], off
	v_lshl_add_u64 v[148:149], s[46:47], 0, v[132:133]
	s_mov_b32 m0, s54
	s_nop 0
	global_load_lds_dwordx4 v[148:149], off
	v_lshl_add_u64 v[148:149], s[46:47], 0, v[128:129]
	s_add_i32 m0, s54, 0x2000
	s_nop 0
	global_load_lds_dwordx4 v[148:149], off
	v_lshl_add_u64 v[148:149], v[196:197], 0, s[16:17]
	s_mov_b32 m0, s58
	s_nop 0
	global_load_lds_dwordx4 v[148:149], off
	v_lshl_add_u64 v[148:149], v[222:223], 0, s[16:17]
	s_mov_b32 m0, s59
	s_nop 0
	global_load_lds_dwordx4 v[148:149], off
	s_waitcnt vmcnt(8)
	s_waitcnt lgkmcnt(0)
	s_barrier
	s_setprio 1
	s_waitcnt lgkmcnt(0)
	v_mfma_f32_16x16x32_bf16 v[60:63], v[144:147], v[186:189], v[60:63]
	v_mfma_f32_16x16x32_bf16 v[56:59], v[162:165], v[186:189], v[56:59]
	v_mfma_f32_16x16x32_bf16 v[44:47], v[144:147], v[198:201], v[44:47]
	v_mfma_f32_16x16x32_bf16 v[40:43], v[162:165], v[198:201], v[40:43]
	v_mfma_f32_16x16x32_bf16 v[28:31], v[144:147], v[206:209], v[28:31]
	v_mfma_f32_16x16x32_bf16 v[24:27], v[162:165], v[206:209], v[24:27]
	v_mfma_f32_16x16x32_bf16 v[12:15], v[144:147], v[214:217], v[12:15]
	v_mfma_f32_16x16x32_bf16 v[8:11], v[162:165], v[214:217], v[8:11]
	v_mfma_f32_16x16x32_bf16 v[60:63], v[158:161], v[190:193], v[60:63]
	v_mfma_f32_16x16x32_bf16 v[56:59], v[166:169], v[190:193], v[56:59]
	v_mfma_f32_16x16x32_bf16 v[44:47], v[158:161], v[202:205], v[44:47]
	v_mfma_f32_16x16x32_bf16 v[40:43], v[166:169], v[202:205], v[40:43]
	v_mfma_f32_16x16x32_bf16 v[28:31], v[158:161], v[210:213], v[28:31]
	v_mfma_f32_16x16x32_bf16 v[24:27], v[166:169], v[210:213], v[24:27]
	v_mfma_f32_16x16x32_bf16 v[12:15], v[158:161], v[218:221], v[12:15]
	v_mfma_f32_16x16x32_bf16 v[8:11], v[166:169], v[218:221], v[8:11]
	s_setprio 0
	s_setprio 1
	v_mfma_f32_16x16x32_bf16 v[52:55], v[170:173], v[186:189], v[52:55]
	v_mfma_f32_16x16x32_bf16 v[48:51], v[178:181], v[186:189], v[48:51]
	v_mfma_f32_16x16x32_bf16 v[36:39], v[170:173], v[198:201], v[36:39]
	v_mfma_f32_16x16x32_bf16 v[32:35], v[178:181], v[198:201], v[32:35]
	v_mfma_f32_16x16x32_bf16 v[20:23], v[170:173], v[206:209], v[20:23]
	v_mfma_f32_16x16x32_bf16 v[16:19], v[178:181], v[206:209], v[16:19]
	v_mfma_f32_16x16x32_bf16 v[4:7], v[170:173], v[214:217], v[4:7]
	v_mfma_f32_16x16x32_bf16 v[0:3], v[178:181], v[214:217], v[0:3]
	v_mfma_f32_16x16x32_bf16 v[52:55], v[174:177], v[190:193], v[52:55]
	v_mfma_f32_16x16x32_bf16 v[48:51], v[182:185], v[190:193], v[48:51]
	v_mfma_f32_16x16x32_bf16 v[36:39], v[174:177], v[202:205], v[36:39]
	v_mfma_f32_16x16x32_bf16 v[32:35], v[182:185], v[202:205], v[32:35]
	v_mfma_f32_16x16x32_bf16 v[20:23], v[174:177], v[210:213], v[20:23]
	v_mfma_f32_16x16x32_bf16 v[16:19], v[182:185], v[210:213], v[16:19]
	v_mfma_f32_16x16x32_bf16 v[4:7], v[174:177], v[218:221], v[4:7]
	v_mfma_f32_16x16x32_bf16 v[0:3], v[182:185], v[218:221], v[0:3]
	s_setprio 0
	s_barrier
	s_add_i32 s69, s69, 2
	s_add_u32 s52, s52, 0x100
	s_addc_u32 s53, s53, 0
	s_add_u32 s67, s67, 0x100
	s_addc_u32 s68, s68, 0
	s_cmp_gt_u32 s69, 13
	s_cbranch_scc0 .LBB0_1077
	s_and_b64 vcc, exec, s[18:19]
	s_cbranch_vccz .LBB0_1080
	s_barrier

.LBB0_1166:
	ds_read_b128 v[0:3], v141
	ds_read_b128 v[4:7], v141 offset:1024
	ds_read_b128 v[8:11], v141 offset:2048
	ds_read_b128 v[12:15], v141 offset:3072
	ds_read_b128 v[16:19], v142
	ds_read_b128 v[20:23], v142 offset:1024
	ds_read_b128 v[24:27], v142 offset:2048
	ds_read_b128 v[28:31], v142 offset:3072
	s_add_u32 s46, s58, 0x40080
	s_addc_u32 s47, s59, 0
	s_add_i32 s71, s5, 0xc000
	v_lshl_add_u64 v[64:65], s[46:47], 0, v[134:135]
	s_mov_b32 m0, s71
	s_add_i32 s27, s5, 0xe000
	ds_read_b128 v[32:35], v143
	ds_read_b128 v[36:39], v143 offset:1024
	ds_read_b128 v[40:43], v143 offset:2048
	ds_read_b128 v[44:47], v143 offset:3072
	ds_read_b128 v[48:51], v143 offset:4096
	ds_read_b128 v[52:55], v143 offset:5120
	ds_read_b128 v[56:59], v143 offset:6144
	ds_read_b128 v[60:63], v143 offset:7168
	global_load_lds_dwordx4 v[64:65], off
	v_lshl_add_u64 v[64:65], s[46:47], 0, v[130:131]
	s_mov_b32 m0, s27
	s_nop 0
	global_load_lds_dwordx4 v[64:65], off
	s_waitcnt vmcnt(8)
	s_waitcnt lgkmcnt(0)
	s_barrier
	s_setprio 1
	s_waitcnt lgkmcnt(0)
	v_mfma_f32_16x16x32_bf16 v[64:67], v[0:3], v[32:35], 0
	v_mfma_f32_16x16x32_bf16 v[68:71], v[8:11], v[32:35], 0
	v_mfma_f32_16x16x32_bf16 v[72:75], v[0:3], v[40:43], 0
	v_mfma_f32_16x16x32_bf16 v[76:79], v[8:11], v[40:43], 0
	v_mfma_f32_16x16x32_bf16 v[80:83], v[0:3], v[48:51], 0
	v_mfma_f32_16x16x32_bf16 v[84:87], v[8:11], v[48:51], 0
	v_mfma_f32_16x16x32_bf16 v[88:91], v[0:3], v[56:59], 0
	v_mfma_f32_16x16x32_bf16 v[92:95], v[8:11], v[56:59], 0
	v_mfma_f32_16x16x32_bf16 v[64:67], v[4:7], v[36:39], v[64:67]
	v_mfma_f32_16x16x32_bf16 v[68:71], v[12:15], v[36:39], v[68:71]
	v_mfma_f32_16x16x32_bf16 v[72:75], v[4:7], v[44:47], v[72:75]
	v_mfma_f32_16x16x32_bf16 v[76:79], v[12:15], v[44:47], v[76:79]
	v_mfma_f32_16x16x32_bf16 v[80:83], v[4:7], v[52:55], v[80:83]
	v_mfma_f32_16x16x32_bf16 v[84:87], v[12:15], v[52:55], v[84:87]
	v_mfma_f32_16x16x32_bf16 v[88:91], v[4:7], v[60:63], v[88:91]
	v_mfma_f32_16x16x32_bf16 v[92:95], v[12:15], v[60:63], v[92:95]
	s_setprio 0
	s_setprio 1
	v_mfma_f32_16x16x32_bf16 v[96:99], v[16:19], v[32:35], 0
	v_mfma_f32_16x16x32_bf16 v[32:35], v[24:27], v[32:35], 0
	v_mfma_f32_16x16x32_bf16 v[96:99], v[20:23], v[36:39], v[96:99]
	v_mfma_f32_16x16x32_bf16 v[32:35], v[28:31], v[36:39], v[32:35]
	v_mfma_f32_16x16x32_bf16 v[36:39], v[16:19], v[40:43], 0
	v_mfma_f32_16x16x32_bf16 v[40:43], v[24:27], v[40:43], 0
	v_mfma_f32_16x16x32_bf16 v[36:39], v[20:23], v[44:47], v[36:39]
	v_mfma_f32_16x16x32_bf16 v[40:43], v[28:31], v[44:47], v[40:43]
	v_mfma_f32_16x16x32_bf16 v[44:47], v[16:19], v[48:51], 0
	v_mfma_f32_16x16x32_bf16 v[48:51], v[24:27], v[48:51], 0
	v_mfma_f32_16x16x32_bf16 v[44:47], v[20:23], v[52:55], v[44:47]
	v_mfma_f32_16x16x32_bf16 v[48:51], v[28:31], v[52:55], v[48:51]
	v_mfma_f32_16x16x32_bf16 v[52:55], v[16:19], v[56:59], 0
	v_mfma_f32_16x16x32_bf16 v[56:59], v[24:27], v[56:59], 0
	v_mfma_f32_16x16x32_bf16 v[52:55], v[20:23], v[60:63], v[52:55]
	v_mfma_f32_16x16x32_bf16 v[56:59], v[28:31], v[60:63], v[56:59]
	s_setprio 0
	s_barrier
	s_add_i32 s47, s64, s4
	v_lshl_add_u64 v[136:137], s[60:61], 0, v[132:133]
	s_add_i32 s29, s47, 0x2000
	v_lshl_add_u64 v[144:145], v[136:137], 0, s[16:17]
	s_mov_b32 m0, s47
	v_lshl_add_u64 v[196:197], s[60:61], 0, v[128:129]
	s_add_u32 s72, s60, 0x40100
	ds_read_b128 v[60:63], v143 offset:16384
	ds_read_b128 v[100:103], v143 offset:17408
	ds_read_b128 v[104:107], v143 offset:18432
	ds_read_b128 v[108:111], v143 offset:19456
	ds_read_b128 v[112:115], v143 offset:20480
	ds_read_b128 v[116:119], v143 offset:21504
	ds_read_b128 v[120:123], v143 offset:22528
	ds_read_b128 v[124:127], v143 offset:23552
	global_load_lds_dwordx4 v[144:145], off
	v_lshl_add_u64 v[144:145], v[196:197], 0, s[16:17]
	s_mov_b32 m0, s29
	s_addc_u32 s73, s61, 0
	s_add_i32 s31, s65, s4
	global_load_lds_dwordx4 v[144:145], off
	v_lshl_add_u64 v[144:145], s[72:73], 0, v[132:133]
	s_mov_b32 m0, s31
	s_add_i32 s46, s31, 0x2000
	global_load_lds_dwordx4 v[144:145], off
	v_lshl_add_u64 v[144:145], s[72:73], 0, v[128:129]
	s_mov_b32 m0, s46
	v_lshl_add_u64 v[210:211], s[58:59], 0, v[134:135]
	global_load_lds_dwordx4 v[144:145], off
	v_lshl_add_u64 v[144:145], v[210:211], 0, s[16:17]
	s_mov_b32 m0, s5
	v_lshl_add_u64 v[212:213], s[58:59], 0, v[130:131]
	global_load_lds_dwordx4 v[144:145], off
	v_lshl_add_u64 v[144:145], v[212:213], 0, s[16:17]
	s_mov_b32 m0, s35
	s_nop 0
	global_load_lds_dwordx4 v[144:145], off
	s_nop 0
	s_waitcnt vmcnt(8)
	s_waitcnt lgkmcnt(0)
	s_barrier
	s_setprio 1
	s_waitcnt lgkmcnt(0)
	v_mfma_f32_16x16x32_bf16 v[144:147], v[0:3], v[60:63], 0
	v_mfma_f32_16x16x32_bf16 v[152:155], v[0:3], v[104:107], 0
	v_mfma_f32_16x16x32_bf16 v[160:163], v[0:3], v[112:115], 0
	v_mfma_f32_16x16x32_bf16 v[0:3], v[0:3], v[120:123], 0
	v_mfma_f32_16x16x32_bf16 v[144:147], v[4:7], v[100:103], v[144:147]
	v_mfma_f32_16x16x32_bf16 v[152:155], v[4:7], v[108:111], v[152:155]
	v_mfma_f32_16x16x32_bf16 v[160:163], v[4:7], v[116:119], v[160:163]
	v_mfma_f32_16x16x32_bf16 v[0:3], v[4:7], v[124:127], v[0:3]
	v_mfma_f32_16x16x32_bf16 v[4:7], v[8:11], v[120:123], 0
	v_mfma_f32_16x16x32_bf16 v[148:151], v[8:11], v[60:63], 0
	v_mfma_f32_16x16x32_bf16 v[156:159], v[8:11], v[104:107], 0
	v_mfma_f32_16x16x32_bf16 v[164:167], v[8:11], v[112:115], 0
	v_mfma_f32_16x16x32_bf16 v[4:7], v[12:15], v[124:127], v[4:7]
	v_mfma_f32_16x16x32_bf16 v[148:151], v[12:15], v[100:103], v[148:151]
	v_mfma_f32_16x16x32_bf16 v[156:159], v[12:15], v[108:111], v[156:159]
	v_mfma_f32_16x16x32_bf16 v[164:167], v[12:15], v[116:119], v[164:167]
	s_setprio 0
	s_setprio 1
	v_mfma_f32_16x16x32_bf16 v[8:11], v[16:19], v[60:63], 0
	v_mfma_f32_16x16x32_bf16 v[12:15], v[24:27], v[60:63], 0
	v_mfma_f32_16x16x32_bf16 v[8:11], v[20:23], v[100:103], v[8:11]
	v_mfma_f32_16x16x32_bf16 v[12:15], v[28:31], v[100:103], v[12:15]
	v_mfma_f32_16x16x32_bf16 v[60:63], v[16:19], v[104:107], 0
	v_mfma_f32_16x16x32_bf16 v[100:103], v[24:27], v[104:107], 0
	v_mfma_f32_16x16x32_bf16 v[104:107], v[16:19], v[112:115], 0
	v_mfma_f32_16x16x32_bf16 v[16:19], v[16:19], v[120:123], 0
	v_mfma_f32_16x16x32_bf16 v[60:63], v[20:23], v[108:111], v[60:63]
	v_mfma_f32_16x16x32_bf16 v[100:103], v[28:31], v[108:111], v[100:103]
	v_mfma_f32_16x16x32_bf16 v[104:107], v[20:23], v[116:119], v[104:107]
	v_mfma_f32_16x16x32_bf16 v[108:111], v[24:27], v[112:115], 0
	v_mfma_f32_16x16x32_bf16 v[16:19], v[20:23], v[124:127], v[16:19]
	v_mfma_f32_16x16x32_bf16 v[20:23], v[24:27], v[120:123], 0
	v_mfma_f32_16x16x32_bf16 v[108:111], v[28:31], v[116:119], v[108:111]
	v_mfma_f32_16x16x32_bf16 v[20:23], v[28:31], v[124:127], v[20:23]
	s_setprio 0
	s_barrier
	s_add_i32 s70, 0, 0x18000
	s_add_i32 s76, 0, 0x1c000
	v_add_u32_e32 v222, s70, v138
	v_add_u32_e32 v230, s76, v138
	ds_read_b128 v[24:27], v222
	ds_read_b128 v[28:31], v222 offset:1024
	ds_read_b128 v[112:115], v222 offset:2048
	ds_read_b128 v[116:119], v222 offset:3072
	ds_read_b128 v[120:123], v230
	ds_read_b128 v[124:127], v230 offset:1024
	ds_read_b128 v[168:171], v230 offset:2048
	ds_read_b128 v[172:175], v230 offset:3072
	s_add_u32 s72, s58, 0x40100
	s_addc_u32 s73, s59, 0
	s_mov_b32 m0, s48
	v_lshl_add_u64 v[214:215], s[72:73], 0, v[134:135]
	ds_read_b128 v[176:179], v143 offset:32768
	ds_read_b128 v[180:183], v143 offset:33792
	ds_read_b128 v[184:187], v143 offset:34816
	ds_read_b128 v[188:191], v143 offset:35840
	ds_read_b128 v[192:195], v143 offset:36864
	ds_read_b128 v[198:201], v143 offset:37888
	ds_read_b128 v[202:205], v143 offset:38912
	ds_read_b128 v[206:209], v143 offset:39936
	global_load_lds_dwordx4 v[214:215], off
	v_lshl_add_u64 v[214:215], s[72:73], 0, v[130:131]
	s_mov_b32 m0, s49
	s_nop 0
	global_load_lds_dwordx4 v[214:215], off
	s_nop 0
	s_waitcnt vmcnt(8)
	s_waitcnt lgkmcnt(0)
	s_barrier
	s_setprio 1
	s_waitcnt lgkmcnt(0)
	v_mfma_f32_16x16x32_bf16 v[64:67], v[24:27], v[176:179], v[64:67]
	v_mfma_f32_16x16x32_bf16 v[68:71], v[112:115], v[176:179], v[68:71]
	v_mfma_f32_16x16x32_bf16 v[72:75], v[24:27], v[184:187], v[72:75]
	v_mfma_f32_16x16x32_bf16 v[76:79], v[112:115], v[184:187], v[76:79]
	v_mfma_f32_16x16x32_bf16 v[80:83], v[24:27], v[192:195], v[80:83]
	v_mfma_f32_16x16x32_bf16 v[84:87], v[112:115], v[192:195], v[84:87]
	v_mfma_f32_16x16x32_bf16 v[88:91], v[24:27], v[202:205], v[88:91]
	v_mfma_f32_16x16x32_bf16 v[92:95], v[112:115], v[202:205], v[92:95]
	v_mfma_f32_16x16x32_bf16 v[64:67], v[28:31], v[180:183], v[64:67]
	v_mfma_f32_16x16x32_bf16 v[68:71], v[116:119], v[180:183], v[68:71]
	v_mfma_f32_16x16x32_bf16 v[72:75], v[28:31], v[188:191], v[72:75]
	v_mfma_f32_16x16x32_bf16 v[76:79], v[116:119], v[188:191], v[76:79]
	v_mfma_f32_16x16x32_bf16 v[80:83], v[28:31], v[198:201], v[80:83]
	v_mfma_f32_16x16x32_bf16 v[84:87], v[116:119], v[198:201], v[84:87]
	v_mfma_f32_16x16x32_bf16 v[88:91], v[28:31], v[206:209], v[88:91]
	v_mfma_f32_16x16x32_bf16 v[92:95], v[116:119], v[206:209], v[92:95]
	s_setprio 0
	s_setprio 1
	v_mfma_f32_16x16x32_bf16 v[96:99], v[120:123], v[176:179], v[96:99]
	v_mfma_f32_16x16x32_bf16 v[32:35], v[168:171], v[176:179], v[32:35]
	v_mfma_f32_16x16x32_bf16 v[36:39], v[120:123], v[184:187], v[36:39]
	v_mfma_f32_16x16x32_bf16 v[40:43], v[168:171], v[184:187], v[40:43]
	v_mfma_f32_16x16x32_bf16 v[44:47], v[120:123], v[192:195], v[44:47]
	v_mfma_f32_16x16x32_bf16 v[48:51], v[168:171], v[192:195], v[48:51]
	v_mfma_f32_16x16x32_bf16 v[52:55], v[120:123], v[202:205], v[52:55]
	v_mfma_f32_16x16x32_bf16 v[56:59], v[168:171], v[202:205], v[56:59]
	v_mfma_f32_16x16x32_bf16 v[96:99], v[124:127], v[180:183], v[96:99]
	v_mfma_f32_16x16x32_bf16 v[32:35], v[172:175], v[180:183], v[32:35]
	v_mfma_f32_16x16x32_bf16 v[36:39], v[124:127], v[188:191], v[36:39]
	v_mfma_f32_16x16x32_bf16 v[40:43], v[172:175], v[188:191], v[40:43]
	v_mfma_f32_16x16x32_bf16 v[44:47], v[124:127], v[198:201], v[44:47]
	v_mfma_f32_16x16x32_bf16 v[48:51], v[172:175], v[198:201], v[48:51]
	v_mfma_f32_16x16x32_bf16 v[52:55], v[124:127], v[206:209], v[52:55]
	v_mfma_f32_16x16x32_bf16 v[56:59], v[172:175], v[206:209], v[56:59]
	s_setprio 0
	s_barrier
	s_add_i32 s72, s70, s4
	s_add_i32 s70, s72, 0x2000
	v_lshl_add_u64 v[136:137], v[136:137], 0, s[18:19]
	s_mov_b32 m0, s72
	s_add_u32 s74, s60, 0x40180
	ds_read_b128 v[176:179], v143 offset:49152
	ds_read_b128 v[180:183], v143 offset:50176
	ds_read_b128 v[184:187], v143 offset:51200
	ds_read_b128 v[188:191], v143 offset:52224
	ds_read_b128 v[192:195], v143 offset:53248
	ds_read_b128 v[198:201], v143 offset:54272
	ds_read_b128 v[202:205], v143 offset:55296
	ds_read_b128 v[206:209], v143 offset:56320
	global_load_lds_dwordx4 v[136:137], off
	v_lshl_add_u64 v[136:137], v[196:197], 0, s[18:19]
	s_mov_b32 m0, s70
	s_addc_u32 s75, s61, 0
	s_add_i32 s60, s76, s4
	global_load_lds_dwordx4 v[136:137], off
	v_lshl_add_u64 v[136:137], s[74:75], 0, v[132:133]
	s_mov_b32 m0, s60
	s_add_i32 s61, s60, 0x2000
	global_load_lds_dwordx4 v[136:137], off
	v_lshl_add_u64 v[136:137], s[74:75], 0, v[128:129]
	s_mov_b32 m0, s61
	s_nop 0
	global_load_lds_dwordx4 v[136:137], off
	v_lshl_add_u64 v[136:137], v[210:211], 0, s[18:19]
	s_mov_b32 m0, s53
	s_nop 0
	global_load_lds_dwordx4 v[136:137], off
	v_lshl_add_u64 v[136:137], v[212:213], 0, s[18:19]
	s_mov_b32 m0, s55
	s_nop 0
	global_load_lds_dwordx4 v[136:137], off
	s_nop 0
	s_waitcnt vmcnt(8)
	s_waitcnt lgkmcnt(0)
	s_barrier
	s_setprio 1
	s_waitcnt lgkmcnt(0)
	v_mfma_f32_16x16x32_bf16 v[0:3], v[24:27], v[202:205], v[0:3]
	v_mfma_f32_16x16x32_bf16 v[4:7], v[112:115], v[202:205], v[4:7]
	v_mfma_f32_16x16x32_bf16 v[144:147], v[24:27], v[176:179], v[144:147]
	v_mfma_f32_16x16x32_bf16 v[148:151], v[112:115], v[176:179], v[148:151]
	v_mfma_f32_16x16x32_bf16 v[152:155], v[24:27], v[184:187], v[152:155]
	v_mfma_f32_16x16x32_bf16 v[156:159], v[112:115], v[184:187], v[156:159]
	v_mfma_f32_16x16x32_bf16 v[160:163], v[24:27], v[192:195], v[160:163]
	v_mfma_f32_16x16x32_bf16 v[164:167], v[112:115], v[192:195], v[164:167]
	v_mfma_f32_16x16x32_bf16 v[0:3], v[28:31], v[206:209], v[0:3]
	v_mfma_f32_16x16x32_bf16 v[4:7], v[116:119], v[206:209], v[4:7]
	v_mfma_f32_16x16x32_bf16 v[144:147], v[28:31], v[180:183], v[144:147]
	v_mfma_f32_16x16x32_bf16 v[148:151], v[116:119], v[180:183], v[148:151]
	v_mfma_f32_16x16x32_bf16 v[152:155], v[28:31], v[188:191], v[152:155]
	v_mfma_f32_16x16x32_bf16 v[156:159], v[116:119], v[188:191], v[156:159]
	v_mfma_f32_16x16x32_bf16 v[160:163], v[28:31], v[198:201], v[160:163]
	v_mfma_f32_16x16x32_bf16 v[164:167], v[116:119], v[198:201], v[164:167]
	s_setprio 0
	s_setprio 1
	v_mfma_f32_16x16x32_bf16 v[8:11], v[120:123], v[176:179], v[8:11]
	v_mfma_f32_16x16x32_bf16 v[12:15], v[168:171], v[176:179], v[12:15]
	v_mfma_f32_16x16x32_bf16 v[24:27], v[120:123], v[184:187], v[60:63]
	v_mfma_f32_16x16x32_bf16 v[28:31], v[168:171], v[184:187], v[100:103]
	v_mfma_f32_16x16x32_bf16 v[60:63], v[120:123], v[192:195], v[104:107]
	v_mfma_f32_16x16x32_bf16 v[100:103], v[168:171], v[192:195], v[108:111]
	v_mfma_f32_16x16x32_bf16 v[16:19], v[120:123], v[202:205], v[16:19]
	v_mfma_f32_16x16x32_bf16 v[20:23], v[168:171], v[202:205], v[20:23]
	v_mfma_f32_16x16x32_bf16 v[8:11], v[124:127], v[180:183], v[8:11]
	v_mfma_f32_16x16x32_bf16 v[12:15], v[172:175], v[180:183], v[12:15]
	v_mfma_f32_16x16x32_bf16 v[24:27], v[124:127], v[188:191], v[24:27]
	v_mfma_f32_16x16x32_bf16 v[28:31], v[172:175], v[188:191], v[28:31]
	v_mfma_f32_16x16x32_bf16 v[60:63], v[124:127], v[198:201], v[60:63]
	v_mfma_f32_16x16x32_bf16 v[100:103], v[172:175], v[198:201], v[100:103]
	v_mfma_f32_16x16x32_bf16 v[16:19], v[124:127], v[206:209], v[16:19]
	v_mfma_f32_16x16x32_bf16 v[20:23], v[172:175], v[206:209], v[20:23]
	s_setprio 0
	s_barrier
	ds_read_b128 v[104:107], v141
	ds_read_b128 v[108:111], v141 offset:1024
	ds_read_b128 v[112:115], v141 offset:2048
	ds_read_b128 v[116:119], v141 offset:3072
	ds_read_b128 v[120:123], v142
	ds_read_b128 v[124:127], v142 offset:1024
	ds_read_b128 v[168:171], v142 offset:2048
	ds_read_b128 v[172:175], v142 offset:3072
	s_add_u32 s58, s58, 0x40180
	s_addc_u32 s59, s59, 0
	s_mov_b32 m0, s71
	v_lshl_add_u64 v[136:137], s[58:59], 0, v[134:135]
	ds_read_b128 v[176:179], v143
	ds_read_b128 v[180:183], v143 offset:1024
	ds_read_b128 v[184:187], v143 offset:2048
	ds_read_b128 v[188:191], v143 offset:3072
	ds_read_b128 v[192:195], v143 offset:4096
	ds_read_b128 v[198:201], v143 offset:5120
	ds_read_b128 v[202:205], v143 offset:6144
	ds_read_b128 v[206:209], v143 offset:7168
	global_load_lds_dwordx4 v[136:137], off
	v_lshl_add_u64 v[136:137], s[58:59], 0, v[130:131]
	s_mov_b32 m0, s27
	s_nop 0
	global_load_lds_dwordx4 v[136:137], off
	s_nop 0
	s_waitcnt vmcnt(8)
	s_waitcnt lgkmcnt(0)
	s_barrier
	s_setprio 1
	s_waitcnt lgkmcnt(0)
	v_mfma_f32_16x16x32_bf16 v[88:91], v[104:107], v[202:205], v[88:91]
	v_mfma_f32_16x16x32_bf16 v[64:67], v[104:107], v[176:179], v[64:67]
	v_mfma_f32_16x16x32_bf16 v[68:71], v[112:115], v[176:179], v[68:71]
	v_mfma_f32_16x16x32_bf16 v[72:75], v[104:107], v[184:187], v[72:75]
	v_mfma_f32_16x16x32_bf16 v[76:79], v[112:115], v[184:187], v[76:79]
	v_mfma_f32_16x16x32_bf16 v[80:83], v[104:107], v[192:195], v[80:83]
	v_mfma_f32_16x16x32_bf16 v[84:87], v[112:115], v[192:195], v[84:87]
	v_mfma_f32_16x16x32_bf16 v[210:213], v[108:111], v[206:209], v[88:91]
	v_mfma_f32_16x16x32_bf16 v[88:91], v[112:115], v[202:205], v[92:95]
	v_mfma_f32_16x16x32_bf16 v[64:67], v[108:111], v[180:183], v[64:67]
	v_mfma_f32_16x16x32_bf16 v[68:71], v[116:119], v[180:183], v[68:71]
	v_mfma_f32_16x16x32_bf16 v[72:75], v[108:111], v[188:191], v[72:75]
	v_mfma_f32_16x16x32_bf16 v[76:79], v[116:119], v[188:191], v[76:79]
	v_mfma_f32_16x16x32_bf16 v[80:83], v[108:111], v[198:201], v[80:83]
	v_mfma_f32_16x16x32_bf16 v[84:87], v[116:119], v[198:201], v[84:87]
	v_mfma_f32_16x16x32_bf16 v[92:95], v[116:119], v[206:209], v[88:91]
	s_setprio 0
	s_setprio 1
	v_mfma_f32_16x16x32_bf16 v[48:51], v[168:171], v[192:195], v[48:51]
	v_mfma_f32_16x16x32_bf16 v[88:91], v[120:123], v[176:179], v[96:99]
	v_mfma_f32_16x16x32_bf16 v[32:35], v[168:171], v[176:179], v[32:35]
	v_mfma_f32_16x16x32_bf16 v[36:39], v[120:123], v[184:187], v[36:39]
	v_mfma_f32_16x16x32_bf16 v[40:43], v[168:171], v[184:187], v[40:43]
	v_mfma_f32_16x16x32_bf16 v[44:47], v[120:123], v[192:195], v[44:47]
	v_mfma_f32_16x16x32_bf16 v[176:179], v[172:175], v[198:201], v[48:51]
	v_mfma_f32_16x16x32_bf16 v[48:51], v[120:123], v[202:205], v[52:55]
	v_mfma_f32_16x16x32_bf16 v[32:35], v[172:175], v[180:183], v[32:35]
	v_mfma_f32_16x16x32_bf16 v[36:39], v[124:127], v[188:191], v[36:39]
	v_mfma_f32_16x16x32_bf16 v[40:43], v[172:175], v[188:191], v[40:43]
	v_mfma_f32_16x16x32_bf16 v[44:47], v[124:127], v[198:201], v[44:47]
	v_mfma_f32_16x16x32_bf16 v[52:55], v[124:127], v[206:209], v[48:51]
	v_mfma_f32_16x16x32_bf16 v[48:51], v[168:171], v[202:205], v[56:59]
	v_mfma_f32_16x16x32_bf16 v[214:217], v[124:127], v[180:183], v[88:91]
	v_mfma_f32_16x16x32_bf16 v[180:183], v[172:175], v[206:209], v[48:51]
	s_setprio 0
	s_barrier
	s_mov_b32 m0, s47
	v_lshl_add_u64 v[136:137], s[42:43], 0, v[132:133]
	s_add_u32 s58, s42, 0x40000
	s_nop 0
	ds_read_b128 v[48:51], v143 offset:16384
	ds_read_b128 v[56:59], v143 offset:17408
	ds_read_b128 v[88:91], v143 offset:18432
	ds_read_b128 v[96:99], v143 offset:19456
	ds_read_b128 v[184:187], v143 offset:20480
	ds_read_b128 v[188:191], v143 offset:21504
	ds_read_b128 v[192:195], v143 offset:22528
	ds_read_b128 v[198:201], v143 offset:23552
	global_load_lds_dwordx4 v[136:137], off
	v_lshl_add_u64 v[196:197], s[42:43], 0, v[128:129]
	s_mov_b32 m0, s29
	s_addc_u32 s59, s43, 0
	global_load_lds_dwordx4 v[196:197], off
	v_lshl_add_u64 v[202:203], s[58:59], 0, v[132:133]
	s_mov_b32 m0, s31
	v_lshl_add_u64 v[250:251], s[40:41], 0, v[134:135]
	global_load_lds_dwordx4 v[202:203], off
	v_lshl_add_u64 v[202:203], s[58:59], 0, v[128:129]
	s_mov_b32 m0, s46
	v_lshl_add_u64 v[252:253], s[40:41], 0, v[130:131]
	global_load_lds_dwordx4 v[202:203], off
	s_mov_b32 m0, s5
	s_nop 0
	global_load_lds_dwordx4 v[250:251], off
	s_mov_b32 m0, s35
	s_nop 0
	global_load_lds_dwordx4 v[252:253], off
	s_nop 0
	s_waitcnt vmcnt(8)
	s_waitcnt lgkmcnt(0)
	s_barrier
	s_setprio 1
	s_waitcnt lgkmcnt(0)
	v_mfma_f32_16x16x32_bf16 v[0:3], v[104:107], v[192:195], v[0:3]
	v_mfma_f32_16x16x32_bf16 v[4:7], v[112:115], v[192:195], v[4:7]
	v_mfma_f32_16x16x32_bf16 v[144:147], v[104:107], v[48:51], v[144:147]
	v_mfma_f32_16x16x32_bf16 v[148:151], v[112:115], v[48:51], v[148:151]
	v_mfma_f32_16x16x32_bf16 v[152:155], v[104:107], v[88:91], v[152:155]
	v_mfma_f32_16x16x32_bf16 v[156:159], v[112:115], v[88:91], v[156:159]
	v_mfma_f32_16x16x32_bf16 v[160:163], v[104:107], v[184:187], v[160:163]
	v_mfma_f32_16x16x32_bf16 v[164:167], v[112:115], v[184:187], v[164:167]
	v_mfma_f32_16x16x32_bf16 v[0:3], v[108:111], v[198:201], v[0:3]
	v_mfma_f32_16x16x32_bf16 v[4:7], v[116:119], v[198:201], v[4:7]
	v_mfma_f32_16x16x32_bf16 v[144:147], v[108:111], v[56:59], v[144:147]
	v_mfma_f32_16x16x32_bf16 v[148:151], v[116:119], v[56:59], v[148:151]
	v_mfma_f32_16x16x32_bf16 v[152:155], v[108:111], v[96:99], v[152:155]
	v_mfma_f32_16x16x32_bf16 v[156:159], v[116:119], v[96:99], v[156:159]
	v_mfma_f32_16x16x32_bf16 v[160:163], v[108:111], v[188:191], v[160:163]
	v_mfma_f32_16x16x32_bf16 v[164:167], v[116:119], v[188:191], v[164:167]
	s_setprio 0
	s_setprio 1
	v_mfma_f32_16x16x32_bf16 v[12:15], v[168:171], v[48:51], v[12:15]
	v_mfma_f32_16x16x32_bf16 v[202:205], v[172:175], v[56:59], v[12:15]
	v_mfma_f32_16x16x32_bf16 v[12:15], v[120:123], v[88:91], v[24:27]
	v_mfma_f32_16x16x32_bf16 v[24:27], v[124:127], v[96:99], v[12:15]
	v_mfma_f32_16x16x32_bf16 v[12:15], v[168:171], v[88:91], v[28:31]
	v_mfma_f32_16x16x32_bf16 v[206:209], v[172:175], v[96:99], v[12:15]
	v_mfma_f32_16x16x32_bf16 v[12:15], v[120:123], v[184:187], v[60:63]
	v_mfma_f32_16x16x32_bf16 v[218:221], v[124:127], v[188:191], v[12:15]
	v_mfma_f32_16x16x32_bf16 v[12:15], v[168:171], v[184:187], v[100:103]
	v_mfma_f32_16x16x32_bf16 v[8:11], v[120:123], v[48:51], v[8:11]
	v_mfma_f32_16x16x32_bf16 v[184:187], v[172:175], v[188:191], v[12:15]
	v_mfma_f32_16x16x32_bf16 v[12:15], v[120:123], v[192:195], v[16:19]
	v_mfma_f32_16x16x32_bf16 v[8:11], v[124:127], v[56:59], v[8:11]
	v_mfma_f32_16x16x32_bf16 v[188:191], v[124:127], v[198:201], v[12:15]
	v_mfma_f32_16x16x32_bf16 v[12:15], v[168:171], v[192:195], v[20:23]
	v_mfma_f32_16x16x32_bf16 v[168:171], v[172:175], v[198:201], v[12:15]
	s_setprio 0
	s_barrier
	s_nop 4
	ds_read_b128 v[12:15], v222
	ds_read_b128 v[16:19], v222 offset:1024
	ds_read_b128 v[172:175], v222 offset:2048
	ds_read_b128 v[192:195], v222 offset:3072
	ds_read_b128 v[198:201], v230
	ds_read_b128 v[222:225], v230 offset:1024
	ds_read_b128 v[226:229], v230 offset:2048
	ds_read_b128 v[230:233], v230 offset:3072
	s_add_u32 s46, s40, 0x40000
	s_addc_u32 s47, s41, 0
	s_mov_b32 m0, s48
	v_lshl_add_u64 v[48:49], s[46:47], 0, v[134:135]
	ds_read_b128 v[20:23], v143 offset:32768
	ds_read_b128 v[28:31], v143 offset:33792
	ds_read_b128 v[60:63], v143 offset:34816
	ds_read_b128 v[100:103], v143 offset:35840
	ds_read_b128 v[234:237], v143 offset:36864
	ds_read_b128 v[238:241], v143 offset:37888
	ds_read_b128 v[242:245], v143 offset:38912
	ds_read_b128 v[246:249], v143 offset:39936
	global_load_lds_dwordx4 v[48:49], off
	v_lshl_add_u64 v[48:49], s[46:47], 0, v[130:131]
	s_mov_b32 m0, s49
	s_nop 0
	global_load_lds_dwordx4 v[48:49], off
	s_waitcnt vmcnt(8)
	s_waitcnt lgkmcnt(0)
	s_barrier
	s_setprio 1
	s_waitcnt lgkmcnt(0)
	v_mfma_f32_16x16x32_bf16 v[48:51], v[12:15], v[20:23], v[64:67]
	v_mfma_f32_16x16x32_bf16 v[120:123], v[16:19], v[28:31], v[48:51]
	v_mfma_f32_16x16x32_bf16 v[48:51], v[172:175], v[20:23], v[68:71]
	v_mfma_f32_16x16x32_bf16 v[112:115], v[192:195], v[28:31], v[48:51]
	v_mfma_f32_16x16x32_bf16 v[48:51], v[12:15], v[60:63], v[72:75]
	v_mfma_f32_16x16x32_bf16 v[104:107], v[16:19], v[100:103], v[48:51]
	v_mfma_f32_16x16x32_bf16 v[48:51], v[172:175], v[60:63], v[76:79]
	v_mfma_f32_16x16x32_bf16 v[96:99], v[192:195], v[100:103], v[48:51]
	v_mfma_f32_16x16x32_bf16 v[48:51], v[12:15], v[234:237], v[80:83]
	v_mfma_f32_16x16x32_bf16 v[88:91], v[16:19], v[238:241], v[48:51]
	v_mfma_f32_16x16x32_bf16 v[48:51], v[172:175], v[234:237], v[84:87]
	v_mfma_f32_16x16x32_bf16 v[80:83], v[192:195], v[238:241], v[48:51]
	v_mfma_f32_16x16x32_bf16 v[48:51], v[12:15], v[242:245], v[210:213]
	v_mfma_f32_16x16x32_bf16 v[56:59], v[16:19], v[246:249], v[48:51]
	v_mfma_f32_16x16x32_bf16 v[48:51], v[172:175], v[242:245], v[92:95]
	v_mfma_f32_16x16x32_bf16 v[48:51], v[192:195], v[246:249], v[48:51]
	s_setprio 0
	s_setprio 1
	v_mfma_f32_16x16x32_bf16 v[64:67], v[198:201], v[20:23], v[214:217]
	v_mfma_f32_16x16x32_bf16 v[20:23], v[226:229], v[20:23], v[32:35]
	v_mfma_f32_16x16x32_bf16 v[116:119], v[230:233], v[28:31], v[20:23]
	v_mfma_f32_16x16x32_bf16 v[20:23], v[198:201], v[60:63], v[36:39]
	v_mfma_f32_16x16x32_bf16 v[108:111], v[222:225], v[100:103], v[20:23]
	v_mfma_f32_16x16x32_bf16 v[20:23], v[226:229], v[60:63], v[40:43]
	v_mfma_f32_16x16x32_bf16 v[100:103], v[230:233], v[100:103], v[20:23]
	v_mfma_f32_16x16x32_bf16 v[20:23], v[198:201], v[234:237], v[44:47]
	v_mfma_f32_16x16x32_bf16 v[92:95], v[222:225], v[238:241], v[20:23]
	v_mfma_f32_16x16x32_bf16 v[20:23], v[226:229], v[234:237], v[176:179]
	v_mfma_f32_16x16x32_bf16 v[84:87], v[230:233], v[238:241], v[20:23]
	v_mfma_f32_16x16x32_bf16 v[20:23], v[198:201], v[242:245], v[52:55]
	v_mfma_f32_16x16x32_bf16 v[60:63], v[222:225], v[246:249], v[20:23]
	v_mfma_f32_16x16x32_bf16 v[20:23], v[226:229], v[242:245], v[180:183]
	v_mfma_f32_16x16x32_bf16 v[124:127], v[222:225], v[28:31], v[64:67]
	v_mfma_f32_16x16x32_bf16 v[52:55], v[230:233], v[246:249], v[20:23]
	s_setprio 0
	s_barrier
	s_mov_b32 m0, s72
	s_nop 2
	v_lshl_add_u64 v[20:21], v[136:137], 0, s[12:13]
	s_add_u32 s46, s42, 0x40080
	ds_read_b128 v[32:35], v143 offset:49152
	ds_read_b128 v[40:43], v143 offset:50176
	ds_read_b128 v[176:179], v143 offset:51200
	ds_read_b128 v[180:183], v143 offset:52224
	ds_read_b128 v[210:213], v143 offset:53248
	ds_read_b128 v[214:217], v143 offset:54272
	ds_read_b128 v[234:237], v143 offset:55296
	ds_read_b128 v[238:241], v143 offset:56320
	global_load_lds_dwordx4 v[20:21], off
	v_lshl_add_u64 v[20:21], v[196:197], 0, s[12:13]
	s_mov_b32 m0, s70
	s_addc_u32 s47, s43, 0
	global_load_lds_dwordx4 v[20:21], off
	v_lshl_add_u64 v[20:21], s[46:47], 0, v[132:133]
	s_mov_b32 m0, s60
	s_nop 0
	global_load_lds_dwordx4 v[20:21], off
	v_lshl_add_u64 v[20:21], s[46:47], 0, v[128:129]
	s_mov_b32 m0, s61
	s_nop 0
	global_load_lds_dwordx4 v[20:21], off
	v_lshl_add_u64 v[20:21], v[250:251], 0, s[12:13]
	s_mov_b32 m0, s53
	s_nop 0
	global_load_lds_dwordx4 v[20:21], off
	v_lshl_add_u64 v[20:21], v[252:253], 0, s[12:13]
	s_mov_b32 m0, s55
	s_nop 0
	global_load_lds_dwordx4 v[20:21], off
	s_nop 0
	s_waitcnt vmcnt(8)
	s_waitcnt lgkmcnt(0)
	s_barrier
	s_setprio 1
	s_waitcnt lgkmcnt(0)
	v_mfma_f32_16x16x32_bf16 v[20:23], v[12:15], v[32:35], v[144:147]
	v_mfma_f32_16x16x32_bf16 v[76:79], v[16:19], v[40:43], v[20:23]
	v_mfma_f32_16x16x32_bf16 v[20:23], v[172:175], v[32:35], v[148:151]
	v_mfma_f32_16x16x32_bf16 v[68:71], v[192:195], v[40:43], v[20:23]
	v_mfma_f32_16x16x32_bf16 v[20:23], v[12:15], v[176:179], v[152:155]
	v_mfma_f32_16x16x32_bf16 v[44:47], v[16:19], v[180:183], v[20:23]
	v_mfma_f32_16x16x32_bf16 v[20:23], v[172:175], v[176:179], v[156:159]
	v_mfma_f32_16x16x32_bf16 v[36:39], v[192:195], v[180:183], v[20:23]
	v_mfma_f32_16x16x32_bf16 v[20:23], v[12:15], v[210:213], v[160:163]
	v_mfma_f32_16x16x32_bf16 v[0:3], v[12:15], v[234:237], v[0:3]
	v_mfma_f32_16x16x32_bf16 v[28:31], v[16:19], v[214:217], v[20:23]
	v_mfma_f32_16x16x32_bf16 v[20:23], v[172:175], v[210:213], v[164:167]
	v_mfma_f32_16x16x32_bf16 v[12:15], v[16:19], v[238:241], v[0:3]
	v_mfma_f32_16x16x32_bf16 v[0:3], v[172:175], v[234:237], v[4:7]
	v_mfma_f32_16x16x32_bf16 v[20:23], v[192:195], v[214:217], v[20:23]
	v_mfma_f32_16x16x32_bf16 v[4:7], v[192:195], v[238:241], v[0:3]
	s_setprio 0
	s_setprio 1
	v_mfma_f32_16x16x32_bf16 v[0:3], v[198:201], v[32:35], v[8:11]
	v_mfma_f32_16x16x32_bf16 v[72:75], v[222:225], v[40:43], v[0:3]
	v_mfma_f32_16x16x32_bf16 v[0:3], v[226:229], v[32:35], v[202:205]
	v_mfma_f32_16x16x32_bf16 v[64:67], v[230:233], v[40:43], v[0:3]
	v_mfma_f32_16x16x32_bf16 v[0:3], v[198:201], v[176:179], v[24:27]
	v_mfma_f32_16x16x32_bf16 v[40:43], v[222:225], v[180:183], v[0:3]
	v_mfma_f32_16x16x32_bf16 v[0:3], v[226:229], v[176:179], v[206:209]
	v_mfma_f32_16x16x32_bf16 v[32:35], v[230:233], v[180:183], v[0:3]
	v_mfma_f32_16x16x32_bf16 v[0:3], v[198:201], v[210:213], v[218:221]
	v_mfma_f32_16x16x32_bf16 v[24:27], v[222:225], v[214:217], v[0:3]
	v_mfma_f32_16x16x32_bf16 v[0:3], v[226:229], v[210:213], v[184:187]
	v_mfma_f32_16x16x32_bf16 v[16:19], v[230:233], v[214:217], v[0:3]
	v_mfma_f32_16x16x32_bf16 v[0:3], v[198:201], v[234:237], v[188:191]
	v_mfma_f32_16x16x32_bf16 v[8:11], v[222:225], v[238:241], v[0:3]
	v_mfma_f32_16x16x32_bf16 v[0:3], v[226:229], v[234:237], v[168:171]
	v_mfma_f32_16x16x32_bf16 v[0:3], v[230:233], v[238:241], v[0:3]
	s_setprio 0
	s_barrier
	s_andn2_b64 vcc, exec, s[14:15]
	s_cbranch_vccnz .LBB0_1168
	s_barrier

.LBB0_1306:
	ds_read_b128 v[52:55], v206
	ds_read_b128 v[56:59], v206 offset:1024
	ds_read_b128 v[60:63], v206 offset:2048
	ds_read_b128 v[64:67], v206 offset:3072
	ds_read_b128 v[76:79], v207
	ds_read_b128 v[80:83], v207 offset:1024
	ds_read_b128 v[84:87], v207 offset:2048
	ds_read_b128 v[88:91], v207 offset:3072
	s_add_u32 s46, s68, 0xfffc0080
	s_addc_u32 s47, s69, -1
	s_cmp_eq_u32 s84, 12
	s_cselect_b32 s73, s35, s47
	s_cselect_b32 s72, s57, s46
	s_cselect_b32 s71, s55, s83
	s_cselect_b32 s70, s65, s67
	v_lshl_add_u64 v[194:195], s[68:69], 0, v[186:187]
	s_add_i32 m0, s78, 0xc000
	ds_read_b128 v[160:163], v208
	ds_read_b128 v[164:167], v208 offset:1024
	ds_read_b128 v[168:171], v208 offset:2048
	ds_read_b128 v[172:175], v208 offset:3072
	ds_read_b128 v[190:193], v208 offset:4096
	ds_read_b128 v[210:213], v208 offset:5120
	ds_read_b128 v[214:217], v208 offset:6144
	ds_read_b128 v[218:221], v208 offset:7168
	global_load_lds_dwordx4 v[194:195], off
	v_lshl_add_u64 v[194:195], s[68:69], 0, v[188:189]
	s_add_i32 m0, s78, 0xe000
	s_nop 0
	global_load_lds_dwordx4 v[194:195], off
	s_waitcnt vmcnt(8)
	s_waitcnt lgkmcnt(0)
	s_barrier
	s_setprio 1
	s_waitcnt lgkmcnt(0)
	v_mfma_f32_16x16x32_bf16 v[148:151], v[52:55], v[160:163], v[148:151]
	v_mfma_f32_16x16x32_bf16 v[144:147], v[60:63], v[160:163], v[144:147]
	v_mfma_f32_16x16x32_bf16 v[132:135], v[52:55], v[168:171], v[132:135]
	v_mfma_f32_16x16x32_bf16 v[128:131], v[60:63], v[168:171], v[128:131]
	v_mfma_f32_16x16x32_bf16 v[116:119], v[52:55], v[190:193], v[116:119]
	v_mfma_f32_16x16x32_bf16 v[108:111], v[60:63], v[190:193], v[108:111]
	v_mfma_f32_16x16x32_bf16 v[112:115], v[52:55], v[214:217], v[112:115]
	v_mfma_f32_16x16x32_bf16 v[100:103], v[60:63], v[214:217], v[100:103]
	v_mfma_f32_16x16x32_bf16 v[148:151], v[56:59], v[164:167], v[148:151]
	v_mfma_f32_16x16x32_bf16 v[144:147], v[64:67], v[164:167], v[144:147]
	v_mfma_f32_16x16x32_bf16 v[132:135], v[56:59], v[172:175], v[132:135]
	v_mfma_f32_16x16x32_bf16 v[128:131], v[64:67], v[172:175], v[128:131]
	v_mfma_f32_16x16x32_bf16 v[116:119], v[56:59], v[210:213], v[116:119]
	v_mfma_f32_16x16x32_bf16 v[108:111], v[64:67], v[210:213], v[108:111]
	v_mfma_f32_16x16x32_bf16 v[112:115], v[56:59], v[218:221], v[112:115]
	v_mfma_f32_16x16x32_bf16 v[100:103], v[64:67], v[218:221], v[100:103]
	s_setprio 0
	s_setprio 1
	v_mfma_f32_16x16x32_bf16 v[156:159], v[76:79], v[160:163], v[156:159]
	v_mfma_f32_16x16x32_bf16 v[152:155], v[84:87], v[160:163], v[152:155]
	v_mfma_f32_16x16x32_bf16 v[140:143], v[76:79], v[168:171], v[140:143]
	v_mfma_f32_16x16x32_bf16 v[136:139], v[84:87], v[168:171], v[136:139]
	v_mfma_f32_16x16x32_bf16 v[124:127], v[76:79], v[190:193], v[124:127]
	v_mfma_f32_16x16x32_bf16 v[120:123], v[84:87], v[190:193], v[120:123]
	v_mfma_f32_16x16x32_bf16 v[104:107], v[76:79], v[214:217], v[104:107]
	v_mfma_f32_16x16x32_bf16 v[96:99], v[84:87], v[214:217], v[96:99]
	v_mfma_f32_16x16x32_bf16 v[156:159], v[80:83], v[164:167], v[156:159]
	v_mfma_f32_16x16x32_bf16 v[152:155], v[88:91], v[164:167], v[152:155]
	v_mfma_f32_16x16x32_bf16 v[140:143], v[80:83], v[172:175], v[140:143]
	v_mfma_f32_16x16x32_bf16 v[136:139], v[88:91], v[172:175], v[136:139]
	v_mfma_f32_16x16x32_bf16 v[124:127], v[80:83], v[210:213], v[124:127]
	v_mfma_f32_16x16x32_bf16 v[120:123], v[88:91], v[210:213], v[120:123]
	v_mfma_f32_16x16x32_bf16 v[104:107], v[80:83], v[218:221], v[104:107]
	v_mfma_f32_16x16x32_bf16 v[96:99], v[88:91], v[218:221], v[96:99]
	s_setprio 0
	s_barrier
	s_add_i32 s46, s74, s77
	v_lshl_add_u64 v[194:195], s[70:71], 0, v[178:179]
	s_mov_b32 m0, s46
	ds_read_b128 v[160:163], v208 offset:16384
	ds_read_b128 v[164:167], v208 offset:17408
	ds_read_b128 v[168:171], v208 offset:18432
	ds_read_b128 v[172:175], v208 offset:19456
	ds_read_b128 v[190:193], v208 offset:20480
	ds_read_b128 v[210:213], v208 offset:21504
	ds_read_b128 v[214:217], v208 offset:22528
	ds_read_b128 v[218:221], v208 offset:23552
	global_load_lds_dwordx4 v[194:195], off
	s_add_i32 m0, s46, 0x2000
	s_add_u32 s46, s70, 0x40000
	v_lshl_add_u64 v[226:227], s[70:71], 0, v[182:183]
	s_addc_u32 s47, s71, 0
	s_add_i32 s85, s79, s77
	global_load_lds_dwordx4 v[226:227], off
	v_lshl_add_u64 v[222:223], s[46:47], 0, v[178:179]
	s_mov_b32 m0, s85
	v_lshl_add_u64 v[228:229], s[72:73], 0, v[176:177]
	global_load_lds_dwordx4 v[222:223], off
	v_lshl_add_u64 v[222:223], s[46:47], 0, v[182:183]
	s_add_i32 m0, s85, 0x2000
	v_lshl_add_u64 v[230:231], s[72:73], 0, v[180:181]
	global_load_lds_dwordx4 v[222:223], off
	s_mov_b32 m0, s78
	s_nop 0
	global_load_lds_dwordx4 v[228:229], off
	s_mov_b32 m0, s4
	s_nop 0
	global_load_lds_dwordx4 v[230:231], off
	s_waitcnt vmcnt(8)
	s_waitcnt lgkmcnt(0)
	s_barrier
	s_setprio 1
	s_waitcnt lgkmcnt(0)
	v_mfma_f32_16x16x32_bf16 v[68:71], v[52:55], v[160:163], v[68:71]
	v_mfma_f32_16x16x32_bf16 v[48:51], v[60:63], v[160:163], v[48:51]
	v_mfma_f32_16x16x32_bf16 v[36:39], v[52:55], v[168:171], v[36:39]
	v_mfma_f32_16x16x32_bf16 v[32:35], v[60:63], v[168:171], v[32:35]
	v_mfma_f32_16x16x32_bf16 v[20:23], v[52:55], v[190:193], v[20:23]
	v_mfma_f32_16x16x32_bf16 v[12:15], v[60:63], v[190:193], v[12:15]
	v_mfma_f32_16x16x32_bf16 v[16:19], v[52:55], v[214:217], v[16:19]
	v_mfma_f32_16x16x32_bf16 v[4:7], v[60:63], v[214:217], v[4:7]
	v_mfma_f32_16x16x32_bf16 v[68:71], v[56:59], v[164:167], v[68:71]
	v_mfma_f32_16x16x32_bf16 v[48:51], v[64:67], v[164:167], v[48:51]
	v_mfma_f32_16x16x32_bf16 v[36:39], v[56:59], v[172:175], v[36:39]
	v_mfma_f32_16x16x32_bf16 v[32:35], v[64:67], v[172:175], v[32:35]
	v_mfma_f32_16x16x32_bf16 v[20:23], v[56:59], v[210:213], v[20:23]
	v_mfma_f32_16x16x32_bf16 v[12:15], v[64:67], v[210:213], v[12:15]
	v_mfma_f32_16x16x32_bf16 v[16:19], v[56:59], v[218:221], v[16:19]
	v_mfma_f32_16x16x32_bf16 v[4:7], v[64:67], v[218:221], v[4:7]
	s_setprio 0
	s_setprio 1
	v_mfma_f32_16x16x32_bf16 v[44:47], v[76:79], v[168:171], v[44:47]
	v_mfma_f32_16x16x32_bf16 v[40:43], v[84:87], v[168:171], v[40:43]
	v_mfma_f32_16x16x32_bf16 v[28:31], v[76:79], v[190:193], v[28:31]
	v_mfma_f32_16x16x32_bf16 v[24:27], v[84:87], v[190:193], v[24:27]
	v_mfma_f32_16x16x32_bf16 v[8:11], v[76:79], v[214:217], v[8:11]
	v_mfma_f32_16x16x32_bf16 v[0:3], v[84:87], v[214:217], v[0:3]
	v_mfma_f32_16x16x32_bf16 v[52:55], v[76:79], v[160:163], v[92:95]
	v_mfma_f32_16x16x32_bf16 v[56:59], v[84:87], v[160:163], v[72:75]
	v_mfma_f32_16x16x32_bf16 v[44:47], v[80:83], v[172:175], v[44:47]
	v_mfma_f32_16x16x32_bf16 v[40:43], v[88:91], v[172:175], v[40:43]
	v_mfma_f32_16x16x32_bf16 v[28:31], v[80:83], v[210:213], v[28:31]
	v_mfma_f32_16x16x32_bf16 v[24:27], v[88:91], v[210:213], v[24:27]
	v_mfma_f32_16x16x32_bf16 v[8:11], v[80:83], v[218:221], v[8:11]
	v_mfma_f32_16x16x32_bf16 v[0:3], v[88:91], v[218:221], v[0:3]
	v_mfma_f32_16x16x32_bf16 v[52:55], v[80:83], v[164:167], v[52:55]
	v_mfma_f32_16x16x32_bf16 v[56:59], v[88:91], v[164:167], v[56:59]
	s_setprio 0
	s_barrier
	s_add_i32 s85, 0, 0x18000
	s_add_i32 s86, 0, 0x1c000
	v_add_u32_e32 v76, s85, v198
	v_add_u32_e32 v92, s86, v198
	ds_read_b128 v[60:63], v76
	ds_read_b128 v[64:67], v76 offset:1024
	ds_read_b128 v[72:75], v76 offset:2048
	ds_read_b128 v[76:79], v76 offset:3072
	ds_read_b128 v[80:83], v92
	ds_read_b128 v[84:87], v92 offset:1024
	ds_read_b128 v[88:91], v92 offset:2048
	ds_read_b128 v[160:163], v92 offset:3072
	s_add_u32 s46, s72, 0x40000
	s_addc_u32 s47, s73, 0
	s_mov_b32 m0, s5
	v_lshl_add_u64 v[222:223], s[46:47], 0, v[176:177]
	ds_read_b128 v[92:95], v208 offset:32768
	ds_read_b128 v[164:167], v208 offset:33792
	ds_read_b128 v[168:171], v208 offset:34816
	ds_read_b128 v[172:175], v208 offset:35840
	ds_read_b128 v[190:193], v208 offset:36864
	ds_read_b128 v[210:213], v208 offset:37888
	ds_read_b128 v[214:217], v208 offset:38912
	ds_read_b128 v[218:221], v208 offset:39936
	global_load_lds_dwordx4 v[222:223], off
	v_lshl_add_u64 v[222:223], s[46:47], 0, v[180:181]
	s_mov_b32 m0, s48
	s_nop 0
	global_load_lds_dwordx4 v[222:223], off
	s_nop 0
	s_waitcnt vmcnt(8)
	s_waitcnt lgkmcnt(0)
	s_barrier
	s_setprio 1
	s_waitcnt lgkmcnt(0)
	v_mfma_f32_16x16x32_bf16 v[148:151], v[60:63], v[92:95], v[148:151]
	v_mfma_f32_16x16x32_bf16 v[144:147], v[72:75], v[92:95], v[144:147]
	v_mfma_f32_16x16x32_bf16 v[132:135], v[60:63], v[168:171], v[132:135]
	v_mfma_f32_16x16x32_bf16 v[128:131], v[72:75], v[168:171], v[128:131]
	v_mfma_f32_16x16x32_bf16 v[116:119], v[60:63], v[190:193], v[116:119]
	v_mfma_f32_16x16x32_bf16 v[108:111], v[72:75], v[190:193], v[108:111]
	v_mfma_f32_16x16x32_bf16 v[112:115], v[60:63], v[214:217], v[112:115]
	v_mfma_f32_16x16x32_bf16 v[100:103], v[72:75], v[214:217], v[100:103]
	v_mfma_f32_16x16x32_bf16 v[148:151], v[64:67], v[164:167], v[148:151]
	v_mfma_f32_16x16x32_bf16 v[144:147], v[76:79], v[164:167], v[144:147]
	v_mfma_f32_16x16x32_bf16 v[132:135], v[64:67], v[172:175], v[132:135]
	v_mfma_f32_16x16x32_bf16 v[128:131], v[76:79], v[172:175], v[128:131]
	v_mfma_f32_16x16x32_bf16 v[116:119], v[64:67], v[210:213], v[116:119]
	v_mfma_f32_16x16x32_bf16 v[108:111], v[76:79], v[210:213], v[108:111]
	v_mfma_f32_16x16x32_bf16 v[112:115], v[64:67], v[218:221], v[112:115]
	v_mfma_f32_16x16x32_bf16 v[100:103], v[76:79], v[218:221], v[100:103]
	s_setprio 0
	s_setprio 1
	v_mfma_f32_16x16x32_bf16 v[156:159], v[80:83], v[92:95], v[156:159]
	v_mfma_f32_16x16x32_bf16 v[92:95], v[88:91], v[92:95], v[152:155]
	v_mfma_f32_16x16x32_bf16 v[152:155], v[160:163], v[164:167], v[92:95]
	v_mfma_f32_16x16x32_bf16 v[92:95], v[80:83], v[168:171], v[140:143]
	v_mfma_f32_16x16x32_bf16 v[140:143], v[84:87], v[172:175], v[92:95]
	v_mfma_f32_16x16x32_bf16 v[92:95], v[88:91], v[168:171], v[136:139]
	v_mfma_f32_16x16x32_bf16 v[136:139], v[160:163], v[172:175], v[92:95]
	v_mfma_f32_16x16x32_bf16 v[92:95], v[80:83], v[190:193], v[124:127]
	v_mfma_f32_16x16x32_bf16 v[124:127], v[84:87], v[210:213], v[92:95]
	v_mfma_f32_16x16x32_bf16 v[92:95], v[88:91], v[190:193], v[120:123]
	v_mfma_f32_16x16x32_bf16 v[120:123], v[160:163], v[210:213], v[92:95]
	v_mfma_f32_16x16x32_bf16 v[92:95], v[80:83], v[214:217], v[104:107]
	v_mfma_f32_16x16x32_bf16 v[104:107], v[84:87], v[218:221], v[92:95]
	v_mfma_f32_16x16x32_bf16 v[92:95], v[88:91], v[214:217], v[96:99]
	v_mfma_f32_16x16x32_bf16 v[156:159], v[84:87], v[164:167], v[156:159]
	v_mfma_f32_16x16x32_bf16 v[96:99], v[160:163], v[218:221], v[92:95]
	s_setprio 0
	s_barrier
	s_add_i32 s46, s85, s77
	s_nop 2
	v_lshl_add_u64 v[92:93], v[194:195], 0, s[20:21]
	s_mov_b32 m0, s46
	ds_read_b128 v[164:167], v208 offset:49152
	ds_read_b128 v[168:171], v208 offset:50176
	ds_read_b128 v[172:175], v208 offset:51200
	ds_read_b128 v[190:193], v208 offset:52224
	ds_read_b128 v[210:213], v208 offset:53248
	ds_read_b128 v[214:217], v208 offset:54272
	ds_read_b128 v[218:221], v208 offset:55296
	ds_read_b128 v[222:225], v208 offset:56320
	global_load_lds_dwordx4 v[92:93], off
	s_add_i32 m0, s46, 0x2000
	s_add_u32 s46, s70, 0x40080
	v_lshl_add_u64 v[92:93], v[226:227], 0, s[20:21]
	s_addc_u32 s47, s71, 0
	s_add_i32 s70, s86, s77
	global_load_lds_dwordx4 v[92:93], off
	v_lshl_add_u64 v[92:93], s[46:47], 0, v[178:179]
	s_mov_b32 m0, s70
	s_nop 0
	global_load_lds_dwordx4 v[92:93], off
	v_lshl_add_u64 v[92:93], s[46:47], 0, v[182:183]
	s_add_i32 m0, s70, 0x2000
	s_nop 0
	global_load_lds_dwordx4 v[92:93], off
	v_lshl_add_u64 v[92:93], v[228:229], 0, s[20:21]
	s_mov_b32 m0, s50
	s_nop 0
	global_load_lds_dwordx4 v[92:93], off
	v_lshl_add_u64 v[92:93], v[230:231], 0, s[20:21]
	s_mov_b32 m0, s51
	s_nop 0
	global_load_lds_dwordx4 v[92:93], off
	s_nop 0
	s_waitcnt vmcnt(8)
	s_waitcnt lgkmcnt(0)
	s_barrier
	s_setprio 1
	s_waitcnt lgkmcnt(0)
	v_mfma_f32_16x16x32_bf16 v[68:71], v[60:63], v[164:167], v[68:71]
	v_mfma_f32_16x16x32_bf16 v[48:51], v[72:75], v[164:167], v[48:51]
	v_mfma_f32_16x16x32_bf16 v[36:39], v[60:63], v[172:175], v[36:39]
	v_mfma_f32_16x16x32_bf16 v[32:35], v[72:75], v[172:175], v[32:35]
	v_mfma_f32_16x16x32_bf16 v[20:23], v[60:63], v[210:213], v[20:23]
	v_mfma_f32_16x16x32_bf16 v[12:15], v[72:75], v[210:213], v[12:15]
	v_mfma_f32_16x16x32_bf16 v[16:19], v[60:63], v[218:221], v[16:19]
	v_mfma_f32_16x16x32_bf16 v[4:7], v[72:75], v[218:221], v[4:7]
	v_mfma_f32_16x16x32_bf16 v[68:71], v[64:67], v[168:171], v[68:71]
	v_mfma_f32_16x16x32_bf16 v[48:51], v[76:79], v[168:171], v[48:51]
	v_mfma_f32_16x16x32_bf16 v[36:39], v[64:67], v[190:193], v[36:39]
	v_mfma_f32_16x16x32_bf16 v[32:35], v[76:79], v[190:193], v[32:35]
	v_mfma_f32_16x16x32_bf16 v[20:23], v[64:67], v[214:217], v[20:23]
	v_mfma_f32_16x16x32_bf16 v[12:15], v[76:79], v[214:217], v[12:15]
	v_mfma_f32_16x16x32_bf16 v[16:19], v[64:67], v[222:225], v[16:19]
	v_mfma_f32_16x16x32_bf16 v[4:7], v[76:79], v[222:225], v[4:7]
	s_setprio 0
	s_setprio 1
	v_mfma_f32_16x16x32_bf16 v[52:55], v[80:83], v[164:167], v[52:55]
	v_mfma_f32_16x16x32_bf16 v[92:95], v[84:87], v[168:171], v[52:55]
	v_mfma_f32_16x16x32_bf16 v[52:55], v[88:91], v[164:167], v[56:59]
	v_mfma_f32_16x16x32_bf16 v[44:47], v[80:83], v[172:175], v[44:47]
	v_mfma_f32_16x16x32_bf16 v[40:43], v[88:91], v[172:175], v[40:43]
	v_mfma_f32_16x16x32_bf16 v[28:31], v[80:83], v[210:213], v[28:31]
	v_mfma_f32_16x16x32_bf16 v[24:27], v[88:91], v[210:213], v[24:27]
	v_mfma_f32_16x16x32_bf16 v[8:11], v[80:83], v[218:221], v[8:11]
	v_mfma_f32_16x16x32_bf16 v[0:3], v[88:91], v[218:221], v[0:3]
	v_mfma_f32_16x16x32_bf16 v[72:75], v[160:163], v[168:171], v[52:55]
	v_mfma_f32_16x16x32_bf16 v[44:47], v[84:87], v[190:193], v[44:47]
	v_mfma_f32_16x16x32_bf16 v[40:43], v[160:163], v[190:193], v[40:43]
	v_mfma_f32_16x16x32_bf16 v[28:31], v[84:87], v[214:217], v[28:31]
	v_mfma_f32_16x16x32_bf16 v[24:27], v[160:163], v[214:217], v[24:27]
	v_mfma_f32_16x16x32_bf16 v[8:11], v[84:87], v[222:225], v[8:11]
	v_mfma_f32_16x16x32_bf16 v[0:3], v[160:163], v[222:225], v[0:3]
	s_setprio 0
	s_barrier
	s_add_i32 s84, s84, 2
	s_add_u32 s68, s68, 0x100
	s_addc_u32 s69, s69, 0
	s_add_u32 s67, s67, 0x100
	s_addc_u32 s83, s83, 0
	s_cmp_gt_u32 s84, 13
	s_cbranch_scc0 .LBB0_1306
	s_and_b64 vcc, exec, s[22:23]
	s_cbranch_vccnz .LBB0_1414
	s_and_saveexec_b64 s[68:69], s[24:25]
	s_cbranch_execnz .LBB0_1415

.LBB0_1483:
	ds_read_b128 v[68:71], v202
	ds_read_b128 v[72:75], v202 offset:1024
	ds_read_b128 v[76:79], v202 offset:2048
	ds_read_b128 v[84:87], v202 offset:3072
	ds_read_b128 v[96:99], v203
	ds_read_b128 v[100:103], v203 offset:1024
	ds_read_b128 v[104:107], v203 offset:2048
	ds_read_b128 v[108:111], v203 offset:3072
	s_add_u32 s46, s66, 0xfffc0080
	s_addc_u32 s47, s67, -1
	s_cmp_eq_u32 s84, 12
	s_cselect_b32 s71, s11, s47
	s_cselect_b32 s70, s35, s46
	s_cselect_b32 s69, s57, s83
	s_cselect_b32 s68, s59, s65
	v_lshl_add_u64 v[156:157], s[66:67], 0, v[180:181]
	s_add_i32 m0, s49, 0xc000
	ds_read_b128 v[162:165], v204
	ds_read_b128 v[166:169], v204 offset:1024
	ds_read_b128 v[188:191], v204 offset:2048
	ds_read_b128 v[206:209], v204 offset:3072
	ds_read_b128 v[210:213], v204 offset:4096
	ds_read_b128 v[214:217], v204 offset:5120
	ds_read_b128 v[218:221], v204 offset:6144
	ds_read_b128 v[222:225], v204 offset:7168
	global_load_lds_dwordx4 v[156:157], off
	v_lshl_add_u64 v[156:157], s[66:67], 0, v[182:183]
	s_add_i32 m0, s49, 0xe000
	s_nop 0
	global_load_lds_dwordx4 v[156:157], off
	s_waitcnt vmcnt(8)
	s_waitcnt lgkmcnt(0)
	s_barrier
	s_setprio 1
	s_waitcnt lgkmcnt(0)
	v_mfma_f32_16x16x32_bf16 v[148:151], v[68:71], v[162:165], v[148:151]
	v_mfma_f32_16x16x32_bf16 v[144:147], v[76:79], v[162:165], v[144:147]
	v_mfma_f32_16x16x32_bf16 v[132:135], v[68:71], v[188:191], v[132:135]
	v_mfma_f32_16x16x32_bf16 v[128:131], v[76:79], v[188:191], v[128:131]
	v_mfma_f32_16x16x32_bf16 v[116:119], v[68:71], v[210:213], v[116:119]
	v_mfma_f32_16x16x32_bf16 v[92:95], v[76:79], v[210:213], v[92:95]
	v_mfma_f32_16x16x32_bf16 v[112:115], v[68:71], v[218:221], v[112:115]
	v_mfma_f32_16x16x32_bf16 v[80:83], v[76:79], v[218:221], v[80:83]
	v_mfma_f32_16x16x32_bf16 v[148:151], v[72:75], v[166:169], v[148:151]
	v_mfma_f32_16x16x32_bf16 v[144:147], v[84:87], v[166:169], v[144:147]
	v_mfma_f32_16x16x32_bf16 v[132:135], v[72:75], v[206:209], v[132:135]
	v_mfma_f32_16x16x32_bf16 v[128:131], v[84:87], v[206:209], v[128:131]
	v_mfma_f32_16x16x32_bf16 v[116:119], v[72:75], v[214:217], v[116:119]
	v_mfma_f32_16x16x32_bf16 v[92:95], v[84:87], v[214:217], v[92:95]
	v_mfma_f32_16x16x32_bf16 v[112:115], v[72:75], v[222:225], v[112:115]
	v_mfma_f32_16x16x32_bf16 v[80:83], v[84:87], v[222:225], v[80:83]
	s_setprio 0
	s_setprio 1
	v_mfma_f32_16x16x32_bf16 v[156:159], v[96:99], v[162:165], v[158:161]
	v_mfma_f32_16x16x32_bf16 v[152:155], v[104:107], v[162:165], v[152:155]
	v_mfma_f32_16x16x32_bf16 v[140:143], v[96:99], v[188:191], v[140:143]
	v_mfma_f32_16x16x32_bf16 v[136:139], v[104:107], v[188:191], v[136:139]
	v_mfma_f32_16x16x32_bf16 v[124:127], v[96:99], v[210:213], v[124:127]
	v_mfma_f32_16x16x32_bf16 v[120:123], v[104:107], v[210:213], v[120:123]
	v_mfma_f32_16x16x32_bf16 v[88:91], v[96:99], v[218:221], v[88:91]
	v_mfma_f32_16x16x32_bf16 v[64:67], v[104:107], v[218:221], v[64:67]
	v_mfma_f32_16x16x32_bf16 v[156:159], v[100:103], v[166:169], v[156:159]
	v_mfma_f32_16x16x32_bf16 v[152:155], v[108:111], v[166:169], v[152:155]
	v_mfma_f32_16x16x32_bf16 v[140:143], v[100:103], v[206:209], v[140:143]
	v_mfma_f32_16x16x32_bf16 v[136:139], v[108:111], v[206:209], v[136:139]
	v_mfma_f32_16x16x32_bf16 v[124:127], v[100:103], v[214:217], v[124:127]
	v_mfma_f32_16x16x32_bf16 v[120:123], v[108:111], v[214:217], v[120:123]
	v_mfma_f32_16x16x32_bf16 v[88:91], v[100:103], v[222:225], v[88:91]
	v_mfma_f32_16x16x32_bf16 v[64:67], v[108:111], v[222:225], v[64:67]
	s_setprio 0
	s_barrier
	s_add_i32 s46, s79, s48
	v_lshl_add_u64 v[226:227], s[68:69], 0, v[172:173]
	s_mov_b32 m0, s46
	ds_read_b128 v[160:163], v204 offset:16384
	ds_read_b128 v[164:167], v204 offset:17408
	ds_read_b128 v[188:191], v204 offset:18432
	ds_read_b128 v[206:209], v204 offset:19456
	ds_read_b128 v[210:213], v204 offset:20480
	ds_read_b128 v[214:217], v204 offset:21504
	ds_read_b128 v[218:221], v204 offset:22528
	ds_read_b128 v[222:225], v204 offset:23552
	global_load_lds_dwordx4 v[226:227], off
	s_add_i32 m0, s46, 0x2000
	s_add_u32 s46, s68, 0x40000
	v_lshl_add_u64 v[228:229], s[68:69], 0, v[176:177]
	s_addc_u32 s47, s69, 0
	s_add_i32 s85, s80, s48
	global_load_lds_dwordx4 v[228:229], off
	v_lshl_add_u64 v[168:169], s[46:47], 0, v[172:173]
	s_mov_b32 m0, s85
	v_lshl_add_u64 v[230:231], s[70:71], 0, v[170:171]
	global_load_lds_dwordx4 v[168:169], off
	v_lshl_add_u64 v[168:169], s[46:47], 0, v[176:177]
	s_add_i32 m0, s85, 0x2000
	v_lshl_add_u64 v[232:233], s[70:71], 0, v[174:175]
	global_load_lds_dwordx4 v[168:169], off
	s_mov_b32 m0, s49
	s_nop 0
	global_load_lds_dwordx4 v[230:231], off
	s_mov_b32 m0, s50
	s_nop 0
	global_load_lds_dwordx4 v[232:233], off
	s_waitcnt vmcnt(8)
	s_waitcnt lgkmcnt(0)
	s_barrier
	s_setprio 1
	s_waitcnt lgkmcnt(0)
	v_mfma_f32_16x16x32_bf16 v[52:55], v[68:71], v[160:163], v[52:55]
	v_mfma_f32_16x16x32_bf16 v[48:51], v[76:79], v[160:163], v[48:51]
	v_mfma_f32_16x16x32_bf16 v[36:39], v[68:71], v[188:191], v[36:39]
	v_mfma_f32_16x16x32_bf16 v[32:35], v[76:79], v[188:191], v[32:35]
	v_mfma_f32_16x16x32_bf16 v[20:23], v[68:71], v[210:213], v[20:23]
	v_mfma_f32_16x16x32_bf16 v[12:15], v[76:79], v[210:213], v[12:15]
	v_mfma_f32_16x16x32_bf16 v[16:19], v[68:71], v[218:221], v[16:19]
	v_mfma_f32_16x16x32_bf16 v[4:7], v[76:79], v[218:221], v[4:7]
	v_mfma_f32_16x16x32_bf16 v[52:55], v[72:75], v[164:167], v[52:55]
	v_mfma_f32_16x16x32_bf16 v[48:51], v[84:87], v[164:167], v[48:51]
	v_mfma_f32_16x16x32_bf16 v[36:39], v[72:75], v[206:209], v[36:39]
	v_mfma_f32_16x16x32_bf16 v[32:35], v[84:87], v[206:209], v[32:35]
	v_mfma_f32_16x16x32_bf16 v[20:23], v[72:75], v[214:217], v[20:23]
	v_mfma_f32_16x16x32_bf16 v[12:15], v[84:87], v[214:217], v[12:15]
	v_mfma_f32_16x16x32_bf16 v[16:19], v[72:75], v[222:225], v[16:19]
	v_mfma_f32_16x16x32_bf16 v[4:7], v[84:87], v[222:225], v[4:7]
	s_setprio 0
	s_setprio 1
	v_mfma_f32_16x16x32_bf16 v[60:63], v[96:99], v[160:163], v[60:63]
	v_mfma_f32_16x16x32_bf16 v[56:59], v[104:107], v[160:163], v[56:59]
	v_mfma_f32_16x16x32_bf16 v[44:47], v[96:99], v[188:191], v[44:47]
	v_mfma_f32_16x16x32_bf16 v[40:43], v[104:107], v[188:191], v[40:43]
	v_mfma_f32_16x16x32_bf16 v[28:31], v[96:99], v[210:213], v[28:31]
	v_mfma_f32_16x16x32_bf16 v[24:27], v[104:107], v[210:213], v[24:27]
	v_mfma_f32_16x16x32_bf16 v[8:11], v[96:99], v[218:221], v[8:11]
	v_mfma_f32_16x16x32_bf16 v[0:3], v[104:107], v[218:221], v[0:3]
	v_mfma_f32_16x16x32_bf16 v[60:63], v[100:103], v[164:167], v[60:63]
	v_mfma_f32_16x16x32_bf16 v[56:59], v[108:111], v[164:167], v[56:59]
	v_mfma_f32_16x16x32_bf16 v[44:47], v[100:103], v[206:209], v[44:47]
	v_mfma_f32_16x16x32_bf16 v[40:43], v[108:111], v[206:209], v[40:43]
	v_mfma_f32_16x16x32_bf16 v[28:31], v[100:103], v[214:217], v[28:31]
	v_mfma_f32_16x16x32_bf16 v[24:27], v[108:111], v[214:217], v[24:27]
	v_mfma_f32_16x16x32_bf16 v[8:11], v[100:103], v[222:225], v[8:11]
	v_mfma_f32_16x16x32_bf16 v[0:3], v[108:111], v[222:225], v[0:3]
	s_setprio 0
	s_barrier
	s_add_i32 s85, 0, 0x18000
	s_add_i32 s86, 0, 0x1c000
	v_add_u32_e32 v84, s85, v193
	v_add_u32_e32 v108, s86, v193
	ds_read_b128 v[68:71], v84
	ds_read_b128 v[72:75], v84 offset:1024
	ds_read_b128 v[76:79], v84 offset:2048
	ds_read_b128 v[84:87], v84 offset:3072
	ds_read_b128 v[96:99], v108
	ds_read_b128 v[100:103], v108 offset:1024
	ds_read_b128 v[104:107], v108 offset:2048
	ds_read_b128 v[108:111], v108 offset:3072
	s_add_u32 s46, s70, 0x40000
	s_addc_u32 s47, s71, 0
	s_mov_b32 m0, s51
	v_lshl_add_u64 v[160:161], s[46:47], 0, v[170:171]
	ds_read_b128 v[162:165], v204 offset:32768
	ds_read_b128 v[166:169], v204 offset:33792
	ds_read_b128 v[188:191], v204 offset:34816
	ds_read_b128 v[206:209], v204 offset:35840
	ds_read_b128 v[210:213], v204 offset:36864
	ds_read_b128 v[214:217], v204 offset:37888
	ds_read_b128 v[218:221], v204 offset:38912
	ds_read_b128 v[222:225], v204 offset:39936
	global_load_lds_dwordx4 v[160:161], off
	v_lshl_add_u64 v[160:161], s[46:47], 0, v[174:175]
	s_mov_b32 m0, s72
	s_nop 0
	global_load_lds_dwordx4 v[160:161], off
	s_nop 0
	s_waitcnt vmcnt(8)
	s_waitcnt lgkmcnt(0)
	s_barrier
	s_setprio 1
	s_waitcnt lgkmcnt(0)
	v_mfma_f32_16x16x32_bf16 v[148:151], v[68:71], v[162:165], v[148:151]
	v_mfma_f32_16x16x32_bf16 v[144:147], v[76:79], v[162:165], v[144:147]
	v_mfma_f32_16x16x32_bf16 v[132:135], v[68:71], v[188:191], v[132:135]
	v_mfma_f32_16x16x32_bf16 v[128:131], v[76:79], v[188:191], v[128:131]
	v_mfma_f32_16x16x32_bf16 v[116:119], v[68:71], v[210:213], v[116:119]
	v_mfma_f32_16x16x32_bf16 v[92:95], v[76:79], v[210:213], v[92:95]
	v_mfma_f32_16x16x32_bf16 v[112:115], v[68:71], v[218:221], v[112:115]
	v_mfma_f32_16x16x32_bf16 v[80:83], v[76:79], v[218:221], v[80:83]
	v_mfma_f32_16x16x32_bf16 v[148:151], v[72:75], v[166:169], v[148:151]
	v_mfma_f32_16x16x32_bf16 v[144:147], v[84:87], v[166:169], v[144:147]
	v_mfma_f32_16x16x32_bf16 v[132:135], v[72:75], v[206:209], v[132:135]
	v_mfma_f32_16x16x32_bf16 v[128:131], v[84:87], v[206:209], v[128:131]
	v_mfma_f32_16x16x32_bf16 v[116:119], v[72:75], v[214:217], v[116:119]
	v_mfma_f32_16x16x32_bf16 v[92:95], v[84:87], v[214:217], v[92:95]
	v_mfma_f32_16x16x32_bf16 v[112:115], v[72:75], v[222:225], v[112:115]
	v_mfma_f32_16x16x32_bf16 v[80:83], v[84:87], v[222:225], v[80:83]
	s_setprio 0
	s_setprio 1
	v_mfma_f32_16x16x32_bf16 v[156:159], v[96:99], v[162:165], v[156:159]
	v_mfma_f32_16x16x32_bf16 v[152:155], v[104:107], v[162:165], v[152:155]
	v_mfma_f32_16x16x32_bf16 v[140:143], v[96:99], v[188:191], v[140:143]
	v_mfma_f32_16x16x32_bf16 v[136:139], v[104:107], v[188:191], v[136:139]
	v_mfma_f32_16x16x32_bf16 v[124:127], v[96:99], v[210:213], v[124:127]
	v_mfma_f32_16x16x32_bf16 v[120:123], v[104:107], v[210:213], v[120:123]
	v_mfma_f32_16x16x32_bf16 v[88:91], v[96:99], v[218:221], v[88:91]
	v_mfma_f32_16x16x32_bf16 v[64:67], v[104:107], v[218:221], v[64:67]
	v_mfma_f32_16x16x32_bf16 v[158:161], v[100:103], v[166:169], v[156:159]
	v_mfma_f32_16x16x32_bf16 v[152:155], v[108:111], v[166:169], v[152:155]
	v_mfma_f32_16x16x32_bf16 v[140:143], v[100:103], v[206:209], v[140:143]
	v_mfma_f32_16x16x32_bf16 v[136:139], v[108:111], v[206:209], v[136:139]
	v_mfma_f32_16x16x32_bf16 v[124:127], v[100:103], v[214:217], v[124:127]
	v_mfma_f32_16x16x32_bf16 v[120:123], v[108:111], v[214:217], v[120:123]
	v_mfma_f32_16x16x32_bf16 v[88:91], v[100:103], v[222:225], v[88:91]
	v_mfma_f32_16x16x32_bf16 v[64:67], v[108:111], v[222:225], v[64:67]
	s_setprio 0
	s_barrier
	s_add_i32 s46, s85, s48
	v_lshl_add_u64 v[156:157], v[226:227], 0, s[28:29]
	s_mov_b32 m0, s46
	ds_read_b128 v[162:165], v204 offset:49152
	ds_read_b128 v[166:169], v204 offset:50176
	ds_read_b128 v[188:191], v204 offset:51200
	ds_read_b128 v[206:209], v204 offset:52224
	ds_read_b128 v[210:213], v204 offset:53248
	ds_read_b128 v[214:217], v204 offset:54272
	ds_read_b128 v[218:221], v204 offset:55296
	ds_read_b128 v[222:225], v204 offset:56320
	global_load_lds_dwordx4 v[156:157], off
	s_add_i32 m0, s46, 0x2000
	s_add_u32 s46, s68, 0x40080
	v_lshl_add_u64 v[156:157], v[228:229], 0, s[28:29]
	s_addc_u32 s47, s69, 0
	s_add_i32 s68, s86, s48
	global_load_lds_dwordx4 v[156:157], off
	v_lshl_add_u64 v[156:157], s[46:47], 0, v[172:173]
	s_mov_b32 m0, s68
	s_nop 0
	global_load_lds_dwordx4 v[156:157], off
	v_lshl_add_u64 v[156:157], s[46:47], 0, v[176:177]
	s_add_i32 m0, s68, 0x2000
	s_nop 0
	global_load_lds_dwordx4 v[156:157], off
	v_lshl_add_u64 v[156:157], v[230:231], 0, s[28:29]
	s_mov_b32 m0, s76
	s_nop 0
	global_load_lds_dwordx4 v[156:157], off
	v_lshl_add_u64 v[156:157], v[232:233], 0, s[28:29]
	s_mov_b32 m0, s77
	s_nop 0
	global_load_lds_dwordx4 v[156:157], off
	s_waitcnt vmcnt(8)
	s_waitcnt lgkmcnt(0)
	s_barrier
	s_setprio 1
	s_waitcnt lgkmcnt(0)
	v_mfma_f32_16x16x32_bf16 v[52:55], v[68:71], v[162:165], v[52:55]
	v_mfma_f32_16x16x32_bf16 v[48:51], v[76:79], v[162:165], v[48:51]
	v_mfma_f32_16x16x32_bf16 v[36:39], v[68:71], v[188:191], v[36:39]
	v_mfma_f32_16x16x32_bf16 v[32:35], v[76:79], v[188:191], v[32:35]
	v_mfma_f32_16x16x32_bf16 v[20:23], v[68:71], v[210:213], v[20:23]
	v_mfma_f32_16x16x32_bf16 v[12:15], v[76:79], v[210:213], v[12:15]
	v_mfma_f32_16x16x32_bf16 v[16:19], v[68:71], v[218:221], v[16:19]
	v_mfma_f32_16x16x32_bf16 v[4:7], v[76:79], v[218:221], v[4:7]
	v_mfma_f32_16x16x32_bf16 v[52:55], v[72:75], v[166:169], v[52:55]
	v_mfma_f32_16x16x32_bf16 v[48:51], v[84:87], v[166:169], v[48:51]
	v_mfma_f32_16x16x32_bf16 v[36:39], v[72:75], v[206:209], v[36:39]
	v_mfma_f32_16x16x32_bf16 v[32:35], v[84:87], v[206:209], v[32:35]
	v_mfma_f32_16x16x32_bf16 v[20:23], v[72:75], v[214:217], v[20:23]
	v_mfma_f32_16x16x32_bf16 v[12:15], v[84:87], v[214:217], v[12:15]
	v_mfma_f32_16x16x32_bf16 v[16:19], v[72:75], v[222:225], v[16:19]
	v_mfma_f32_16x16x32_bf16 v[4:7], v[84:87], v[222:225], v[4:7]
	s_setprio 0
	s_setprio 1
	v_mfma_f32_16x16x32_bf16 v[60:63], v[96:99], v[162:165], v[60:63]
	v_mfma_f32_16x16x32_bf16 v[56:59], v[104:107], v[162:165], v[56:59]
	v_mfma_f32_16x16x32_bf16 v[44:47], v[96:99], v[188:191], v[44:47]
	v_mfma_f32_16x16x32_bf16 v[40:43], v[104:107], v[188:191], v[40:43]
	v_mfma_f32_16x16x32_bf16 v[28:31], v[96:99], v[210:213], v[28:31]
	v_mfma_f32_16x16x32_bf16 v[24:27], v[104:107], v[210:213], v[24:27]
	v_mfma_f32_16x16x32_bf16 v[8:11], v[96:99], v[218:221], v[8:11]
	v_mfma_f32_16x16x32_bf16 v[0:3], v[104:107], v[218:221], v[0:3]
	v_mfma_f32_16x16x32_bf16 v[60:63], v[100:103], v[166:169], v[60:63]
	v_mfma_f32_16x16x32_bf16 v[56:59], v[108:111], v[166:169], v[56:59]
	v_mfma_f32_16x16x32_bf16 v[44:47], v[100:103], v[206:209], v[44:47]
	v_mfma_f32_16x16x32_bf16 v[40:43], v[108:111], v[206:209], v[40:43]
	v_mfma_f32_16x16x32_bf16 v[28:31], v[100:103], v[214:217], v[28:31]
	v_mfma_f32_16x16x32_bf16 v[24:27], v[108:111], v[214:217], v[24:27]
	v_mfma_f32_16x16x32_bf16 v[8:11], v[100:103], v[222:225], v[8:11]
	v_mfma_f32_16x16x32_bf16 v[0:3], v[108:111], v[222:225], v[0:3]
	s_setprio 0
	s_barrier
	s_add_i32 s84, s84, 2
	s_add_u32 s66, s66, 0x100
	s_addc_u32 s67, s67, 0
	s_add_u32 s65, s65, 0x100
	s_addc_u32 s83, s83, 0
	s_cmp_gt_u32 s84, 13
	s_cbranch_scc0 .LBB0_1483
	s_and_b64 vcc, exec, s[30:31]
	s_cbranch_vccz .LBB0_1486
	s_barrier

.LBB0_1584:
	ds_read_b128 v[144:147], v154
	ds_read_b128 v[158:161], v154 offset:1024
	ds_read_b128 v[162:165], v154 offset:2048
	ds_read_b128 v[166:169], v154 offset:3072
	ds_read_b128 v[170:173], v155
	ds_read_b128 v[174:177], v155 offset:1024
	ds_read_b128 v[178:181], v155 offset:2048
	ds_read_b128 v[182:185], v155 offset:3072
	s_add_u32 s40, s30, 0x100
	s_addc_u32 s41, s31, 0
	s_cmp_eq_u32 s67, 40
	s_cselect_b32 s53, s9, s41
	s_cselect_b32 s52, s8, s40
	s_cselect_b32 s43, s29, s66
	s_cselect_b32 s42, s28, s65
	v_lshl_add_u64 v[148:149], s[30:31], 0, v[136:137]
	s_add_i32 m0, s50, 0xc000
	ds_read_b128 v[186:189], v156
	ds_read_b128 v[190:193], v156 offset:1024
	ds_read_b128 v[198:201], v156 offset:2048
	ds_read_b128 v[202:205], v156 offset:3072
	ds_read_b128 v[206:209], v156 offset:4096
	ds_read_b128 v[210:213], v156 offset:5120
	ds_read_b128 v[214:217], v156 offset:6144
	ds_read_b128 v[218:221], v156 offset:7168
	global_load_lds_dwordx4 v[148:149], off
	v_lshl_add_u64 v[148:149], s[30:31], 0, v[138:139]
	s_add_i32 m0, s50, 0xe000
	s_nop 0
	global_load_lds_dwordx4 v[148:149], off
	s_nop 0
	s_waitcnt vmcnt(8)
	s_waitcnt lgkmcnt(0)
	s_barrier
	s_setprio 1
	s_waitcnt lgkmcnt(0)
	v_mfma_f32_16x16x32_bf16 v[124:127], v[144:147], v[186:189], v[124:127]
	v_mfma_f32_16x16x32_bf16 v[120:123], v[162:165], v[186:189], v[120:123]
	v_mfma_f32_16x16x32_bf16 v[108:111], v[144:147], v[198:201], v[108:111]
	v_mfma_f32_16x16x32_bf16 v[104:107], v[162:165], v[198:201], v[104:107]
	v_mfma_f32_16x16x32_bf16 v[92:95], v[144:147], v[206:209], v[92:95]
	v_mfma_f32_16x16x32_bf16 v[88:91], v[162:165], v[206:209], v[88:91]
	v_mfma_f32_16x16x32_bf16 v[76:79], v[144:147], v[214:217], v[76:79]
	v_mfma_f32_16x16x32_bf16 v[72:75], v[162:165], v[214:217], v[72:75]
	v_mfma_f32_16x16x32_bf16 v[124:127], v[158:161], v[190:193], v[124:127]
	v_mfma_f32_16x16x32_bf16 v[120:123], v[166:169], v[190:193], v[120:123]
	v_mfma_f32_16x16x32_bf16 v[108:111], v[158:161], v[202:205], v[108:111]
	v_mfma_f32_16x16x32_bf16 v[104:107], v[166:169], v[202:205], v[104:107]
	v_mfma_f32_16x16x32_bf16 v[92:95], v[158:161], v[210:213], v[92:95]
	v_mfma_f32_16x16x32_bf16 v[88:91], v[166:169], v[210:213], v[88:91]
	v_mfma_f32_16x16x32_bf16 v[76:79], v[158:161], v[218:221], v[76:79]
	v_mfma_f32_16x16x32_bf16 v[72:75], v[166:169], v[218:221], v[72:75]
	s_setprio 0
	s_setprio 1
	v_mfma_f32_16x16x32_bf16 v[116:119], v[170:173], v[186:189], v[116:119]
	v_mfma_f32_16x16x32_bf16 v[112:115], v[178:181], v[186:189], v[112:115]
	v_mfma_f32_16x16x32_bf16 v[100:103], v[170:173], v[198:201], v[100:103]
	v_mfma_f32_16x16x32_bf16 v[96:99], v[178:181], v[198:201], v[96:99]
	v_mfma_f32_16x16x32_bf16 v[84:87], v[170:173], v[206:209], v[84:87]
	v_mfma_f32_16x16x32_bf16 v[80:83], v[178:181], v[206:209], v[80:83]
	v_mfma_f32_16x16x32_bf16 v[68:71], v[170:173], v[214:217], v[68:71]
	v_mfma_f32_16x16x32_bf16 v[64:67], v[178:181], v[214:217], v[64:67]
	v_mfma_f32_16x16x32_bf16 v[116:119], v[174:177], v[190:193], v[116:119]
	v_mfma_f32_16x16x32_bf16 v[112:115], v[182:185], v[190:193], v[112:115]
	v_mfma_f32_16x16x32_bf16 v[100:103], v[174:177], v[202:205], v[100:103]
	v_mfma_f32_16x16x32_bf16 v[96:99], v[182:185], v[202:205], v[96:99]
	v_mfma_f32_16x16x32_bf16 v[84:87], v[174:177], v[210:213], v[84:87]
	v_mfma_f32_16x16x32_bf16 v[80:83], v[182:185], v[210:213], v[80:83]
	v_mfma_f32_16x16x32_bf16 v[68:71], v[174:177], v[218:221], v[68:71]
	v_mfma_f32_16x16x32_bf16 v[64:67], v[182:185], v[218:221], v[64:67]
	s_setprio 0
	s_barrier
	s_add_i32 s30, s60, s3
	v_lshl_add_u64 v[148:149], s[42:43], 0, v[132:133]
	s_mov_b32 m0, s30
	ds_read_b128 v[186:189], v156 offset:16384
	ds_read_b128 v[190:193], v156 offset:17408
	ds_read_b128 v[198:201], v156 offset:18432
	ds_read_b128 v[202:205], v156 offset:19456
	ds_read_b128 v[206:209], v156 offset:20480
	ds_read_b128 v[210:213], v156 offset:21504
	ds_read_b128 v[214:217], v156 offset:22528
	ds_read_b128 v[218:221], v156 offset:23552
	global_load_lds_dwordx4 v[148:149], off
	s_add_i32 m0, s30, 0x2000
	s_add_u32 s30, s42, 0xb0000
	v_lshl_add_u64 v[194:195], s[42:43], 0, v[128:129]
	s_addc_u32 s31, s43, 0
	s_add_i32 s46, s61, s3
	global_load_lds_dwordx4 v[194:195], off
	v_lshl_add_u64 v[196:197], s[30:31], 0, v[132:133]
	s_mov_b32 m0, s46
	v_lshl_add_u64 v[222:223], s[52:53], 0, v[130:131]
	global_load_lds_dwordx4 v[196:197], off
	v_lshl_add_u64 v[196:197], s[30:31], 0, v[128:129]
	s_add_i32 m0, s46, 0x2000
	s_nop 0
	global_load_lds_dwordx4 v[196:197], off
	v_lshl_add_u64 v[196:197], s[52:53], 0, v[134:135]
	s_mov_b32 m0, s50
	s_nop 0
	global_load_lds_dwordx4 v[196:197], off
	s_mov_b32 m0, s51
	s_nop 0
	global_load_lds_dwordx4 v[222:223], off
	s_nop 0
	s_waitcnt vmcnt(8)
	s_waitcnt lgkmcnt(0)
	s_barrier
	s_setprio 1
	s_waitcnt lgkmcnt(0)
	v_mfma_f32_16x16x32_bf16 v[60:63], v[144:147], v[186:189], v[60:63]
	v_mfma_f32_16x16x32_bf16 v[56:59], v[162:165], v[186:189], v[56:59]
	v_mfma_f32_16x16x32_bf16 v[44:47], v[144:147], v[198:201], v[44:47]
	v_mfma_f32_16x16x32_bf16 v[40:43], v[162:165], v[198:201], v[40:43]
	v_mfma_f32_16x16x32_bf16 v[28:31], v[144:147], v[206:209], v[28:31]
	v_mfma_f32_16x16x32_bf16 v[24:27], v[162:165], v[206:209], v[24:27]
	v_mfma_f32_16x16x32_bf16 v[12:15], v[144:147], v[214:217], v[12:15]
	v_mfma_f32_16x16x32_bf16 v[8:11], v[162:165], v[214:217], v[8:11]
	v_mfma_f32_16x16x32_bf16 v[60:63], v[158:161], v[190:193], v[60:63]
	v_mfma_f32_16x16x32_bf16 v[56:59], v[166:169], v[190:193], v[56:59]
	v_mfma_f32_16x16x32_bf16 v[44:47], v[158:161], v[202:205], v[44:47]
	v_mfma_f32_16x16x32_bf16 v[40:43], v[166:169], v[202:205], v[40:43]
	v_mfma_f32_16x16x32_bf16 v[28:31], v[158:161], v[210:213], v[28:31]
	v_mfma_f32_16x16x32_bf16 v[24:27], v[166:169], v[210:213], v[24:27]
	v_mfma_f32_16x16x32_bf16 v[12:15], v[158:161], v[218:221], v[12:15]
	v_mfma_f32_16x16x32_bf16 v[8:11], v[166:169], v[218:221], v[8:11]
	s_setprio 0
	s_setprio 1
	v_mfma_f32_16x16x32_bf16 v[52:55], v[170:173], v[186:189], v[52:55]
	v_mfma_f32_16x16x32_bf16 v[48:51], v[178:181], v[186:189], v[48:51]
	v_mfma_f32_16x16x32_bf16 v[36:39], v[170:173], v[198:201], v[36:39]
	v_mfma_f32_16x16x32_bf16 v[32:35], v[178:181], v[198:201], v[32:35]
	v_mfma_f32_16x16x32_bf16 v[20:23], v[170:173], v[206:209], v[20:23]
	v_mfma_f32_16x16x32_bf16 v[16:19], v[178:181], v[206:209], v[16:19]
	v_mfma_f32_16x16x32_bf16 v[4:7], v[170:173], v[214:217], v[4:7]
	v_mfma_f32_16x16x32_bf16 v[0:3], v[178:181], v[214:217], v[0:3]
	v_mfma_f32_16x16x32_bf16 v[52:55], v[174:177], v[190:193], v[52:55]
	v_mfma_f32_16x16x32_bf16 v[48:51], v[182:185], v[190:193], v[48:51]
	v_mfma_f32_16x16x32_bf16 v[36:39], v[174:177], v[202:205], v[36:39]
	v_mfma_f32_16x16x32_bf16 v[32:35], v[182:185], v[202:205], v[32:35]
	v_mfma_f32_16x16x32_bf16 v[20:23], v[174:177], v[210:213], v[20:23]
	v_mfma_f32_16x16x32_bf16 v[16:19], v[182:185], v[210:213], v[16:19]
	v_mfma_f32_16x16x32_bf16 v[4:7], v[174:177], v[218:221], v[4:7]
	v_mfma_f32_16x16x32_bf16 v[0:3], v[182:185], v[218:221], v[0:3]
	s_setprio 0
	s_barrier
	s_add_i32 s46, 0, 0x18000
	v_add_u32_e32 v157, s46, v152
	s_add_i32 s47, 0, 0x1c000
	ds_read_b128 v[144:147], v157
	ds_read_b128 v[158:161], v157 offset:1024
	ds_read_b128 v[162:165], v157 offset:2048
	ds_read_b128 v[166:169], v157 offset:3072
	v_add_u32_e32 v157, s47, v152
	ds_read_b128 v[170:173], v157
	ds_read_b128 v[174:177], v157 offset:1024
	ds_read_b128 v[178:181], v157 offset:2048
	ds_read_b128 v[182:185], v157 offset:3072
	s_add_u32 s30, s52, 0xb0000
	s_addc_u32 s31, s53, 0
	s_mov_b32 m0, s54
	v_lshl_add_u64 v[224:225], s[30:31], 0, v[134:135]
	ds_read_b128 v[186:189], v156 offset:32768
	ds_read_b128 v[190:193], v156 offset:33792
	ds_read_b128 v[198:201], v156 offset:34816
	ds_read_b128 v[202:205], v156 offset:35840
	ds_read_b128 v[206:209], v156 offset:36864
	ds_read_b128 v[210:213], v156 offset:37888
	ds_read_b128 v[214:217], v156 offset:38912
	ds_read_b128 v[218:221], v156 offset:39936
	global_load_lds_dwordx4 v[224:225], off
	v_lshl_add_u64 v[224:225], s[30:31], 0, v[130:131]
	s_mov_b32 m0, s55
	s_nop 0
	global_load_lds_dwordx4 v[224:225], off
	s_nop 0
	s_waitcnt vmcnt(8)
	s_waitcnt lgkmcnt(0)
	s_barrier
	s_setprio 1
	s_waitcnt lgkmcnt(0)
	v_mfma_f32_16x16x32_bf16 v[124:127], v[144:147], v[186:189], v[124:127]
	v_mfma_f32_16x16x32_bf16 v[120:123], v[162:165], v[186:189], v[120:123]
	v_mfma_f32_16x16x32_bf16 v[108:111], v[144:147], v[198:201], v[108:111]
	v_mfma_f32_16x16x32_bf16 v[104:107], v[162:165], v[198:201], v[104:107]
	v_mfma_f32_16x16x32_bf16 v[92:95], v[144:147], v[206:209], v[92:95]
	v_mfma_f32_16x16x32_bf16 v[88:91], v[162:165], v[206:209], v[88:91]
	v_mfma_f32_16x16x32_bf16 v[76:79], v[144:147], v[214:217], v[76:79]
	v_mfma_f32_16x16x32_bf16 v[72:75], v[162:165], v[214:217], v[72:75]
	v_mfma_f32_16x16x32_bf16 v[124:127], v[158:161], v[190:193], v[124:127]
	v_mfma_f32_16x16x32_bf16 v[120:123], v[166:169], v[190:193], v[120:123]
	v_mfma_f32_16x16x32_bf16 v[108:111], v[158:161], v[202:205], v[108:111]
	v_mfma_f32_16x16x32_bf16 v[104:107], v[166:169], v[202:205], v[104:107]
	v_mfma_f32_16x16x32_bf16 v[92:95], v[158:161], v[210:213], v[92:95]
	v_mfma_f32_16x16x32_bf16 v[88:91], v[166:169], v[210:213], v[88:91]
	v_mfma_f32_16x16x32_bf16 v[76:79], v[158:161], v[218:221], v[76:79]
	v_mfma_f32_16x16x32_bf16 v[72:75], v[166:169], v[218:221], v[72:75]
	s_setprio 0
	s_setprio 1
	v_mfma_f32_16x16x32_bf16 v[116:119], v[170:173], v[186:189], v[116:119]
	v_mfma_f32_16x16x32_bf16 v[112:115], v[178:181], v[186:189], v[112:115]
	v_mfma_f32_16x16x32_bf16 v[100:103], v[170:173], v[198:201], v[100:103]
	v_mfma_f32_16x16x32_bf16 v[96:99], v[178:181], v[198:201], v[96:99]
	v_mfma_f32_16x16x32_bf16 v[84:87], v[170:173], v[206:209], v[84:87]
	v_mfma_f32_16x16x32_bf16 v[80:83], v[178:181], v[206:209], v[80:83]
	v_mfma_f32_16x16x32_bf16 v[68:71], v[170:173], v[214:217], v[68:71]
	v_mfma_f32_16x16x32_bf16 v[64:67], v[178:181], v[214:217], v[64:67]
	v_mfma_f32_16x16x32_bf16 v[116:119], v[174:177], v[190:193], v[116:119]
	v_mfma_f32_16x16x32_bf16 v[112:115], v[182:185], v[190:193], v[112:115]
	v_mfma_f32_16x16x32_bf16 v[100:103], v[174:177], v[202:205], v[100:103]
	v_mfma_f32_16x16x32_bf16 v[96:99], v[182:185], v[202:205], v[96:99]
	v_mfma_f32_16x16x32_bf16 v[84:87], v[174:177], v[210:213], v[84:87]
	v_mfma_f32_16x16x32_bf16 v[80:83], v[182:185], v[210:213], v[80:83]
	v_mfma_f32_16x16x32_bf16 v[68:71], v[174:177], v[218:221], v[68:71]
	v_mfma_f32_16x16x32_bf16 v[64:67], v[182:185], v[218:221], v[64:67]
	s_setprio 0
	s_barrier
	s_add_i32 s30, s46, s3
	v_lshl_add_u64 v[148:149], v[148:149], 0, s[16:17]
	s_mov_b32 m0, s30
	ds_read_b128 v[186:189], v156 offset:49152
	ds_read_b128 v[190:193], v156 offset:50176
	ds_read_b128 v[198:201], v156 offset:51200
	ds_read_b128 v[202:205], v156 offset:52224
	ds_read_b128 v[206:209], v156 offset:53248
	ds_read_b128 v[210:213], v156 offset:54272
	ds_read_b128 v[214:217], v156 offset:55296
	ds_read_b128 v[218:221], v156 offset:56320
	global_load_lds_dwordx4 v[148:149], off
	s_add_i32 m0, s30, 0x2000
	s_add_u32 s30, s42, 0xb0080
	v_lshl_add_u64 v[148:149], v[194:195], 0, s[16:17]
	s_addc_u32 s31, s43, 0
	s_add_i32 s42, s47, s3
	global_load_lds_dwordx4 v[148:149], off
	v_lshl_add_u64 v[148:149], s[30:31], 0, v[132:133]
	s_mov_b32 m0, s42
	s_nop 0
	global_load_lds_dwordx4 v[148:149], off
	v_lshl_add_u64 v[148:149], s[30:31], 0, v[128:129]
	s_add_i32 m0, s42, 0x2000
	s_nop 0
	global_load_lds_dwordx4 v[148:149], off
	v_lshl_add_u64 v[148:149], v[196:197], 0, s[16:17]
	s_mov_b32 m0, s57
	s_nop 0
	global_load_lds_dwordx4 v[148:149], off
	v_lshl_add_u64 v[148:149], v[222:223], 0, s[16:17]
	s_mov_b32 m0, s58
	s_nop 0
	global_load_lds_dwordx4 v[148:149], off
	s_waitcnt vmcnt(8)
	s_waitcnt lgkmcnt(0)
	s_barrier
	s_setprio 1
	s_waitcnt lgkmcnt(0)
	v_mfma_f32_16x16x32_bf16 v[60:63], v[144:147], v[186:189], v[60:63]
	v_mfma_f32_16x16x32_bf16 v[56:59], v[162:165], v[186:189], v[56:59]
	v_mfma_f32_16x16x32_bf16 v[44:47], v[144:147], v[198:201], v[44:47]
	v_mfma_f32_16x16x32_bf16 v[40:43], v[162:165], v[198:201], v[40:43]
	v_mfma_f32_16x16x32_bf16 v[28:31], v[144:147], v[206:209], v[28:31]
	v_mfma_f32_16x16x32_bf16 v[24:27], v[162:165], v[206:209], v[24:27]
	v_mfma_f32_16x16x32_bf16 v[12:15], v[144:147], v[214:217], v[12:15]
	v_mfma_f32_16x16x32_bf16 v[8:11], v[162:165], v[214:217], v[8:11]
	v_mfma_f32_16x16x32_bf16 v[60:63], v[158:161], v[190:193], v[60:63]
	v_mfma_f32_16x16x32_bf16 v[56:59], v[166:169], v[190:193], v[56:59]
	v_mfma_f32_16x16x32_bf16 v[44:47], v[158:161], v[202:205], v[44:47]
	v_mfma_f32_16x16x32_bf16 v[40:43], v[166:169], v[202:205], v[40:43]
	v_mfma_f32_16x16x32_bf16 v[28:31], v[158:161], v[210:213], v[28:31]
	v_mfma_f32_16x16x32_bf16 v[24:27], v[166:169], v[210:213], v[24:27]
	v_mfma_f32_16x16x32_bf16 v[12:15], v[158:161], v[218:221], v[12:15]
	v_mfma_f32_16x16x32_bf16 v[8:11], v[166:169], v[218:221], v[8:11]
	s_setprio 0
	s_setprio 1
	v_mfma_f32_16x16x32_bf16 v[52:55], v[170:173], v[186:189], v[52:55]
	v_mfma_f32_16x16x32_bf16 v[48:51], v[178:181], v[186:189], v[48:51]
	v_mfma_f32_16x16x32_bf16 v[36:39], v[170:173], v[198:201], v[36:39]
	v_mfma_f32_16x16x32_bf16 v[32:35], v[178:181], v[198:201], v[32:35]
	v_mfma_f32_16x16x32_bf16 v[20:23], v[170:173], v[206:209], v[20:23]
	v_mfma_f32_16x16x32_bf16 v[16:19], v[178:181], v[206:209], v[16:19]
	v_mfma_f32_16x16x32_bf16 v[4:7], v[170:173], v[214:217], v[4:7]
	v_mfma_f32_16x16x32_bf16 v[0:3], v[178:181], v[214:217], v[0:3]
	v_mfma_f32_16x16x32_bf16 v[52:55], v[174:177], v[190:193], v[52:55]
	v_mfma_f32_16x16x32_bf16 v[48:51], v[182:185], v[190:193], v[48:51]
	v_mfma_f32_16x16x32_bf16 v[36:39], v[174:177], v[202:205], v[36:39]
	v_mfma_f32_16x16x32_bf16 v[32:35], v[182:185], v[202:205], v[32:35]
	v_mfma_f32_16x16x32_bf16 v[20:23], v[174:177], v[210:213], v[20:23]
	v_mfma_f32_16x16x32_bf16 v[16:19], v[182:185], v[210:213], v[16:19]
	v_mfma_f32_16x16x32_bf16 v[4:7], v[174:177], v[218:221], v[4:7]
	v_mfma_f32_16x16x32_bf16 v[0:3], v[182:185], v[218:221], v[0:3]
	s_setprio 0
	s_barrier
	s_add_i32 s67, s67, 2
	s_add_u32 s65, s65, 0x100
	s_addc_u32 s66, s66, 0
	s_cmp_gt_u32 s67, 41
	s_mov_b64 s[30:31], s[40:41]
	s_cbranch_scc0 .LBB0_1584
	s_and_b64 vcc, exec, s[18:19]
	s_cbranch_vccz .LBB0_1587
	s_barrier

.LBB0_1603:
	ds_read_b128 v[0:3], v141
	ds_read_b128 v[4:7], v141 offset:1024
	ds_read_b128 v[8:11], v141 offset:2048
	ds_read_b128 v[12:15], v141 offset:3072
	ds_read_b128 v[16:19], v142
	ds_read_b128 v[20:23], v142 offset:1024
	ds_read_b128 v[24:27], v142 offset:2048
	ds_read_b128 v[28:31], v142 offset:3072
	s_add_u32 s46, s40, 0xb0080
	s_addc_u32 s47, s41, 0
	s_mov_b32 m0, s62
	v_lshl_add_u64 v[64:65], s[46:47], 0, v[134:135]
	ds_read_b128 v[32:35], v143
	ds_read_b128 v[36:39], v143 offset:1024
	ds_read_b128 v[40:43], v143 offset:2048
	ds_read_b128 v[44:47], v143 offset:3072
	ds_read_b128 v[48:51], v143 offset:4096
	ds_read_b128 v[52:55], v143 offset:5120
	ds_read_b128 v[56:59], v143 offset:6144
	ds_read_b128 v[60:63], v143 offset:7168
	global_load_lds_dwordx4 v[64:65], off
	v_lshl_add_u64 v[64:65], s[46:47], 0, v[130:131]
	s_mov_b32 m0, s63
	s_nop 0
	global_load_lds_dwordx4 v[64:65], off
	s_nop 0
	s_waitcnt vmcnt(8)
	s_waitcnt lgkmcnt(0)
	s_barrier
	s_setprio 1
	s_waitcnt lgkmcnt(0)
	v_mfma_f32_16x16x32_bf16 v[64:67], v[0:3], v[32:35], 0
	v_mfma_f32_16x16x32_bf16 v[68:71], v[8:11], v[32:35], 0
	v_mfma_f32_16x16x32_bf16 v[72:75], v[0:3], v[40:43], 0
	v_mfma_f32_16x16x32_bf16 v[76:79], v[8:11], v[40:43], 0
	v_mfma_f32_16x16x32_bf16 v[80:83], v[0:3], v[48:51], 0
	v_mfma_f32_16x16x32_bf16 v[84:87], v[8:11], v[48:51], 0
	v_mfma_f32_16x16x32_bf16 v[88:91], v[0:3], v[56:59], 0
	v_mfma_f32_16x16x32_bf16 v[92:95], v[8:11], v[56:59], 0
	v_mfma_f32_16x16x32_bf16 v[64:67], v[4:7], v[36:39], v[64:67]
	v_mfma_f32_16x16x32_bf16 v[68:71], v[12:15], v[36:39], v[68:71]
	v_mfma_f32_16x16x32_bf16 v[72:75], v[4:7], v[44:47], v[72:75]
	v_mfma_f32_16x16x32_bf16 v[76:79], v[12:15], v[44:47], v[76:79]
	v_mfma_f32_16x16x32_bf16 v[80:83], v[4:7], v[52:55], v[80:83]
	v_mfma_f32_16x16x32_bf16 v[84:87], v[12:15], v[52:55], v[84:87]
	v_mfma_f32_16x16x32_bf16 v[88:91], v[4:7], v[60:63], v[88:91]
	v_mfma_f32_16x16x32_bf16 v[92:95], v[12:15], v[60:63], v[92:95]
	s_setprio 0
	s_setprio 1
	v_mfma_f32_16x16x32_bf16 v[96:99], v[16:19], v[32:35], 0
	v_mfma_f32_16x16x32_bf16 v[32:35], v[24:27], v[32:35], 0
	v_mfma_f32_16x16x32_bf16 v[96:99], v[20:23], v[36:39], v[96:99]
	v_mfma_f32_16x16x32_bf16 v[32:35], v[28:31], v[36:39], v[32:35]
	v_mfma_f32_16x16x32_bf16 v[36:39], v[16:19], v[40:43], 0
	v_mfma_f32_16x16x32_bf16 v[40:43], v[24:27], v[40:43], 0
	v_mfma_f32_16x16x32_bf16 v[36:39], v[20:23], v[44:47], v[36:39]
	v_mfma_f32_16x16x32_bf16 v[40:43], v[28:31], v[44:47], v[40:43]
	v_mfma_f32_16x16x32_bf16 v[44:47], v[16:19], v[48:51], 0
	v_mfma_f32_16x16x32_bf16 v[48:51], v[24:27], v[48:51], 0
	v_mfma_f32_16x16x32_bf16 v[44:47], v[20:23], v[52:55], v[44:47]
	v_mfma_f32_16x16x32_bf16 v[48:51], v[28:31], v[52:55], v[48:51]
	v_mfma_f32_16x16x32_bf16 v[52:55], v[16:19], v[56:59], 0
	v_mfma_f32_16x16x32_bf16 v[56:59], v[24:27], v[56:59], 0
	v_mfma_f32_16x16x32_bf16 v[52:55], v[20:23], v[60:63], v[52:55]
	v_mfma_f32_16x16x32_bf16 v[56:59], v[28:31], v[60:63], v[56:59]
	s_setprio 0
	s_barrier
	v_lshl_add_u64 v[136:137], s[42:43], 0, v[132:133]
	s_mov_b32 m0, s64
	v_lshl_add_u64 v[144:145], v[136:137], 0, s[12:13]
	v_lshl_add_u64 v[196:197], s[42:43], 0, v[128:129]
	s_add_u32 s46, s42, 0xb0100
	ds_read_b128 v[60:63], v143 offset:16384
	ds_read_b128 v[100:103], v143 offset:17408
	ds_read_b128 v[104:107], v143 offset:18432
	ds_read_b128 v[108:111], v143 offset:19456
	ds_read_b128 v[112:115], v143 offset:20480
	ds_read_b128 v[116:119], v143 offset:21504
	ds_read_b128 v[120:123], v143 offset:22528
	ds_read_b128 v[124:127], v143 offset:23552
	global_load_lds_dwordx4 v[144:145], off
	v_lshl_add_u64 v[144:145], v[196:197], 0, s[12:13]
	s_mov_b32 m0, s65
	s_addc_u32 s47, s43, 0
	s_add_i32 s25, s57, s35
	global_load_lds_dwordx4 v[144:145], off
	v_lshl_add_u64 v[144:145], s[46:47], 0, v[132:133]
	s_mov_b32 m0, s25
	v_lshl_add_u64 v[210:211], s[40:41], 0, v[134:135]
	global_load_lds_dwordx4 v[144:145], off
	v_lshl_add_u64 v[144:145], s[46:47], 0, v[128:129]
	s_add_i32 s46, s25, 0x2000
	s_mov_b32 m0, s46
	v_lshl_add_u64 v[212:213], s[40:41], 0, v[130:131]
	global_load_lds_dwordx4 v[144:145], off
	v_lshl_add_u64 v[144:145], v[210:211], 0, s[12:13]
	s_mov_b32 m0, s31
	s_nop 0
	global_load_lds_dwordx4 v[144:145], off
	v_lshl_add_u64 v[144:145], v[212:213], 0, s[12:13]
	s_mov_b32 m0, s49
	s_nop 0
	global_load_lds_dwordx4 v[144:145], off
	s_nop 0
	s_waitcnt vmcnt(8)
	s_waitcnt lgkmcnt(0)
	s_barrier
	s_setprio 1
	s_waitcnt lgkmcnt(0)
	v_mfma_f32_16x16x32_bf16 v[144:147], v[0:3], v[60:63], 0
	v_mfma_f32_16x16x32_bf16 v[152:155], v[0:3], v[104:107], 0
	v_mfma_f32_16x16x32_bf16 v[160:163], v[0:3], v[112:115], 0
	v_mfma_f32_16x16x32_bf16 v[0:3], v[0:3], v[120:123], 0
	v_mfma_f32_16x16x32_bf16 v[144:147], v[4:7], v[100:103], v[144:147]
	v_mfma_f32_16x16x32_bf16 v[152:155], v[4:7], v[108:111], v[152:155]
	v_mfma_f32_16x16x32_bf16 v[160:163], v[4:7], v[116:119], v[160:163]
	v_mfma_f32_16x16x32_bf16 v[0:3], v[4:7], v[124:127], v[0:3]
	v_mfma_f32_16x16x32_bf16 v[4:7], v[8:11], v[120:123], 0
	v_mfma_f32_16x16x32_bf16 v[148:151], v[8:11], v[60:63], 0
	v_mfma_f32_16x16x32_bf16 v[156:159], v[8:11], v[104:107], 0
	v_mfma_f32_16x16x32_bf16 v[164:167], v[8:11], v[112:115], 0
	v_mfma_f32_16x16x32_bf16 v[4:7], v[12:15], v[124:127], v[4:7]
	v_mfma_f32_16x16x32_bf16 v[148:151], v[12:15], v[100:103], v[148:151]
	v_mfma_f32_16x16x32_bf16 v[156:159], v[12:15], v[108:111], v[156:159]
	v_mfma_f32_16x16x32_bf16 v[164:167], v[12:15], v[116:119], v[164:167]
	s_setprio 0
	s_setprio 1
	v_mfma_f32_16x16x32_bf16 v[8:11], v[16:19], v[60:63], 0
	v_mfma_f32_16x16x32_bf16 v[12:15], v[24:27], v[60:63], 0
	v_mfma_f32_16x16x32_bf16 v[8:11], v[20:23], v[100:103], v[8:11]
	v_mfma_f32_16x16x32_bf16 v[12:15], v[28:31], v[100:103], v[12:15]
	v_mfma_f32_16x16x32_bf16 v[60:63], v[16:19], v[104:107], 0
	v_mfma_f32_16x16x32_bf16 v[100:103], v[24:27], v[104:107], 0
	v_mfma_f32_16x16x32_bf16 v[104:107], v[16:19], v[112:115], 0
	v_mfma_f32_16x16x32_bf16 v[16:19], v[16:19], v[120:123], 0
	v_mfma_f32_16x16x32_bf16 v[60:63], v[20:23], v[108:111], v[60:63]
	v_mfma_f32_16x16x32_bf16 v[100:103], v[28:31], v[108:111], v[100:103]
	v_mfma_f32_16x16x32_bf16 v[104:107], v[20:23], v[116:119], v[104:107]
	v_mfma_f32_16x16x32_bf16 v[108:111], v[24:27], v[112:115], 0
	v_mfma_f32_16x16x32_bf16 v[16:19], v[20:23], v[124:127], v[16:19]
	v_mfma_f32_16x16x32_bf16 v[20:23], v[24:27], v[120:123], 0
	v_mfma_f32_16x16x32_bf16 v[108:111], v[28:31], v[116:119], v[108:111]
	v_mfma_f32_16x16x32_bf16 v[20:23], v[28:31], v[124:127], v[20:23]
	s_setprio 0
	s_barrier
	s_add_i32 s47, 0, 0x18000
	s_add_i32 s74, 0, 0x1c000
	v_add_u32_e32 v222, s47, v138
	v_add_u32_e32 v230, s74, v138
	ds_read_b128 v[24:27], v222
	ds_read_b128 v[28:31], v222 offset:1024
	ds_read_b128 v[112:115], v222 offset:2048
	ds_read_b128 v[116:119], v222 offset:3072
	ds_read_b128 v[120:123], v230
	ds_read_b128 v[124:127], v230 offset:1024
	ds_read_b128 v[168:171], v230 offset:2048
	ds_read_b128 v[172:175], v230 offset:3072
	s_add_u32 s70, s40, 0xb0100
	s_addc_u32 s71, s41, 0
	s_mov_b32 m0, s50
	v_lshl_add_u64 v[214:215], s[70:71], 0, v[134:135]
	ds_read_b128 v[176:179], v143 offset:32768
	ds_read_b128 v[180:183], v143 offset:33792
	ds_read_b128 v[184:187], v143 offset:34816
	ds_read_b128 v[188:191], v143 offset:35840
	ds_read_b128 v[192:195], v143 offset:36864
	ds_read_b128 v[198:201], v143 offset:37888
	ds_read_b128 v[202:205], v143 offset:38912
	ds_read_b128 v[206:209], v143 offset:39936
	global_load_lds_dwordx4 v[214:215], off
	v_lshl_add_u64 v[214:215], s[70:71], 0, v[130:131]
	s_mov_b32 m0, s51
	s_nop 0
	global_load_lds_dwordx4 v[214:215], off
	s_nop 0
	s_waitcnt vmcnt(8)
	s_waitcnt lgkmcnt(0)
	s_barrier
	s_setprio 1
	s_waitcnt lgkmcnt(0)
	v_mfma_f32_16x16x32_bf16 v[64:67], v[24:27], v[176:179], v[64:67]
	v_mfma_f32_16x16x32_bf16 v[68:71], v[112:115], v[176:179], v[68:71]
	v_mfma_f32_16x16x32_bf16 v[72:75], v[24:27], v[184:187], v[72:75]
	v_mfma_f32_16x16x32_bf16 v[76:79], v[112:115], v[184:187], v[76:79]
	v_mfma_f32_16x16x32_bf16 v[80:83], v[24:27], v[192:195], v[80:83]
	v_mfma_f32_16x16x32_bf16 v[84:87], v[112:115], v[192:195], v[84:87]
	v_mfma_f32_16x16x32_bf16 v[88:91], v[24:27], v[202:205], v[88:91]
	v_mfma_f32_16x16x32_bf16 v[92:95], v[112:115], v[202:205], v[92:95]
	v_mfma_f32_16x16x32_bf16 v[64:67], v[28:31], v[180:183], v[64:67]
	v_mfma_f32_16x16x32_bf16 v[68:71], v[116:119], v[180:183], v[68:71]
	v_mfma_f32_16x16x32_bf16 v[72:75], v[28:31], v[188:191], v[72:75]
	v_mfma_f32_16x16x32_bf16 v[76:79], v[116:119], v[188:191], v[76:79]
	v_mfma_f32_16x16x32_bf16 v[80:83], v[28:31], v[198:201], v[80:83]
	v_mfma_f32_16x16x32_bf16 v[84:87], v[116:119], v[198:201], v[84:87]
	v_mfma_f32_16x16x32_bf16 v[88:91], v[28:31], v[206:209], v[88:91]
	v_mfma_f32_16x16x32_bf16 v[92:95], v[116:119], v[206:209], v[92:95]
	s_setprio 0
	s_setprio 1
	v_mfma_f32_16x16x32_bf16 v[96:99], v[120:123], v[176:179], v[96:99]
	v_mfma_f32_16x16x32_bf16 v[32:35], v[168:171], v[176:179], v[32:35]
	v_mfma_f32_16x16x32_bf16 v[36:39], v[120:123], v[184:187], v[36:39]
	v_mfma_f32_16x16x32_bf16 v[40:43], v[168:171], v[184:187], v[40:43]
	v_mfma_f32_16x16x32_bf16 v[44:47], v[120:123], v[192:195], v[44:47]
	v_mfma_f32_16x16x32_bf16 v[48:51], v[168:171], v[192:195], v[48:51]
	v_mfma_f32_16x16x32_bf16 v[52:55], v[120:123], v[202:205], v[52:55]
	v_mfma_f32_16x16x32_bf16 v[56:59], v[168:171], v[202:205], v[56:59]
	v_mfma_f32_16x16x32_bf16 v[96:99], v[124:127], v[180:183], v[96:99]
	v_mfma_f32_16x16x32_bf16 v[32:35], v[172:175], v[180:183], v[32:35]
	v_mfma_f32_16x16x32_bf16 v[36:39], v[124:127], v[188:191], v[36:39]
	v_mfma_f32_16x16x32_bf16 v[40:43], v[172:175], v[188:191], v[40:43]
	v_mfma_f32_16x16x32_bf16 v[44:47], v[124:127], v[198:201], v[44:47]
	v_mfma_f32_16x16x32_bf16 v[48:51], v[172:175], v[198:201], v[48:51]
	v_mfma_f32_16x16x32_bf16 v[52:55], v[124:127], v[206:209], v[52:55]
	v_mfma_f32_16x16x32_bf16 v[56:59], v[172:175], v[206:209], v[56:59]
	s_setprio 0
	s_barrier
	s_add_i32 s70, s47, s35
	s_add_i32 s47, s70, 0x2000
	v_lshl_add_u64 v[136:137], v[136:137], 0, s[14:15]
	s_mov_b32 m0, s70
	s_add_u32 s72, s42, 0xb0180
	ds_read_b128 v[176:179], v143 offset:49152
	ds_read_b128 v[180:183], v143 offset:50176
	ds_read_b128 v[184:187], v143 offset:51200
	ds_read_b128 v[188:191], v143 offset:52224
	ds_read_b128 v[192:195], v143 offset:53248
	ds_read_b128 v[198:201], v143 offset:54272
	ds_read_b128 v[202:205], v143 offset:55296
	ds_read_b128 v[206:209], v143 offset:56320
	global_load_lds_dwordx4 v[136:137], off
	v_lshl_add_u64 v[136:137], v[196:197], 0, s[14:15]
	s_mov_b32 m0, s47
	s_addc_u32 s73, s43, 0
	s_add_i32 s42, s74, s35
	global_load_lds_dwordx4 v[136:137], off
	v_lshl_add_u64 v[136:137], s[72:73], 0, v[132:133]
	s_mov_b32 m0, s42
	s_add_i32 s43, s42, 0x2000
	global_load_lds_dwordx4 v[136:137], off
	v_lshl_add_u64 v[136:137], s[72:73], 0, v[128:129]
	s_mov_b32 m0, s43
	s_nop 0
	global_load_lds_dwordx4 v[136:137], off
	v_lshl_add_u64 v[136:137], v[210:211], 0, s[14:15]
	s_mov_b32 m0, s54
	s_nop 0
	global_load_lds_dwordx4 v[136:137], off
	v_lshl_add_u64 v[136:137], v[212:213], 0, s[14:15]
	s_mov_b32 m0, s55
	s_nop 0
	global_load_lds_dwordx4 v[136:137], off
	s_nop 0
	s_waitcnt vmcnt(8)
	s_waitcnt lgkmcnt(0)
	s_barrier
	s_setprio 1
	s_waitcnt lgkmcnt(0)
	v_mfma_f32_16x16x32_bf16 v[0:3], v[24:27], v[202:205], v[0:3]
	v_mfma_f32_16x16x32_bf16 v[4:7], v[112:115], v[202:205], v[4:7]
	v_mfma_f32_16x16x32_bf16 v[144:147], v[24:27], v[176:179], v[144:147]
	v_mfma_f32_16x16x32_bf16 v[148:151], v[112:115], v[176:179], v[148:151]
	v_mfma_f32_16x16x32_bf16 v[152:155], v[24:27], v[184:187], v[152:155]
	v_mfma_f32_16x16x32_bf16 v[156:159], v[112:115], v[184:187], v[156:159]
	v_mfma_f32_16x16x32_bf16 v[160:163], v[24:27], v[192:195], v[160:163]
	v_mfma_f32_16x16x32_bf16 v[164:167], v[112:115], v[192:195], v[164:167]
	v_mfma_f32_16x16x32_bf16 v[0:3], v[28:31], v[206:209], v[0:3]
	v_mfma_f32_16x16x32_bf16 v[4:7], v[116:119], v[206:209], v[4:7]
	v_mfma_f32_16x16x32_bf16 v[144:147], v[28:31], v[180:183], v[144:147]
	v_mfma_f32_16x16x32_bf16 v[148:151], v[116:119], v[180:183], v[148:151]
	v_mfma_f32_16x16x32_bf16 v[152:155], v[28:31], v[188:191], v[152:155]
	v_mfma_f32_16x16x32_bf16 v[156:159], v[116:119], v[188:191], v[156:159]
	v_mfma_f32_16x16x32_bf16 v[160:163], v[28:31], v[198:201], v[160:163]
	v_mfma_f32_16x16x32_bf16 v[164:167], v[116:119], v[198:201], v[164:167]
	s_setprio 0
	s_setprio 1
	v_mfma_f32_16x16x32_bf16 v[8:11], v[120:123], v[176:179], v[8:11]
	v_mfma_f32_16x16x32_bf16 v[12:15], v[168:171], v[176:179], v[12:15]
	v_mfma_f32_16x16x32_bf16 v[24:27], v[120:123], v[184:187], v[60:63]
	v_mfma_f32_16x16x32_bf16 v[28:31], v[168:171], v[184:187], v[100:103]
	v_mfma_f32_16x16x32_bf16 v[60:63], v[120:123], v[192:195], v[104:107]
	v_mfma_f32_16x16x32_bf16 v[100:103], v[168:171], v[192:195], v[108:111]
	v_mfma_f32_16x16x32_bf16 v[16:19], v[120:123], v[202:205], v[16:19]
	v_mfma_f32_16x16x32_bf16 v[20:23], v[168:171], v[202:205], v[20:23]
	v_mfma_f32_16x16x32_bf16 v[8:11], v[124:127], v[180:183], v[8:11]
	v_mfma_f32_16x16x32_bf16 v[12:15], v[172:175], v[180:183], v[12:15]
	v_mfma_f32_16x16x32_bf16 v[24:27], v[124:127], v[188:191], v[24:27]
	v_mfma_f32_16x16x32_bf16 v[28:31], v[172:175], v[188:191], v[28:31]
	v_mfma_f32_16x16x32_bf16 v[60:63], v[124:127], v[198:201], v[60:63]
	v_mfma_f32_16x16x32_bf16 v[100:103], v[172:175], v[198:201], v[100:103]
	v_mfma_f32_16x16x32_bf16 v[16:19], v[124:127], v[206:209], v[16:19]
	v_mfma_f32_16x16x32_bf16 v[20:23], v[172:175], v[206:209], v[20:23]
	s_setprio 0
	s_barrier
	ds_read_b128 v[104:107], v141
	ds_read_b128 v[108:111], v141 offset:1024
	ds_read_b128 v[112:115], v141 offset:2048
	ds_read_b128 v[116:119], v141 offset:3072
	ds_read_b128 v[120:123], v142
	ds_read_b128 v[124:127], v142 offset:1024
	ds_read_b128 v[168:171], v142 offset:2048
	ds_read_b128 v[172:175], v142 offset:3072
	s_add_u32 s40, s40, 0xb0180
	s_addc_u32 s41, s41, 0
	s_mov_b32 m0, s62
	v_lshl_add_u64 v[136:137], s[40:41], 0, v[134:135]
	ds_read_b128 v[176:179], v143
	ds_read_b128 v[180:183], v143 offset:1024
	ds_read_b128 v[184:187], v143 offset:2048
	ds_read_b128 v[188:191], v143 offset:3072
	ds_read_b128 v[192:195], v143 offset:4096
	ds_read_b128 v[198:201], v143 offset:5120
	ds_read_b128 v[202:205], v143 offset:6144
	ds_read_b128 v[206:209], v143 offset:7168
	global_load_lds_dwordx4 v[136:137], off
	v_lshl_add_u64 v[136:137], s[40:41], 0, v[130:131]
	s_mov_b32 m0, s63
	s_nop 0
	global_load_lds_dwordx4 v[136:137], off
	s_nop 0
	s_waitcnt vmcnt(8)
	s_waitcnt lgkmcnt(0)
	s_barrier
	s_setprio 1
	s_waitcnt lgkmcnt(0)
	v_mfma_f32_16x16x32_bf16 v[88:91], v[104:107], v[202:205], v[88:91]
	v_mfma_f32_16x16x32_bf16 v[64:67], v[104:107], v[176:179], v[64:67]
	v_mfma_f32_16x16x32_bf16 v[68:71], v[112:115], v[176:179], v[68:71]
	v_mfma_f32_16x16x32_bf16 v[72:75], v[104:107], v[184:187], v[72:75]
	v_mfma_f32_16x16x32_bf16 v[76:79], v[112:115], v[184:187], v[76:79]
	v_mfma_f32_16x16x32_bf16 v[80:83], v[104:107], v[192:195], v[80:83]
	v_mfma_f32_16x16x32_bf16 v[84:87], v[112:115], v[192:195], v[84:87]
	v_mfma_f32_16x16x32_bf16 v[210:213], v[108:111], v[206:209], v[88:91]
	v_mfma_f32_16x16x32_bf16 v[88:91], v[112:115], v[202:205], v[92:95]
	v_mfma_f32_16x16x32_bf16 v[64:67], v[108:111], v[180:183], v[64:67]
	v_mfma_f32_16x16x32_bf16 v[68:71], v[116:119], v[180:183], v[68:71]
	v_mfma_f32_16x16x32_bf16 v[72:75], v[108:111], v[188:191], v[72:75]
	v_mfma_f32_16x16x32_bf16 v[76:79], v[116:119], v[188:191], v[76:79]
	v_mfma_f32_16x16x32_bf16 v[80:83], v[108:111], v[198:201], v[80:83]
	v_mfma_f32_16x16x32_bf16 v[84:87], v[116:119], v[198:201], v[84:87]
	v_mfma_f32_16x16x32_bf16 v[92:95], v[116:119], v[206:209], v[88:91]
	s_setprio 0
	s_setprio 1
	v_mfma_f32_16x16x32_bf16 v[48:51], v[168:171], v[192:195], v[48:51]
	v_mfma_f32_16x16x32_bf16 v[88:91], v[120:123], v[176:179], v[96:99]
	v_mfma_f32_16x16x32_bf16 v[32:35], v[168:171], v[176:179], v[32:35]
	v_mfma_f32_16x16x32_bf16 v[36:39], v[120:123], v[184:187], v[36:39]
	v_mfma_f32_16x16x32_bf16 v[40:43], v[168:171], v[184:187], v[40:43]
	v_mfma_f32_16x16x32_bf16 v[44:47], v[120:123], v[192:195], v[44:47]
	v_mfma_f32_16x16x32_bf16 v[176:179], v[172:175], v[198:201], v[48:51]
	v_mfma_f32_16x16x32_bf16 v[48:51], v[120:123], v[202:205], v[52:55]
	v_mfma_f32_16x16x32_bf16 v[32:35], v[172:175], v[180:183], v[32:35]
	v_mfma_f32_16x16x32_bf16 v[36:39], v[124:127], v[188:191], v[36:39]
	v_mfma_f32_16x16x32_bf16 v[40:43], v[172:175], v[188:191], v[40:43]
	v_mfma_f32_16x16x32_bf16 v[44:47], v[124:127], v[198:201], v[44:47]
	v_mfma_f32_16x16x32_bf16 v[52:55], v[124:127], v[206:209], v[48:51]
	v_mfma_f32_16x16x32_bf16 v[48:51], v[168:171], v[202:205], v[56:59]
	v_mfma_f32_16x16x32_bf16 v[214:217], v[124:127], v[180:183], v[88:91]
	v_mfma_f32_16x16x32_bf16 v[180:183], v[172:175], v[206:209], v[48:51]
	s_setprio 0
	s_barrier
	s_mov_b32 m0, s64
	v_lshl_add_u64 v[136:137], s[28:29], 0, v[132:133]
	s_add_u32 s40, s28, 0xb0000
	s_nop 0
	ds_read_b128 v[48:51], v143 offset:16384
	ds_read_b128 v[56:59], v143 offset:17408
	ds_read_b128 v[88:91], v143 offset:18432
	ds_read_b128 v[96:99], v143 offset:19456
	ds_read_b128 v[184:187], v143 offset:20480
	ds_read_b128 v[188:191], v143 offset:21504
	ds_read_b128 v[192:195], v143 offset:22528
	ds_read_b128 v[198:201], v143 offset:23552
	global_load_lds_dwordx4 v[136:137], off
	v_lshl_add_u64 v[196:197], s[28:29], 0, v[128:129]
	s_mov_b32 m0, s65
	s_addc_u32 s41, s29, 0
	global_load_lds_dwordx4 v[196:197], off
	v_lshl_add_u64 v[202:203], s[40:41], 0, v[132:133]
	s_mov_b32 m0, s25
	v_lshl_add_u64 v[250:251], s[26:27], 0, v[134:135]
	global_load_lds_dwordx4 v[202:203], off
	v_lshl_add_u64 v[202:203], s[40:41], 0, v[128:129]
	s_mov_b32 m0, s46
	v_lshl_add_u64 v[252:253], s[26:27], 0, v[130:131]
	global_load_lds_dwordx4 v[202:203], off
	s_mov_b32 m0, s31
	s_nop 0
	global_load_lds_dwordx4 v[250:251], off
	s_mov_b32 m0, s49
	s_nop 0
	global_load_lds_dwordx4 v[252:253], off
	s_nop 0
	s_waitcnt vmcnt(8)
	s_waitcnt lgkmcnt(0)
	s_barrier
	s_setprio 1
	s_waitcnt lgkmcnt(0)
	v_mfma_f32_16x16x32_bf16 v[0:3], v[104:107], v[192:195], v[0:3]
	v_mfma_f32_16x16x32_bf16 v[4:7], v[112:115], v[192:195], v[4:7]
	v_mfma_f32_16x16x32_bf16 v[144:147], v[104:107], v[48:51], v[144:147]
	v_mfma_f32_16x16x32_bf16 v[148:151], v[112:115], v[48:51], v[148:151]
	v_mfma_f32_16x16x32_bf16 v[152:155], v[104:107], v[88:91], v[152:155]
	v_mfma_f32_16x16x32_bf16 v[156:159], v[112:115], v[88:91], v[156:159]
	v_mfma_f32_16x16x32_bf16 v[160:163], v[104:107], v[184:187], v[160:163]
	v_mfma_f32_16x16x32_bf16 v[164:167], v[112:115], v[184:187], v[164:167]
	v_mfma_f32_16x16x32_bf16 v[0:3], v[108:111], v[198:201], v[0:3]
	v_mfma_f32_16x16x32_bf16 v[4:7], v[116:119], v[198:201], v[4:7]
	v_mfma_f32_16x16x32_bf16 v[144:147], v[108:111], v[56:59], v[144:147]
	v_mfma_f32_16x16x32_bf16 v[148:151], v[116:119], v[56:59], v[148:151]
	v_mfma_f32_16x16x32_bf16 v[152:155], v[108:111], v[96:99], v[152:155]
	v_mfma_f32_16x16x32_bf16 v[156:159], v[116:119], v[96:99], v[156:159]
	v_mfma_f32_16x16x32_bf16 v[160:163], v[108:111], v[188:191], v[160:163]
	v_mfma_f32_16x16x32_bf16 v[164:167], v[116:119], v[188:191], v[164:167]
	s_setprio 0
	s_setprio 1
	v_mfma_f32_16x16x32_bf16 v[12:15], v[168:171], v[48:51], v[12:15]
	v_mfma_f32_16x16x32_bf16 v[202:205], v[172:175], v[56:59], v[12:15]
	v_mfma_f32_16x16x32_bf16 v[12:15], v[120:123], v[88:91], v[24:27]
	v_mfma_f32_16x16x32_bf16 v[24:27], v[124:127], v[96:99], v[12:15]
	v_mfma_f32_16x16x32_bf16 v[12:15], v[168:171], v[88:91], v[28:31]
	v_mfma_f32_16x16x32_bf16 v[206:209], v[172:175], v[96:99], v[12:15]
	v_mfma_f32_16x16x32_bf16 v[12:15], v[120:123], v[184:187], v[60:63]
	v_mfma_f32_16x16x32_bf16 v[218:221], v[124:127], v[188:191], v[12:15]
	v_mfma_f32_16x16x32_bf16 v[12:15], v[168:171], v[184:187], v[100:103]
	v_mfma_f32_16x16x32_bf16 v[8:11], v[120:123], v[48:51], v[8:11]
	v_mfma_f32_16x16x32_bf16 v[184:187], v[172:175], v[188:191], v[12:15]
	v_mfma_f32_16x16x32_bf16 v[12:15], v[120:123], v[192:195], v[16:19]
	v_mfma_f32_16x16x32_bf16 v[8:11], v[124:127], v[56:59], v[8:11]
	v_mfma_f32_16x16x32_bf16 v[188:191], v[124:127], v[198:201], v[12:15]
	v_mfma_f32_16x16x32_bf16 v[12:15], v[168:171], v[192:195], v[20:23]
	v_mfma_f32_16x16x32_bf16 v[168:171], v[172:175], v[198:201], v[12:15]
	s_setprio 0
	s_barrier
	s_nop 4
	ds_read_b128 v[12:15], v222
	ds_read_b128 v[16:19], v222 offset:1024
	ds_read_b128 v[172:175], v222 offset:2048
	ds_read_b128 v[192:195], v222 offset:3072
	ds_read_b128 v[198:201], v230
	ds_read_b128 v[222:225], v230 offset:1024
	ds_read_b128 v[226:229], v230 offset:2048
	ds_read_b128 v[230:233], v230 offset:3072
	s_add_u32 s40, s26, 0xb0000
	s_addc_u32 s41, s27, 0
	s_mov_b32 m0, s50
	v_lshl_add_u64 v[48:49], s[40:41], 0, v[134:135]
	ds_read_b128 v[20:23], v143 offset:32768
	ds_read_b128 v[28:31], v143 offset:33792
	ds_read_b128 v[60:63], v143 offset:34816
	ds_read_b128 v[100:103], v143 offset:35840
	ds_read_b128 v[234:237], v143 offset:36864
	ds_read_b128 v[238:241], v143 offset:37888
	ds_read_b128 v[242:245], v143 offset:38912
	ds_read_b128 v[246:249], v143 offset:39936
	global_load_lds_dwordx4 v[48:49], off
	v_lshl_add_u64 v[48:49], s[40:41], 0, v[130:131]
	s_mov_b32 m0, s51
	s_nop 0
	global_load_lds_dwordx4 v[48:49], off
	s_waitcnt vmcnt(8)
	s_waitcnt lgkmcnt(0)
	s_barrier
	s_setprio 1
	s_waitcnt lgkmcnt(0)
	v_mfma_f32_16x16x32_bf16 v[48:51], v[12:15], v[20:23], v[64:67]
	v_mfma_f32_16x16x32_bf16 v[120:123], v[16:19], v[28:31], v[48:51]
	v_mfma_f32_16x16x32_bf16 v[48:51], v[172:175], v[20:23], v[68:71]
	v_mfma_f32_16x16x32_bf16 v[112:115], v[192:195], v[28:31], v[48:51]
	v_mfma_f32_16x16x32_bf16 v[48:51], v[12:15], v[60:63], v[72:75]
	v_mfma_f32_16x16x32_bf16 v[104:107], v[16:19], v[100:103], v[48:51]
	v_mfma_f32_16x16x32_bf16 v[48:51], v[172:175], v[60:63], v[76:79]
	v_mfma_f32_16x16x32_bf16 v[96:99], v[192:195], v[100:103], v[48:51]
	v_mfma_f32_16x16x32_bf16 v[48:51], v[12:15], v[234:237], v[80:83]
	v_mfma_f32_16x16x32_bf16 v[88:91], v[16:19], v[238:241], v[48:51]
	v_mfma_f32_16x16x32_bf16 v[48:51], v[172:175], v[234:237], v[84:87]
	v_mfma_f32_16x16x32_bf16 v[80:83], v[192:195], v[238:241], v[48:51]
	v_mfma_f32_16x16x32_bf16 v[48:51], v[12:15], v[242:245], v[210:213]
	v_mfma_f32_16x16x32_bf16 v[56:59], v[16:19], v[246:249], v[48:51]
	v_mfma_f32_16x16x32_bf16 v[48:51], v[172:175], v[242:245], v[92:95]
	v_mfma_f32_16x16x32_bf16 v[48:51], v[192:195], v[246:249], v[48:51]
	s_setprio 0
	s_setprio 1
	v_mfma_f32_16x16x32_bf16 v[64:67], v[198:201], v[20:23], v[214:217]
	v_mfma_f32_16x16x32_bf16 v[20:23], v[226:229], v[20:23], v[32:35]
	v_mfma_f32_16x16x32_bf16 v[116:119], v[230:233], v[28:31], v[20:23]
	v_mfma_f32_16x16x32_bf16 v[20:23], v[198:201], v[60:63], v[36:39]
	v_mfma_f32_16x16x32_bf16 v[108:111], v[222:225], v[100:103], v[20:23]
	v_mfma_f32_16x16x32_bf16 v[20:23], v[226:229], v[60:63], v[40:43]
	v_mfma_f32_16x16x32_bf16 v[100:103], v[230:233], v[100:103], v[20:23]
	v_mfma_f32_16x16x32_bf16 v[20:23], v[198:201], v[234:237], v[44:47]
	v_mfma_f32_16x16x32_bf16 v[92:95], v[222:225], v[238:241], v[20:23]
	v_mfma_f32_16x16x32_bf16 v[20:23], v[226:229], v[234:237], v[176:179]
	v_mfma_f32_16x16x32_bf16 v[84:87], v[230:233], v[238:241], v[20:23]
	v_mfma_f32_16x16x32_bf16 v[20:23], v[198:201], v[242:245], v[52:55]
	v_mfma_f32_16x16x32_bf16 v[60:63], v[222:225], v[246:249], v[20:23]
	v_mfma_f32_16x16x32_bf16 v[20:23], v[226:229], v[242:245], v[180:183]
	v_mfma_f32_16x16x32_bf16 v[124:127], v[222:225], v[28:31], v[64:67]
	v_mfma_f32_16x16x32_bf16 v[52:55], v[230:233], v[246:249], v[20:23]
	s_setprio 0
	s_barrier
	s_mov_b32 m0, s70
	s_nop 2
	v_lshl_add_u64 v[20:21], v[136:137], 0, s[8:9]
	s_add_u32 s40, s28, 0xb0080
	ds_read_b128 v[32:35], v143 offset:49152
	ds_read_b128 v[40:43], v143 offset:50176
	ds_read_b128 v[176:179], v143 offset:51200
	ds_read_b128 v[180:183], v143 offset:52224
	ds_read_b128 v[210:213], v143 offset:53248
	ds_read_b128 v[214:217], v143 offset:54272
	ds_read_b128 v[234:237], v143 offset:55296
	ds_read_b128 v[238:241], v143 offset:56320
	global_load_lds_dwordx4 v[20:21], off
	v_lshl_add_u64 v[20:21], v[196:197], 0, s[8:9]
	s_mov_b32 m0, s47
	s_addc_u32 s41, s29, 0
	global_load_lds_dwordx4 v[20:21], off
	v_lshl_add_u64 v[20:21], s[40:41], 0, v[132:133]
	s_mov_b32 m0, s42
	s_nop 0
	global_load_lds_dwordx4 v[20:21], off
	v_lshl_add_u64 v[20:21], s[40:41], 0, v[128:129]
	s_mov_b32 m0, s43
	s_nop 0
	global_load_lds_dwordx4 v[20:21], off
	v_lshl_add_u64 v[20:21], v[250:251], 0, s[8:9]
	s_mov_b32 m0, s54
	s_nop 0
	global_load_lds_dwordx4 v[20:21], off
	v_lshl_add_u64 v[20:21], v[252:253], 0, s[8:9]
	s_mov_b32 m0, s55
	s_nop 0
	global_load_lds_dwordx4 v[20:21], off
	s_nop 0
	s_waitcnt vmcnt(8)
	s_waitcnt lgkmcnt(0)
	s_barrier
	s_setprio 1
	s_waitcnt lgkmcnt(0)
	v_mfma_f32_16x16x32_bf16 v[20:23], v[12:15], v[32:35], v[144:147]
	v_mfma_f32_16x16x32_bf16 v[76:79], v[16:19], v[40:43], v[20:23]
	v_mfma_f32_16x16x32_bf16 v[20:23], v[172:175], v[32:35], v[148:151]
	v_mfma_f32_16x16x32_bf16 v[68:71], v[192:195], v[40:43], v[20:23]
	v_mfma_f32_16x16x32_bf16 v[20:23], v[12:15], v[176:179], v[152:155]
	v_mfma_f32_16x16x32_bf16 v[44:47], v[16:19], v[180:183], v[20:23]
	v_mfma_f32_16x16x32_bf16 v[20:23], v[172:175], v[176:179], v[156:159]
	v_mfma_f32_16x16x32_bf16 v[36:39], v[192:195], v[180:183], v[20:23]
	v_mfma_f32_16x16x32_bf16 v[20:23], v[12:15], v[210:213], v[160:163]
	v_mfma_f32_16x16x32_bf16 v[0:3], v[12:15], v[234:237], v[0:3]
	v_mfma_f32_16x16x32_bf16 v[28:31], v[16:19], v[214:217], v[20:23]
	v_mfma_f32_16x16x32_bf16 v[20:23], v[172:175], v[210:213], v[164:167]
	v_mfma_f32_16x16x32_bf16 v[12:15], v[16:19], v[238:241], v[0:3]
	v_mfma_f32_16x16x32_bf16 v[0:3], v[172:175], v[234:237], v[4:7]
	v_mfma_f32_16x16x32_bf16 v[20:23], v[192:195], v[214:217], v[20:23]
	v_mfma_f32_16x16x32_bf16 v[4:7], v[192:195], v[238:241], v[0:3]
	s_setprio 0
	s_setprio 1
	v_mfma_f32_16x16x32_bf16 v[0:3], v[198:201], v[32:35], v[8:11]
	v_mfma_f32_16x16x32_bf16 v[72:75], v[222:225], v[40:43], v[0:3]
	v_mfma_f32_16x16x32_bf16 v[0:3], v[226:229], v[32:35], v[202:205]
	v_mfma_f32_16x16x32_bf16 v[64:67], v[230:233], v[40:43], v[0:3]
	v_mfma_f32_16x16x32_bf16 v[0:3], v[198:201], v[176:179], v[24:27]
	v_mfma_f32_16x16x32_bf16 v[40:43], v[222:225], v[180:183], v[0:3]
	v_mfma_f32_16x16x32_bf16 v[0:3], v[226:229], v[176:179], v[206:209]
	v_mfma_f32_16x16x32_bf16 v[32:35], v[230:233], v[180:183], v[0:3]
	v_mfma_f32_16x16x32_bf16 v[0:3], v[198:201], v[210:213], v[218:221]
	v_mfma_f32_16x16x32_bf16 v[24:27], v[222:225], v[214:217], v[0:3]
	v_mfma_f32_16x16x32_bf16 v[0:3], v[226:229], v[210:213], v[184:187]
	v_mfma_f32_16x16x32_bf16 v[16:19], v[230:233], v[214:217], v[0:3]
	v_mfma_f32_16x16x32_bf16 v[0:3], v[198:201], v[234:237], v[188:191]
	v_mfma_f32_16x16x32_bf16 v[8:11], v[222:225], v[238:241], v[0:3]
	v_mfma_f32_16x16x32_bf16 v[0:3], v[226:229], v[234:237], v[168:171]
	v_mfma_f32_16x16x32_bf16 v[0:3], v[230:233], v[238:241], v[0:3]
	s_setprio 0
	s_barrier
	s_andn2_b64 vcc, exec, s[10:11]
	s_cbranch_vccnz .LBB0_1605
	s_barrier
